# GEMM main loops: LDS-DMA loads use SGPR base plus 32-bit VGPR offset directly (46 per-iteration 64-bit address builds removed)
# speedup vs baseline: 1.0462x; 1.0183x over previous
.LBB0_139:
	v_add_u32_e32 v253, 0x10000, v146
	ds_read_b128 v[140:143], v253
	ds_read_b128 v[150:153], v253 offset:1024
	ds_read_b128 v[154:157], v253 offset:2048
	ds_read_b128 v[158:161], v253 offset:3072
	s_add_u32 s10, s6, 0xfff80080
	s_addc_u32 s11, s7, -1
	s_cmp_eq_u32 s41, 28
	s_cselect_b32 s11, s63, s11
	s_cselect_b32 s10, s62, s10
	s_cselect_b32 s53, s61, s29
	s_cselect_b32 s52, s60, s28
	s_mov_b32 m0, s12
	ds_read_b128 v[162:165], v145
	ds_read_b128 v[166:169], v145 offset:1024
	ds_read_b128 v[170:173], v145 offset:2048
	ds_read_b128 v[174:177], v145 offset:3072
	ds_read_b128 v[178:181], v145 offset:4096
	ds_read_b128 v[182:185], v145 offset:5120
	ds_read_b128 v[186:189], v145 offset:6144
	ds_read_b128 v[190:193], v145 offset:7168
	global_load_lds_dwordx4 v136, s[6:7]
	s_mov_b32 m0, s78
	s_nop 0
	global_load_lds_dwordx4 v138, s[6:7]
	s_waitcnt lgkmcnt(8)
	s_setprio 1
	s_barrier
	s_waitcnt lgkmcnt(0)
	v_mfma_f32_16x16x32_bf16 v[126:129], v[140:143], v[162:165], v[126:129]
	v_mfma_f32_16x16x32_bf16 v[122:125], v[154:157], v[162:165], v[122:125]
	v_mfma_f32_16x16x32_bf16 v[118:121], v[140:143], v[170:173], v[118:121]
	v_mfma_f32_16x16x32_bf16 v[110:113], v[154:157], v[170:173], v[110:113]
	v_mfma_f32_16x16x32_bf16 v[102:105], v[140:143], v[178:181], v[102:105]
	v_mfma_f32_16x16x32_bf16 v[94:97], v[154:157], v[178:181], v[94:97]
	v_mfma_f32_16x16x32_bf16 v[86:89], v[140:143], v[186:189], v[86:89]
	v_mfma_f32_16x16x32_bf16 v[78:81], v[154:157], v[186:189], v[78:81]
	v_mfma_f32_16x16x32_bf16 v[126:129], v[150:153], v[166:169], v[126:129]
	v_mfma_f32_16x16x32_bf16 v[122:125], v[158:161], v[166:169], v[122:125]
	v_mfma_f32_16x16x32_bf16 v[118:121], v[150:153], v[174:177], v[118:121]
	v_mfma_f32_16x16x32_bf16 v[110:113], v[158:161], v[174:177], v[110:113]
	v_mfma_f32_16x16x32_bf16 v[102:105], v[150:153], v[182:185], v[102:105]
	v_mfma_f32_16x16x32_bf16 v[94:97], v[158:161], v[182:185], v[94:97]
	v_mfma_f32_16x16x32_bf16 v[86:89], v[150:153], v[190:193], v[86:89]
	v_mfma_f32_16x16x32_bf16 v[78:81], v[158:161], v[190:193], v[78:81]
	s_barrier
	s_setprio 0
	s_mov_b32 m0, s83
	ds_read_b128 v[206:209], v253 offset:16384
	ds_read_b128 v[210:213], v253 offset:17408
	v_lshl_add_u64 v[222:223], s[52:53], 0, v[194:195]
	ds_read_b128 v[214:217], v253 offset:18432
	ds_read_b128 v[218:221], v253 offset:19456
	global_load_lds_dwordx4 v[222:223], off
	v_lshl_add_u64 v[224:225], s[52:53], 0, v[134:135]
	s_mov_b32 m0, s54
	s_nop 0
	global_load_lds_dwordx4 v[224:225], off
	s_setprio 1
	s_barrier
	s_waitcnt lgkmcnt(0)
	v_mfma_f32_16x16x32_bf16 v[114:117], v[206:209], v[162:165], v[114:117]
	v_mfma_f32_16x16x32_bf16 v[106:109], v[214:217], v[162:165], v[106:109]
	v_mfma_f32_16x16x32_bf16 v[98:101], v[206:209], v[170:173], v[98:101]
	v_mfma_f32_16x16x32_bf16 v[90:93], v[214:217], v[170:173], v[90:93]
	v_mfma_f32_16x16x32_bf16 v[82:85], v[206:209], v[178:181], v[82:85]
	v_mfma_f32_16x16x32_bf16 v[74:77], v[214:217], v[178:181], v[74:77]
	v_mfma_f32_16x16x32_bf16 v[70:73], v[206:209], v[186:189], v[70:73]
	v_mfma_f32_16x16x32_bf16 v[66:69], v[214:217], v[186:189], v[66:69]
	v_mfma_f32_16x16x32_bf16 v[114:117], v[210:213], v[166:169], v[114:117]
	v_mfma_f32_16x16x32_bf16 v[106:109], v[218:221], v[166:169], v[106:109]
	v_mfma_f32_16x16x32_bf16 v[98:101], v[210:213], v[174:177], v[98:101]
	v_mfma_f32_16x16x32_bf16 v[90:93], v[218:221], v[174:177], v[90:93]
	v_mfma_f32_16x16x32_bf16 v[82:85], v[210:213], v[182:185], v[82:85]
	v_mfma_f32_16x16x32_bf16 v[74:77], v[218:221], v[182:185], v[74:77]
	s_mov_b32 m0, s55
	v_mfma_f32_16x16x32_bf16 v[70:73], v[210:213], v[190:193], v[70:73]
	v_lshl_add_u64 v[226:227], s[10:11], 0, v[130:131]
	v_mfma_f32_16x16x32_bf16 v[66:69], v[218:221], v[190:193], v[66:69]
	s_barrier
	s_setprio 0
	ds_read_b128 v[162:165], v145 offset:16384
	ds_read_b128 v[166:169], v145 offset:17408
	ds_read_b128 v[170:173], v145 offset:18432
	ds_read_b128 v[174:177], v145 offset:19456
	ds_read_b128 v[178:181], v145 offset:20480
	ds_read_b128 v[182:185], v145 offset:21504
	ds_read_b128 v[186:189], v145 offset:22528
	ds_read_b128 v[190:193], v145 offset:23552
	global_load_lds_dwordx4 v[226:227], off
	v_lshl_add_u64 v[228:229], s[10:11], 0, v[132:133]
	s_mov_b32 m0, s34
	s_nop 0
	global_load_lds_dwordx4 v[228:229], off
	s_setprio 1
	s_barrier
	s_waitcnt lgkmcnt(0)
	v_mfma_f32_16x16x32_bf16 v[62:65], v[140:143], v[162:165], v[62:65]
	v_mfma_f32_16x16x32_bf16 v[58:61], v[154:157], v[162:165], v[58:61]
	v_mfma_f32_16x16x32_bf16 v[54:57], v[140:143], v[170:173], v[54:57]
	v_mfma_f32_16x16x32_bf16 v[46:49], v[154:157], v[170:173], v[46:49]
	v_mfma_f32_16x16x32_bf16 v[38:41], v[140:143], v[178:181], v[38:41]
	v_mfma_f32_16x16x32_bf16 v[30:33], v[154:157], v[178:181], v[30:33]
	v_mfma_f32_16x16x32_bf16 v[22:25], v[140:143], v[186:189], v[22:25]
	v_mfma_f32_16x16x32_bf16 v[14:17], v[154:157], v[186:189], v[14:17]
	v_mfma_f32_16x16x32_bf16 v[62:65], v[150:153], v[166:169], v[62:65]
	v_mfma_f32_16x16x32_bf16 v[58:61], v[158:161], v[166:169], v[58:61]
	v_mfma_f32_16x16x32_bf16 v[54:57], v[150:153], v[174:177], v[54:57]
	v_mfma_f32_16x16x32_bf16 v[46:49], v[158:161], v[174:177], v[46:49]
	v_mfma_f32_16x16x32_bf16 v[38:41], v[150:153], v[182:185], v[38:41]
	v_mfma_f32_16x16x32_bf16 v[30:33], v[158:161], v[182:185], v[30:33]
	v_mfma_f32_16x16x32_bf16 v[22:25], v[150:153], v[190:193], v[22:25]
	v_mfma_f32_16x16x32_bf16 v[14:17], v[158:161], v[190:193], v[14:17]
	s_barrier
	s_setprio 0
	s_add_u32 s58, s52, 0x80000
	s_addc_u32 s59, s53, 0
	s_mov_b32 m0, s4
	global_load_lds_dwordx4 v194, s[58:59]
	s_mov_b32 m0, s5
	s_nop 0
	global_load_lds_dwordx4 v134, s[58:59]
	s_waitcnt vmcnt(6)
	s_setprio 1
	s_barrier
	v_mfma_f32_16x16x32_bf16 v[50:53], v[206:209], v[162:165], v[50:53]
	v_mfma_f32_16x16x32_bf16 v[42:45], v[214:217], v[162:165], v[42:45]
	v_mfma_f32_16x16x32_bf16 v[34:37], v[206:209], v[170:173], v[34:37]
	v_mfma_f32_16x16x32_bf16 v[26:29], v[214:217], v[170:173], v[26:29]
	v_mfma_f32_16x16x32_bf16 v[18:21], v[206:209], v[178:181], v[18:21]
	v_mfma_f32_16x16x32_bf16 v[10:13], v[214:217], v[178:181], v[10:13]
	v_mfma_f32_16x16x32_bf16 v[6:9], v[206:209], v[186:189], v[6:9]
	v_mfma_f32_16x16x32_bf16 v[2:5], v[214:217], v[186:189], v[2:5]
	v_mfma_f32_16x16x32_bf16 v[50:53], v[210:213], v[166:169], v[50:53]
	v_mfma_f32_16x16x32_bf16 v[42:45], v[218:221], v[166:169], v[42:45]
	v_mfma_f32_16x16x32_bf16 v[34:37], v[210:213], v[174:177], v[34:37]
	v_mfma_f32_16x16x32_bf16 v[26:29], v[218:221], v[174:177], v[26:29]
	v_mfma_f32_16x16x32_bf16 v[18:21], v[210:213], v[182:185], v[18:21]
	v_mfma_f32_16x16x32_bf16 v[10:13], v[218:221], v[182:185], v[10:13]
	v_mfma_f32_16x16x32_bf16 v[6:9], v[210:213], v[190:193], v[6:9]
	v_mfma_f32_16x16x32_bf16 v[2:5], v[218:221], v[190:193], v[2:5]
	s_barrier
	s_setprio 0
	ds_read_b128 v[140:143], v253 offset:32768
	ds_read_b128 v[150:153], v253 offset:33792
	ds_read_b128 v[154:157], v253 offset:34816
	ds_read_b128 v[158:161], v253 offset:35840
	s_add_u32 s10, s10, 0x80000
	s_addc_u32 s11, s11, 0
	s_mov_b32 m0, s56
	ds_read_b128 v[162:165], v145 offset:32768
	ds_read_b128 v[166:169], v145 offset:33792
	ds_read_b128 v[170:173], v145 offset:34816
	ds_read_b128 v[174:177], v145 offset:35840
	ds_read_b128 v[178:181], v145 offset:36864
	ds_read_b128 v[182:185], v145 offset:37888
	ds_read_b128 v[186:189], v145 offset:38912
	ds_read_b128 v[190:193], v145 offset:39936
	global_load_lds_dwordx4 v130, s[10:11]
	s_mov_b32 m0, s57
	s_nop 0
	global_load_lds_dwordx4 v132, s[10:11]
	s_waitcnt lgkmcnt(8)
	s_setprio 1
	s_barrier
	s_waitcnt lgkmcnt(0)
	v_mfma_f32_16x16x32_bf16 v[126:129], v[140:143], v[162:165], v[126:129]
	v_mfma_f32_16x16x32_bf16 v[122:125], v[154:157], v[162:165], v[122:125]
	v_mfma_f32_16x16x32_bf16 v[118:121], v[140:143], v[170:173], v[118:121]
	v_mfma_f32_16x16x32_bf16 v[110:113], v[154:157], v[170:173], v[110:113]
	v_mfma_f32_16x16x32_bf16 v[102:105], v[140:143], v[178:181], v[102:105]
	v_mfma_f32_16x16x32_bf16 v[94:97], v[154:157], v[178:181], v[94:97]
	v_mfma_f32_16x16x32_bf16 v[86:89], v[140:143], v[186:189], v[86:89]
	v_mfma_f32_16x16x32_bf16 v[78:81], v[154:157], v[186:189], v[78:81]
	v_mfma_f32_16x16x32_bf16 v[126:129], v[150:153], v[166:169], v[126:129]
	v_mfma_f32_16x16x32_bf16 v[122:125], v[158:161], v[166:169], v[122:125]
	v_mfma_f32_16x16x32_bf16 v[118:121], v[150:153], v[174:177], v[118:121]
	v_mfma_f32_16x16x32_bf16 v[110:113], v[158:161], v[174:177], v[110:113]
	v_mfma_f32_16x16x32_bf16 v[102:105], v[150:153], v[182:185], v[102:105]
	v_mfma_f32_16x16x32_bf16 v[94:97], v[158:161], v[182:185], v[94:97]
	v_mfma_f32_16x16x32_bf16 v[86:89], v[150:153], v[190:193], v[86:89]
	v_mfma_f32_16x16x32_bf16 v[78:81], v[158:161], v[190:193], v[78:81]
	s_barrier
	s_setprio 0
	s_mov_b32 m0, s70
	ds_read_b128 v[206:209], v253 offset:49152
	ds_read_b128 v[210:213], v253 offset:50176
	v_lshl_add_u64 v[222:223], v[222:223], 0, s[76:77]
	ds_read_b128 v[214:217], v253 offset:51200
	ds_read_b128 v[218:221], v253 offset:52224
	global_load_lds_dwordx4 v[222:223], off
	v_lshl_add_u64 v[222:223], v[224:225], 0, s[76:77]
	s_mov_b32 m0, s71
	s_nop 0
	global_load_lds_dwordx4 v[222:223], off
	s_setprio 1
	s_barrier
	s_waitcnt lgkmcnt(0)
	v_mfma_f32_16x16x32_bf16 v[114:117], v[206:209], v[162:165], v[114:117]
	v_mfma_f32_16x16x32_bf16 v[106:109], v[214:217], v[162:165], v[106:109]
	v_mfma_f32_16x16x32_bf16 v[98:101], v[206:209], v[170:173], v[98:101]
	v_mfma_f32_16x16x32_bf16 v[90:93], v[214:217], v[170:173], v[90:93]
	v_mfma_f32_16x16x32_bf16 v[82:85], v[206:209], v[178:181], v[82:85]
	v_mfma_f32_16x16x32_bf16 v[74:77], v[214:217], v[178:181], v[74:77]
	v_mfma_f32_16x16x32_bf16 v[70:73], v[206:209], v[186:189], v[70:73]
	v_mfma_f32_16x16x32_bf16 v[66:69], v[214:217], v[186:189], v[66:69]
	v_mfma_f32_16x16x32_bf16 v[114:117], v[210:213], v[166:169], v[114:117]
	v_mfma_f32_16x16x32_bf16 v[106:109], v[218:221], v[166:169], v[106:109]
	v_mfma_f32_16x16x32_bf16 v[98:101], v[210:213], v[174:177], v[98:101]
	v_mfma_f32_16x16x32_bf16 v[90:93], v[218:221], v[174:177], v[90:93]
	v_mfma_f32_16x16x32_bf16 v[82:85], v[210:213], v[182:185], v[82:85]
	v_mfma_f32_16x16x32_bf16 v[74:77], v[218:221], v[182:185], v[74:77]
	s_mov_b32 m0, s33
	v_mfma_f32_16x16x32_bf16 v[70:73], v[210:213], v[190:193], v[70:73]
	v_lshl_add_u64 v[222:223], v[226:227], 0, s[76:77]
	v_mfma_f32_16x16x32_bf16 v[66:69], v[218:221], v[190:193], v[66:69]
	s_barrier
	s_setprio 0
	ds_read_b128 v[162:165], v145 offset:49152
	ds_read_b128 v[166:169], v145 offset:50176
	ds_read_b128 v[170:173], v145 offset:51200
	ds_read_b128 v[174:177], v145 offset:52224
	ds_read_b128 v[178:181], v145 offset:53248
	ds_read_b128 v[182:185], v145 offset:54272
	ds_read_b128 v[186:189], v145 offset:55296
	ds_read_b128 v[190:193], v145 offset:56320
	global_load_lds_dwordx4 v[222:223], off
	v_lshl_add_u64 v[222:223], v[228:229], 0, s[76:77]
	s_mov_b32 m0, s35
	s_nop 0
	global_load_lds_dwordx4 v[222:223], off
	s_setprio 1
	s_barrier
	s_waitcnt lgkmcnt(0)
	v_mfma_f32_16x16x32_bf16 v[62:65], v[140:143], v[162:165], v[62:65]
	v_mfma_f32_16x16x32_bf16 v[58:61], v[154:157], v[162:165], v[58:61]
	v_mfma_f32_16x16x32_bf16 v[54:57], v[140:143], v[170:173], v[54:57]
	v_mfma_f32_16x16x32_bf16 v[46:49], v[154:157], v[170:173], v[46:49]
	v_mfma_f32_16x16x32_bf16 v[38:41], v[140:143], v[178:181], v[38:41]
	v_mfma_f32_16x16x32_bf16 v[30:33], v[154:157], v[178:181], v[30:33]
	v_mfma_f32_16x16x32_bf16 v[22:25], v[140:143], v[186:189], v[22:25]
	v_mfma_f32_16x16x32_bf16 v[14:17], v[154:157], v[186:189], v[14:17]
	v_mfma_f32_16x16x32_bf16 v[62:65], v[150:153], v[166:169], v[62:65]
	v_mfma_f32_16x16x32_bf16 v[58:61], v[158:161], v[166:169], v[58:61]
	v_mfma_f32_16x16x32_bf16 v[54:57], v[150:153], v[174:177], v[54:57]
	v_mfma_f32_16x16x32_bf16 v[46:49], v[158:161], v[174:177], v[46:49]
	v_mfma_f32_16x16x32_bf16 v[38:41], v[150:153], v[182:185], v[38:41]
	v_mfma_f32_16x16x32_bf16 v[30:33], v[158:161], v[182:185], v[30:33]
	v_mfma_f32_16x16x32_bf16 v[22:25], v[150:153], v[190:193], v[22:25]
	v_mfma_f32_16x16x32_bf16 v[14:17], v[158:161], v[190:193], v[14:17]
	s_barrier
	s_setprio 0
	s_add_u32 s10, s52, 0x80080
	s_addc_u32 s11, s53, 0
	s_mov_b32 m0, s67
	global_load_lds_dwordx4 v194, s[10:11]
	s_mov_b32 m0, s17
	s_nop 0
	global_load_lds_dwordx4 v134, s[10:11]
	s_waitcnt vmcnt(6)
	s_setprio 1
	s_barrier
	v_mfma_f32_16x16x32_bf16 v[50:53], v[206:209], v[162:165], v[50:53]
	v_mfma_f32_16x16x32_bf16 v[42:45], v[214:217], v[162:165], v[42:45]
	v_mfma_f32_16x16x32_bf16 v[34:37], v[206:209], v[170:173], v[34:37]
	v_mfma_f32_16x16x32_bf16 v[26:29], v[214:217], v[170:173], v[26:29]
	v_mfma_f32_16x16x32_bf16 v[18:21], v[206:209], v[178:181], v[18:21]
	v_mfma_f32_16x16x32_bf16 v[10:13], v[214:217], v[178:181], v[10:13]
	v_mfma_f32_16x16x32_bf16 v[6:9], v[206:209], v[186:189], v[6:9]
	v_mfma_f32_16x16x32_bf16 v[2:5], v[214:217], v[186:189], v[2:5]
	v_mfma_f32_16x16x32_bf16 v[50:53], v[210:213], v[166:169], v[50:53]
	v_mfma_f32_16x16x32_bf16 v[42:45], v[218:221], v[166:169], v[42:45]
	v_mfma_f32_16x16x32_bf16 v[34:37], v[210:213], v[174:177], v[34:37]
	v_mfma_f32_16x16x32_bf16 v[26:29], v[218:221], v[174:177], v[26:29]
	v_mfma_f32_16x16x32_bf16 v[18:21], v[210:213], v[182:185], v[18:21]
	v_mfma_f32_16x16x32_bf16 v[10:13], v[218:221], v[182:185], v[10:13]
	v_mfma_f32_16x16x32_bf16 v[6:9], v[210:213], v[190:193], v[6:9]
	v_mfma_f32_16x16x32_bf16 v[2:5], v[218:221], v[190:193], v[2:5]
	s_setprio 0
	s_add_i32 s41, s41, 2
	s_add_u32 s6, s6, 0x100
	s_addc_u32 s7, s7, 0
	s_add_u32 s28, s28, 0x100
	s_addc_u32 s29, s29, 0
	s_cmp_gt_u32 s41, 29
	s_barrier
	s_cbranch_scc0 .LBB0_139
	s_cmp_gt_i32 s79, 3
	s_mov_b64 s[6:7], -1
	s_cbranch_scc0 .LBB0_146
	s_lshl_b32 s10, s82, 8
	v_lshl_or_b32 v140, s80, 8, v149
	s_cmp_lg_u32 s79, 4
	v_ashrrev_i32_e32 v141, 31, v140
	s_cbranch_scc0 .LBB0_143
	v_readlane_b32 s6, v252, 55
	v_readlane_b32 s7, v252, 56
	v_add_u32_e32 v150, s10, v147
	s_nop 0
	v_mov_b64_e32 v[142:143], s[6:7]
	s_mov_b32 s6, 0x9000
	v_mad_i64_i32 v[142:143], s[6:7], v150, s6, v[142:143]
	v_lshl_add_u64 v[142:143], v[140:141], 1, v[142:143]
	v_cvt_pk_bf16_f32 v150, v126, v127
	v_cvt_pk_bf16_f32 v151, v128, v129
	v_cvt_pk_bf16_f32 v152, v122, v123
	v_cvt_pk_bf16_f32 v153, v124, v125
	global_store_dwordx4 v[142:143], v[150:153], off
	v_add_co_u32_e32 v154, vcc, s44, v142
	s_nop 0
	v_cvt_pk_bf16_f32 v150, v114, v115
	v_cvt_pk_bf16_f32 v151, v116, v117
	v_cvt_pk_bf16_f32 v152, v106, v107
	v_cvt_pk_bf16_f32 v153, v108, v109
	global_store_dwordx4 v[142:143], v[150:153], off offset:256
	v_addc_co_u32_e32 v155, vcc, 0, v143, vcc
	s_nop 0
	v_cvt_pk_bf16_f32 v150, v118, v119
	v_cvt_pk_bf16_f32 v151, v120, v121
	v_cvt_pk_bf16_f32 v152, v110, v111
	v_cvt_pk_bf16_f32 v153, v112, v113
	global_store_dwordx4 v[154:155], v[150:153], off
	s_mov_b64 s[6:7], 0
	s_nop 0
	v_cvt_pk_bf16_f32 v150, v98, v99
	v_cvt_pk_bf16_f32 v151, v100, v101
	v_cvt_pk_bf16_f32 v152, v90, v91
	v_cvt_pk_bf16_f32 v153, v92, v93
	global_store_dwordx4 v[154:155], v[150:153], off offset:256
	v_add_co_u32_e32 v154, vcc, s45, v142
	s_nop 0
	v_cvt_pk_bf16_f32 v150, v102, v103
	v_cvt_pk_bf16_f32 v151, v104, v105
	v_cvt_pk_bf16_f32 v152, v94, v95
	v_cvt_pk_bf16_f32 v153, v96, v97
	s_nop 0
	v_addc_co_u32_e32 v155, vcc, 0, v143, vcc
	global_store_dwordx4 v[154:155], v[150:153], off
	s_nop 1
	v_cvt_pk_bf16_f32 v150, v82, v83
	v_cvt_pk_bf16_f32 v151, v84, v85
	v_cvt_pk_bf16_f32 v152, v74, v75
	v_cvt_pk_bf16_f32 v153, v76, v77
	global_store_dwordx4 v[154:155], v[150:153], off offset:256
	v_add_co_u32_e32 v154, vcc, s90, v142
	s_nop 0
	v_cvt_pk_bf16_f32 v150, v86, v87
	v_cvt_pk_bf16_f32 v151, v88, v89
	v_cvt_pk_bf16_f32 v152, v78, v79
	v_cvt_pk_bf16_f32 v153, v80, v81
	s_nop 0
	v_addc_co_u32_e32 v155, vcc, 0, v143, vcc
	global_store_dwordx4 v[154:155], v[150:153], off
	s_nop 1
	v_cvt_pk_bf16_f32 v150, v70, v71
	v_cvt_pk_bf16_f32 v151, v72, v73
	v_cvt_pk_bf16_f32 v152, v66, v67
	v_cvt_pk_bf16_f32 v153, v68, v69
	global_store_dwordx4 v[154:155], v[150:153], off offset:256
	v_add_co_u32_e32 v154, vcc, s20, v142
	s_nop 0
	v_cvt_pk_bf16_f32 v150, v62, v63
	v_cvt_pk_bf16_f32 v151, v64, v65
	v_cvt_pk_bf16_f32 v152, v58, v59
	v_cvt_pk_bf16_f32 v153, v60, v61
	s_nop 0
	v_addc_co_u32_e32 v155, vcc, 0, v143, vcc
	global_store_dwordx4 v[154:155], v[150:153], off
	s_nop 1
	v_cvt_pk_bf16_f32 v150, v50, v51
	v_cvt_pk_bf16_f32 v151, v52, v53
	v_cvt_pk_bf16_f32 v152, v42, v43
	v_cvt_pk_bf16_f32 v153, v44, v45
	global_store_dwordx4 v[154:155], v[150:153], off offset:256
	v_add_co_u32_e32 v154, vcc, s21, v142
	s_nop 0
	v_cvt_pk_bf16_f32 v150, v54, v55
	v_cvt_pk_bf16_f32 v151, v56, v57
	v_cvt_pk_bf16_f32 v152, v46, v47
	v_cvt_pk_bf16_f32 v153, v48, v49
	s_nop 0
	v_addc_co_u32_e32 v155, vcc, 0, v143, vcc
	global_store_dwordx4 v[154:155], v[150:153], off
	s_nop 1
	v_cvt_pk_bf16_f32 v150, v34, v35
	v_cvt_pk_bf16_f32 v151, v36, v37
	v_cvt_pk_bf16_f32 v152, v26, v27
	v_cvt_pk_bf16_f32 v153, v28, v29
	global_store_dwordx4 v[154:155], v[150:153], off offset:256
	v_add_co_u32_e32 v154, vcc, s22, v142
	s_nop 0
	v_cvt_pk_bf16_f32 v150, v38, v39
	v_cvt_pk_bf16_f32 v151, v40, v41
	v_cvt_pk_bf16_f32 v152, v30, v31
	v_cvt_pk_bf16_f32 v153, v32, v33
	s_nop 0
	v_addc_co_u32_e32 v155, vcc, 0, v143, vcc
	global_store_dwordx4 v[154:155], v[150:153], off
	v_add_co_u32_e32 v142, vcc, s23, v142
	s_nop 0
	v_cvt_pk_bf16_f32 v150, v18, v19
	v_cvt_pk_bf16_f32 v151, v20, v21
	v_cvt_pk_bf16_f32 v152, v10, v11
	v_cvt_pk_bf16_f32 v153, v12, v13
	global_store_dwordx4 v[154:155], v[150:153], off offset:256
	v_addc_co_u32_e32 v143, vcc, 0, v143, vcc
	s_nop 0
	v_cvt_pk_bf16_f32 v150, v22, v23
	v_cvt_pk_bf16_f32 v151, v24, v25
	v_cvt_pk_bf16_f32 v152, v14, v15
	v_cvt_pk_bf16_f32 v153, v16, v17
	global_store_dwordx4 v[142:143], v[150:153], off
	s_nop 1
	v_cvt_pk_bf16_f32 v150, v6, v7
	v_cvt_pk_bf16_f32 v151, v8, v9
	v_cvt_pk_bf16_f32 v152, v2, v3
	v_cvt_pk_bf16_f32 v153, v4, v5
	global_store_dwordx4 v[142:143], v[150:153], off offset:256

.LBB0_204:
	s_add_u32 s80, s54, s62
	s_addc_u32 s81, s55, s63
	s_add_u32 s82, s80, 0x100
	s_addc_u32 s83, s81, 0
	s_and_b64 s[10:11], s[8:9], exec
	s_cselect_b32 s83, s1, s83
	s_cselect_b32 s82, s0, s82
	s_add_u32 s10, s52, s62
	s_addc_u32 s11, s53, s63
	s_add_u32 s10, s10, 0x100
	s_addc_u32 s11, s11, 0
	s_and_b64 s[8:9], s[8:9], exec
	s_cselect_b32 vcc_hi, s7, s11
	s_cselect_b32 vcc_lo, s6, s10
	s_add_u32 s10, s80, 0x10080
	v_add_u32_e32 v253, 0x10000, v142
	s_addc_u32 s11, s81, 0
	s_add_i32 m0, s5, 0xc000
	s_add_i32 s87, s5, 0xe000
	ds_read_b128 v[144:147], v253
	s_add_u32 s80, vcc_lo, 0x340000
	ds_read_b128 v[148:151], v253 offset:1024
	s_addc_u32 s81, vcc_hi, 0
	ds_read_b128 v[152:155], v253 offset:2048
	s_add_u32 s62, s82, 0x10000
	ds_read_b128 v[156:159], v253 offset:3072
	s_addc_u32 s63, s83, 0
	s_add_u32 s8, vcc_lo, 0x340080
	s_addc_u32 s9, vcc_hi, 0
	ds_read_b128 v[160:163], v141
	ds_read_b128 v[164:167], v141 offset:1024
	ds_read_b128 v[168:171], v141 offset:2048
	ds_read_b128 v[172:175], v141 offset:3072
	ds_read_b128 v[176:179], v141 offset:4096
	ds_read_b128 v[180:183], v141 offset:5120
	ds_read_b128 v[184:187], v141 offset:6144
	ds_read_b128 v[188:191], v141 offset:7168
	global_load_lds_dwordx4 v136, s[10:11]
	s_mov_b32 m0, s87
	s_nop 0
	global_load_lds_dwordx4 v132, s[10:11]
	s_waitcnt lgkmcnt(8)
	s_setprio 1
	s_barrier
	s_waitcnt lgkmcnt(0)
	v_mfma_f32_16x16x32_bf16 v[126:129], v[144:147], v[160:163], v[126:129]
	v_mfma_f32_16x16x32_bf16 v[122:125], v[152:155], v[160:163], v[122:125]
	v_mfma_f32_16x16x32_bf16 v[118:121], v[144:147], v[168:171], v[118:121]
	v_mfma_f32_16x16x32_bf16 v[110:113], v[152:155], v[168:171], v[110:113]
	v_mfma_f32_16x16x32_bf16 v[102:105], v[144:147], v[176:179], v[102:105]
	v_mfma_f32_16x16x32_bf16 v[94:97], v[152:155], v[176:179], v[94:97]
	v_mfma_f32_16x16x32_bf16 v[86:89], v[144:147], v[184:187], v[86:89]
	v_mfma_f32_16x16x32_bf16 v[78:81], v[152:155], v[184:187], v[78:81]
	v_mfma_f32_16x16x32_bf16 v[126:129], v[148:151], v[164:167], v[126:129]
	v_mfma_f32_16x16x32_bf16 v[122:125], v[156:159], v[164:167], v[122:125]
	v_mfma_f32_16x16x32_bf16 v[118:121], v[148:151], v[172:175], v[118:121]
	v_mfma_f32_16x16x32_bf16 v[110:113], v[156:159], v[172:175], v[110:113]
	v_mfma_f32_16x16x32_bf16 v[102:105], v[148:151], v[180:183], v[102:105]
	v_mfma_f32_16x16x32_bf16 v[94:97], v[156:159], v[180:183], v[94:97]
	v_mfma_f32_16x16x32_bf16 v[86:89], v[148:151], v[188:191], v[86:89]
	v_mfma_f32_16x16x32_bf16 v[78:81], v[156:159], v[188:191], v[78:81]
	s_barrier
	s_setprio 0
	ds_read_b128 v[206:209], v253 offset:16384
	ds_read_b128 v[210:213], v253 offset:17408
	s_mov_b32 m0, s12
	ds_read_b128 v[214:217], v253 offset:18432
	ds_read_b128 v[218:221], v253 offset:19456
	v_lshl_add_u64 v[138:139], vcc, 0, v[134:135]
	global_load_lds_dwordx4 v[138:139], off
	v_lshl_add_u64 v[192:193], vcc, 0, v[130:131]
	s_mov_b32 m0, s17
	s_nop 0
	global_load_lds_dwordx4 v[192:193], off
	s_setprio 1
	s_barrier
	s_waitcnt lgkmcnt(0)
	v_mfma_f32_16x16x32_bf16 v[114:117], v[206:209], v[160:163], v[114:117]
	v_mfma_f32_16x16x32_bf16 v[106:109], v[214:217], v[160:163], v[106:109]
	v_mfma_f32_16x16x32_bf16 v[98:101], v[206:209], v[168:171], v[98:101]
	v_mfma_f32_16x16x32_bf16 v[90:93], v[214:217], v[168:171], v[90:93]
	v_mfma_f32_16x16x32_bf16 v[82:85], v[206:209], v[176:179], v[82:85]
	v_mfma_f32_16x16x32_bf16 v[74:77], v[214:217], v[176:179], v[74:77]
	v_mfma_f32_16x16x32_bf16 v[70:73], v[206:209], v[184:187], v[70:73]
	v_mfma_f32_16x16x32_bf16 v[66:69], v[214:217], v[184:187], v[66:69]
	v_mfma_f32_16x16x32_bf16 v[114:117], v[210:213], v[164:167], v[114:117]
	v_mfma_f32_16x16x32_bf16 v[106:109], v[218:221], v[164:167], v[106:109]
	v_mfma_f32_16x16x32_bf16 v[98:101], v[210:213], v[172:175], v[98:101]
	v_mfma_f32_16x16x32_bf16 v[90:93], v[218:221], v[172:175], v[90:93]
	v_mfma_f32_16x16x32_bf16 v[82:85], v[210:213], v[180:183], v[82:85]
	v_mfma_f32_16x16x32_bf16 v[74:77], v[218:221], v[180:183], v[74:77]
	s_mov_b32 m0, s5
	v_mfma_f32_16x16x32_bf16 v[70:73], v[210:213], v[188:191], v[70:73]
	v_lshl_add_u64 v[222:223], s[82:83], 0, v[136:137]
	v_mfma_f32_16x16x32_bf16 v[66:69], v[218:221], v[188:191], v[66:69]
	s_barrier
	s_setprio 0
	ds_read_b128 v[160:163], v141 offset:16384
	ds_read_b128 v[164:167], v141 offset:17408
	ds_read_b128 v[168:171], v141 offset:18432
	ds_read_b128 v[172:175], v141 offset:19456
	ds_read_b128 v[176:179], v141 offset:20480
	ds_read_b128 v[180:183], v141 offset:21504
	ds_read_b128 v[184:187], v141 offset:22528
	ds_read_b128 v[188:191], v141 offset:23552
	global_load_lds_dwordx4 v[222:223], off
	v_lshl_add_u64 v[224:225], s[82:83], 0, v[132:133]
	s_mov_b32 m0, s26
	s_nop 0
	global_load_lds_dwordx4 v[224:225], off
	s_setprio 1
	s_barrier
	s_waitcnt lgkmcnt(0)
	v_mfma_f32_16x16x32_bf16 v[62:65], v[144:147], v[160:163], v[62:65]
	v_mfma_f32_16x16x32_bf16 v[58:61], v[152:155], v[160:163], v[58:61]
	v_mfma_f32_16x16x32_bf16 v[54:57], v[144:147], v[168:171], v[54:57]
	v_mfma_f32_16x16x32_bf16 v[46:49], v[152:155], v[168:171], v[46:49]
	v_mfma_f32_16x16x32_bf16 v[38:41], v[144:147], v[176:179], v[38:41]
	v_mfma_f32_16x16x32_bf16 v[30:33], v[152:155], v[176:179], v[30:33]
	v_mfma_f32_16x16x32_bf16 v[22:25], v[144:147], v[184:187], v[22:25]
	v_mfma_f32_16x16x32_bf16 v[14:17], v[152:155], v[184:187], v[14:17]
	v_mfma_f32_16x16x32_bf16 v[62:65], v[148:151], v[164:167], v[62:65]
	v_mfma_f32_16x16x32_bf16 v[58:61], v[156:159], v[164:167], v[58:61]
	v_mfma_f32_16x16x32_bf16 v[54:57], v[148:151], v[172:175], v[54:57]
	v_mfma_f32_16x16x32_bf16 v[46:49], v[156:159], v[172:175], v[46:49]
	v_mfma_f32_16x16x32_bf16 v[38:41], v[148:151], v[180:183], v[38:41]
	v_mfma_f32_16x16x32_bf16 v[30:33], v[156:159], v[180:183], v[30:33]
	v_mfma_f32_16x16x32_bf16 v[22:25], v[148:151], v[188:191], v[22:25]
	v_mfma_f32_16x16x32_bf16 v[14:17], v[156:159], v[188:191], v[14:17]
	s_barrier
	s_setprio 0
	s_mov_b32 m0, s34
	global_load_lds_dwordx4 v134, s[80:81]
	s_mov_b32 m0, s35
	s_nop 0
	global_load_lds_dwordx4 v130, s[80:81]
	s_waitcnt vmcnt(6)
	s_setprio 1
	s_barrier
	v_mfma_f32_16x16x32_bf16 v[50:53], v[206:209], v[160:163], v[50:53]
	v_mfma_f32_16x16x32_bf16 v[42:45], v[214:217], v[160:163], v[42:45]
	v_mfma_f32_16x16x32_bf16 v[34:37], v[206:209], v[168:171], v[34:37]
	v_mfma_f32_16x16x32_bf16 v[26:29], v[214:217], v[168:171], v[26:29]
	v_mfma_f32_16x16x32_bf16 v[18:21], v[206:209], v[176:179], v[18:21]
	v_mfma_f32_16x16x32_bf16 v[10:13], v[214:217], v[176:179], v[10:13]
	v_mfma_f32_16x16x32_bf16 v[6:9], v[206:209], v[184:187], v[6:9]
	v_mfma_f32_16x16x32_bf16 v[2:5], v[214:217], v[184:187], v[2:5]
	v_mfma_f32_16x16x32_bf16 v[50:53], v[210:213], v[164:167], v[50:53]
	v_mfma_f32_16x16x32_bf16 v[42:45], v[218:221], v[164:167], v[42:45]
	v_mfma_f32_16x16x32_bf16 v[34:37], v[210:213], v[172:175], v[34:37]
	v_mfma_f32_16x16x32_bf16 v[26:29], v[218:221], v[172:175], v[26:29]
	v_mfma_f32_16x16x32_bf16 v[18:21], v[210:213], v[180:183], v[18:21]
	v_mfma_f32_16x16x32_bf16 v[10:13], v[218:221], v[180:183], v[10:13]
	v_mfma_f32_16x16x32_bf16 v[6:9], v[210:213], v[188:191], v[6:9]
	v_mfma_f32_16x16x32_bf16 v[2:5], v[218:221], v[188:191], v[2:5]
	s_barrier
	s_setprio 0
	ds_read_b128 v[144:147], v253 offset:32768
	ds_read_b128 v[148:151], v253 offset:33792
	ds_read_b128 v[152:155], v253 offset:34816
	ds_read_b128 v[156:159], v253 offset:35840
	s_mov_b32 m0, s56
	ds_read_b128 v[160:163], v141 offset:32768
	ds_read_b128 v[164:167], v141 offset:33792
	ds_read_b128 v[168:171], v141 offset:34816
	ds_read_b128 v[172:175], v141 offset:35840
	ds_read_b128 v[176:179], v141 offset:36864
	ds_read_b128 v[180:183], v141 offset:37888
	ds_read_b128 v[184:187], v141 offset:38912
	ds_read_b128 v[188:191], v141 offset:39936
	global_load_lds_dwordx4 v136, s[62:63]
	s_mov_b32 m0, s57
	s_nop 0
	global_load_lds_dwordx4 v132, s[62:63]
	s_waitcnt lgkmcnt(8)
	s_setprio 1
	s_barrier
	s_waitcnt lgkmcnt(0)
	v_mfma_f32_16x16x32_bf16 v[126:129], v[144:147], v[160:163], v[126:129]
	v_mfma_f32_16x16x32_bf16 v[122:125], v[152:155], v[160:163], v[122:125]
	v_mfma_f32_16x16x32_bf16 v[118:121], v[144:147], v[168:171], v[118:121]
	v_mfma_f32_16x16x32_bf16 v[110:113], v[152:155], v[168:171], v[110:113]
	v_mfma_f32_16x16x32_bf16 v[102:105], v[144:147], v[176:179], v[102:105]
	v_mfma_f32_16x16x32_bf16 v[94:97], v[152:155], v[176:179], v[94:97]
	v_mfma_f32_16x16x32_bf16 v[86:89], v[144:147], v[184:187], v[86:89]
	v_mfma_f32_16x16x32_bf16 v[78:81], v[152:155], v[184:187], v[78:81]
	v_mfma_f32_16x16x32_bf16 v[126:129], v[148:151], v[164:167], v[126:129]
	v_mfma_f32_16x16x32_bf16 v[122:125], v[156:159], v[164:167], v[122:125]
	v_mfma_f32_16x16x32_bf16 v[118:121], v[148:151], v[172:175], v[118:121]
	v_mfma_f32_16x16x32_bf16 v[110:113], v[156:159], v[172:175], v[110:113]
	v_mfma_f32_16x16x32_bf16 v[102:105], v[148:151], v[180:183], v[102:105]
	v_mfma_f32_16x16x32_bf16 v[94:97], v[156:159], v[180:183], v[94:97]
	v_mfma_f32_16x16x32_bf16 v[86:89], v[148:151], v[188:191], v[86:89]
	v_mfma_f32_16x16x32_bf16 v[78:81], v[156:159], v[188:191], v[78:81]
	s_barrier
	s_setprio 0
	s_mov_b32 m0, s58
	ds_read_b128 v[206:209], v253 offset:49152
	ds_read_b128 v[210:213], v253 offset:50176
	v_lshl_add_u64 v[138:139], v[138:139], 0, s[76:77]
	ds_read_b128 v[214:217], v253 offset:51200
	ds_read_b128 v[218:221], v253 offset:52224
	global_load_lds_dwordx4 v[138:139], off
	v_lshl_add_u64 v[138:139], v[192:193], 0, s[76:77]
	s_mov_b32 m0, s59
	s_nop 0
	global_load_lds_dwordx4 v[138:139], off
	s_setprio 1
	s_barrier
	s_waitcnt lgkmcnt(0)
	v_mfma_f32_16x16x32_bf16 v[114:117], v[206:209], v[160:163], v[114:117]
	v_mfma_f32_16x16x32_bf16 v[106:109], v[214:217], v[160:163], v[106:109]
	v_mfma_f32_16x16x32_bf16 v[98:101], v[206:209], v[168:171], v[98:101]
	v_mfma_f32_16x16x32_bf16 v[90:93], v[214:217], v[168:171], v[90:93]
	v_mfma_f32_16x16x32_bf16 v[82:85], v[206:209], v[176:179], v[82:85]
	v_mfma_f32_16x16x32_bf16 v[74:77], v[214:217], v[176:179], v[74:77]
	v_mfma_f32_16x16x32_bf16 v[70:73], v[206:209], v[184:187], v[70:73]
	v_mfma_f32_16x16x32_bf16 v[66:69], v[214:217], v[184:187], v[66:69]
	v_mfma_f32_16x16x32_bf16 v[114:117], v[210:213], v[164:167], v[114:117]
	v_mfma_f32_16x16x32_bf16 v[106:109], v[218:221], v[164:167], v[106:109]
	v_mfma_f32_16x16x32_bf16 v[98:101], v[210:213], v[172:175], v[98:101]
	v_mfma_f32_16x16x32_bf16 v[90:93], v[218:221], v[172:175], v[90:93]
	v_mfma_f32_16x16x32_bf16 v[82:85], v[210:213], v[180:183], v[82:85]
	v_mfma_f32_16x16x32_bf16 v[74:77], v[218:221], v[180:183], v[74:77]
	s_mov_b32 m0, s67
	v_mfma_f32_16x16x32_bf16 v[70:73], v[210:213], v[188:191], v[70:73]
	v_lshl_add_u64 v[138:139], v[222:223], 0, s[76:77]
	v_mfma_f32_16x16x32_bf16 v[66:69], v[218:221], v[188:191], v[66:69]
	s_barrier
	s_setprio 0
	ds_read_b128 v[160:163], v141 offset:49152
	ds_read_b128 v[164:167], v141 offset:50176
	ds_read_b128 v[168:171], v141 offset:51200
	ds_read_b128 v[172:175], v141 offset:52224
	ds_read_b128 v[176:179], v141 offset:53248
	ds_read_b128 v[180:183], v141 offset:54272
	ds_read_b128 v[184:187], v141 offset:55296
	ds_read_b128 v[188:191], v141 offset:56320
	global_load_lds_dwordx4 v[138:139], off
	v_lshl_add_u64 v[138:139], v[224:225], 0, s[76:77]
	s_mov_b32 m0, s70
	s_nop 0
	global_load_lds_dwordx4 v[138:139], off
	s_setprio 1
	s_barrier
	s_waitcnt lgkmcnt(0)
	v_mfma_f32_16x16x32_bf16 v[62:65], v[144:147], v[160:163], v[62:65]
	v_mfma_f32_16x16x32_bf16 v[58:61], v[152:155], v[160:163], v[58:61]
	v_mfma_f32_16x16x32_bf16 v[54:57], v[144:147], v[168:171], v[54:57]
	v_mfma_f32_16x16x32_bf16 v[46:49], v[152:155], v[168:171], v[46:49]
	v_mfma_f32_16x16x32_bf16 v[38:41], v[144:147], v[176:179], v[38:41]
	v_mfma_f32_16x16x32_bf16 v[30:33], v[152:155], v[176:179], v[30:33]
	v_mfma_f32_16x16x32_bf16 v[22:25], v[144:147], v[184:187], v[22:25]
	v_mfma_f32_16x16x32_bf16 v[14:17], v[152:155], v[184:187], v[14:17]
	v_mfma_f32_16x16x32_bf16 v[62:65], v[148:151], v[164:167], v[62:65]
	v_mfma_f32_16x16x32_bf16 v[58:61], v[156:159], v[164:167], v[58:61]
	v_mfma_f32_16x16x32_bf16 v[54:57], v[148:151], v[172:175], v[54:57]
	v_mfma_f32_16x16x32_bf16 v[46:49], v[156:159], v[172:175], v[46:49]
	v_mfma_f32_16x16x32_bf16 v[38:41], v[148:151], v[180:183], v[38:41]
	v_mfma_f32_16x16x32_bf16 v[30:33], v[156:159], v[180:183], v[30:33]
	v_mfma_f32_16x16x32_bf16 v[22:25], v[148:151], v[188:191], v[22:25]
	v_mfma_f32_16x16x32_bf16 v[14:17], v[156:159], v[188:191], v[14:17]
	s_barrier
	s_setprio 0
	s_mov_b32 m0, s71
	global_load_lds_dwordx4 v134, s[8:9]
	s_mov_b32 m0, s78
	s_nop 0
	global_load_lds_dwordx4 v130, s[8:9]
	s_waitcnt vmcnt(6)
	s_setprio 1
	s_barrier
	v_mfma_f32_16x16x32_bf16 v[50:53], v[206:209], v[160:163], v[50:53]
	v_mfma_f32_16x16x32_bf16 v[42:45], v[214:217], v[160:163], v[42:45]
	v_mfma_f32_16x16x32_bf16 v[34:37], v[206:209], v[168:171], v[34:37]
	v_mfma_f32_16x16x32_bf16 v[26:29], v[214:217], v[168:171], v[26:29]
	v_mfma_f32_16x16x32_bf16 v[18:21], v[206:209], v[176:179], v[18:21]
	v_mfma_f32_16x16x32_bf16 v[10:13], v[214:217], v[176:179], v[10:13]
	v_mfma_f32_16x16x32_bf16 v[6:9], v[206:209], v[184:187], v[6:9]
	v_mfma_f32_16x16x32_bf16 v[2:5], v[214:217], v[184:187], v[2:5]
	v_mfma_f32_16x16x32_bf16 v[50:53], v[210:213], v[164:167], v[50:53]
	v_mfma_f32_16x16x32_bf16 v[42:45], v[218:221], v[164:167], v[42:45]
	v_mfma_f32_16x16x32_bf16 v[34:37], v[210:213], v[172:175], v[34:37]
	v_mfma_f32_16x16x32_bf16 v[26:29], v[218:221], v[172:175], v[26:29]
	v_mfma_f32_16x16x32_bf16 v[18:21], v[210:213], v[180:183], v[18:21]
	v_mfma_f32_16x16x32_bf16 v[10:13], v[218:221], v[180:183], v[10:13]
	v_mfma_f32_16x16x32_bf16 v[6:9], v[210:213], v[188:191], v[6:9]
	v_mfma_f32_16x16x32_bf16 v[2:5], v[218:221], v[188:191], v[2:5]
	s_setprio 0
	s_andn2_b64 vcc, exec, s[60:61]
	s_mov_b64 s[8:9], -1
	s_mov_b64 s[60:61], 0
	s_mov_b64 s[62:63], 0x100
	s_barrier
	s_cbranch_vccz .LBB0_204
	s_cmp_gt_i32 s29, 63
	s_cbranch_scc0 .LBB0_207
	s_lshl_b32 s8, s29, 10
	s_lshl_b32 s9, s94, 8
	s_add_i32 s9, s9, s8
	v_add_u32_e32 v138, s9, v143
	v_ashrrev_i32_e32 v139, 31, v138
	v_lshlrev_b64 v[138:139], 10, v[138:139]
	s_lshl_b32 s8, s42, 8
	v_lshl_add_u64 v[138:139], s[64:65], 0, v[138:139]
	s_ashr_i32 s9, s8, 31
	v_lshl_add_u64 v[138:139], s[8:9], 1, v[138:139]
	s_mov_b64 s[8:9], 0

.LBB0_255:
	v_add_u32_e32 v253, 0x10000, v182
	ds_read_b128 v[130:133], v253
	ds_read_b128 v[134:137], v253 offset:1024
	ds_read_b128 v[138:141], v253 offset:2048
	ds_read_b128 v[142:145], v253 offset:3072
	s_add_u32 s8, s6, 0xfff00080
	s_addc_u32 s9, s7, -1
	s_cmp_eq_u32 s79, 60
	s_cselect_b32 s11, s53, s9
	s_cselect_b32 s10, s52, s8
	s_cselect_b32 s9, s61, s78
	s_cselect_b32 s8, s60, s1
	s_add_i32 m0, s5, 0xc000
	ds_read_b128 v[146:149], v181
	ds_read_b128 v[150:153], v181 offset:1024
	ds_read_b128 v[154:157], v181 offset:2048
	ds_read_b128 v[170:173], v181 offset:3072
	ds_read_b128 v[174:177], v181 offset:4096
	ds_read_b128 v[184:187], v181 offset:5120
	ds_read_b128 v[188:191], v181 offset:6144
	ds_read_b128 v[206:209], v181 offset:7168
	global_load_lds_dwordx4 v166, s[6:7]
	s_add_i32 m0, s5, 0xe000
	s_nop 0
	global_load_lds_dwordx4 v168, s[6:7]
	s_waitcnt lgkmcnt(8)
	s_setprio 1
	s_barrier
	s_waitcnt lgkmcnt(0)
	v_mfma_f32_16x16x32_bf16 v[126:129], v[130:133], v[146:149], v[126:129]
	v_mfma_f32_16x16x32_bf16 v[122:125], v[138:141], v[146:149], v[122:125]
	v_mfma_f32_16x16x32_bf16 v[110:113], v[130:133], v[154:157], v[110:113]
	v_mfma_f32_16x16x32_bf16 v[106:109], v[138:141], v[154:157], v[106:109]
	v_mfma_f32_16x16x32_bf16 v[94:97], v[130:133], v[174:177], v[94:97]
	v_mfma_f32_16x16x32_bf16 v[90:93], v[138:141], v[174:177], v[90:93]
	v_mfma_f32_16x16x32_bf16 v[78:81], v[130:133], v[188:191], v[78:81]
	v_mfma_f32_16x16x32_bf16 v[74:77], v[138:141], v[188:191], v[74:77]
	v_mfma_f32_16x16x32_bf16 v[126:129], v[134:137], v[150:153], v[126:129]
	v_mfma_f32_16x16x32_bf16 v[122:125], v[142:145], v[150:153], v[122:125]
	v_mfma_f32_16x16x32_bf16 v[110:113], v[134:137], v[170:173], v[110:113]
	v_mfma_f32_16x16x32_bf16 v[106:109], v[142:145], v[170:173], v[106:109]
	v_mfma_f32_16x16x32_bf16 v[94:97], v[134:137], v[184:187], v[94:97]
	v_mfma_f32_16x16x32_bf16 v[90:93], v[142:145], v[184:187], v[90:93]
	v_mfma_f32_16x16x32_bf16 v[78:81], v[134:137], v[206:209], v[78:81]
	v_mfma_f32_16x16x32_bf16 v[74:77], v[142:145], v[206:209], v[74:77]
	s_barrier
	s_setprio 0
	ds_read_b128 v[210:213], v253 offset:16384
	ds_read_b128 v[214:217], v253 offset:17408
	s_mov_b32 m0, s12
	ds_read_b128 v[218:221], v253 offset:18432
	ds_read_b128 v[222:225], v253 offset:19456
	v_lshl_add_u64 v[178:179], s[8:9], 0, v[162:163]
	global_load_lds_dwordx4 v[178:179], off
	v_lshl_add_u64 v[192:193], s[8:9], 0, v[158:159]
	s_mov_b32 m0, s17
	s_nop 0
	global_load_lds_dwordx4 v[192:193], off
	s_setprio 1
	s_barrier
	s_waitcnt lgkmcnt(0)
	v_mfma_f32_16x16x32_bf16 v[118:121], v[210:213], v[146:149], v[118:121]
	v_mfma_f32_16x16x32_bf16 v[114:117], v[218:221], v[146:149], v[114:117]
	v_mfma_f32_16x16x32_bf16 v[102:105], v[210:213], v[154:157], v[102:105]
	v_mfma_f32_16x16x32_bf16 v[98:101], v[218:221], v[154:157], v[98:101]
	v_mfma_f32_16x16x32_bf16 v[86:89], v[210:213], v[174:177], v[86:89]
	v_mfma_f32_16x16x32_bf16 v[82:85], v[218:221], v[174:177], v[82:85]
	v_mfma_f32_16x16x32_bf16 v[70:73], v[210:213], v[188:191], v[70:73]
	v_mfma_f32_16x16x32_bf16 v[66:69], v[218:221], v[188:191], v[66:69]
	v_mfma_f32_16x16x32_bf16 v[118:121], v[214:217], v[150:153], v[118:121]
	v_mfma_f32_16x16x32_bf16 v[114:117], v[222:225], v[150:153], v[114:117]
	v_mfma_f32_16x16x32_bf16 v[102:105], v[214:217], v[170:173], v[102:105]
	v_mfma_f32_16x16x32_bf16 v[98:101], v[222:225], v[170:173], v[98:101]
	v_mfma_f32_16x16x32_bf16 v[86:89], v[214:217], v[184:187], v[86:89]
	v_mfma_f32_16x16x32_bf16 v[82:85], v[222:225], v[184:187], v[82:85]
	s_mov_b32 m0, s5
	v_mfma_f32_16x16x32_bf16 v[70:73], v[214:217], v[206:209], v[70:73]
	v_lshl_add_u64 v[226:227], s[10:11], 0, v[164:165]
	v_mfma_f32_16x16x32_bf16 v[66:69], v[222:225], v[206:209], v[66:69]
	s_barrier
	s_setprio 0
	ds_read_b128 v[146:149], v181 offset:16384
	ds_read_b128 v[150:153], v181 offset:17408
	ds_read_b128 v[154:157], v181 offset:18432
	ds_read_b128 v[170:173], v181 offset:19456
	ds_read_b128 v[174:177], v181 offset:20480
	ds_read_b128 v[184:187], v181 offset:21504
	ds_read_b128 v[188:191], v181 offset:22528
	ds_read_b128 v[206:209], v181 offset:23552
	global_load_lds_dwordx4 v[226:227], off
	v_lshl_add_u64 v[228:229], s[10:11], 0, v[160:161]
	s_mov_b32 m0, s26
	s_nop 0
	global_load_lds_dwordx4 v[228:229], off
	s_setprio 1
	s_barrier
	s_waitcnt lgkmcnt(0)
	v_mfma_f32_16x16x32_bf16 v[62:65], v[130:133], v[146:149], v[62:65]
	v_mfma_f32_16x16x32_bf16 v[58:61], v[138:141], v[146:149], v[58:61]
	v_mfma_f32_16x16x32_bf16 v[46:49], v[130:133], v[154:157], v[46:49]
	v_mfma_f32_16x16x32_bf16 v[42:45], v[138:141], v[154:157], v[42:45]
	v_mfma_f32_16x16x32_bf16 v[30:33], v[130:133], v[174:177], v[30:33]
	v_mfma_f32_16x16x32_bf16 v[26:29], v[138:141], v[174:177], v[26:29]
	v_mfma_f32_16x16x32_bf16 v[14:17], v[130:133], v[188:191], v[14:17]
	v_mfma_f32_16x16x32_bf16 v[10:13], v[138:141], v[188:191], v[10:13]
	v_mfma_f32_16x16x32_bf16 v[62:65], v[134:137], v[150:153], v[62:65]
	v_mfma_f32_16x16x32_bf16 v[58:61], v[142:145], v[150:153], v[58:61]
	v_mfma_f32_16x16x32_bf16 v[46:49], v[134:137], v[170:173], v[46:49]
	v_mfma_f32_16x16x32_bf16 v[42:45], v[142:145], v[170:173], v[42:45]
	v_mfma_f32_16x16x32_bf16 v[30:33], v[134:137], v[184:187], v[30:33]
	v_mfma_f32_16x16x32_bf16 v[26:29], v[142:145], v[184:187], v[26:29]
	v_mfma_f32_16x16x32_bf16 v[14:17], v[134:137], v[206:209], v[14:17]
	v_mfma_f32_16x16x32_bf16 v[10:13], v[142:145], v[206:209], v[10:13]
	s_barrier
	s_setprio 0
	s_add_u32 s80, s8, 0x100000
	s_addc_u32 s81, s9, 0
	s_mov_b32 m0, s34
	global_load_lds_dwordx4 v162, s[80:81]
	s_mov_b32 m0, s35
	s_nop 0
	global_load_lds_dwordx4 v158, s[80:81]
	s_waitcnt vmcnt(6)
	s_setprio 1
	s_barrier
	v_mfma_f32_16x16x32_bf16 v[54:57], v[210:213], v[146:149], v[54:57]
	v_mfma_f32_16x16x32_bf16 v[50:53], v[218:221], v[146:149], v[50:53]
	v_mfma_f32_16x16x32_bf16 v[38:41], v[210:213], v[154:157], v[38:41]
	v_mfma_f32_16x16x32_bf16 v[34:37], v[218:221], v[154:157], v[34:37]
	v_mfma_f32_16x16x32_bf16 v[22:25], v[210:213], v[174:177], v[22:25]
	v_mfma_f32_16x16x32_bf16 v[18:21], v[218:221], v[174:177], v[18:21]
	v_mfma_f32_16x16x32_bf16 v[6:9], v[210:213], v[188:191], v[6:9]
	v_mfma_f32_16x16x32_bf16 v[2:5], v[218:221], v[188:191], v[2:5]
	v_mfma_f32_16x16x32_bf16 v[54:57], v[214:217], v[150:153], v[54:57]
	v_mfma_f32_16x16x32_bf16 v[50:53], v[222:225], v[150:153], v[50:53]
	v_mfma_f32_16x16x32_bf16 v[38:41], v[214:217], v[170:173], v[38:41]
	v_mfma_f32_16x16x32_bf16 v[34:37], v[222:225], v[170:173], v[34:37]
	v_mfma_f32_16x16x32_bf16 v[22:25], v[214:217], v[184:187], v[22:25]
	v_mfma_f32_16x16x32_bf16 v[18:21], v[222:225], v[184:187], v[18:21]
	v_mfma_f32_16x16x32_bf16 v[6:9], v[214:217], v[206:209], v[6:9]
	v_mfma_f32_16x16x32_bf16 v[2:5], v[222:225], v[206:209], v[2:5]
	s_barrier
	s_setprio 0
	ds_read_b128 v[130:133], v253 offset:32768
	ds_read_b128 v[134:137], v253 offset:33792
	ds_read_b128 v[138:141], v253 offset:34816
	ds_read_b128 v[142:145], v253 offset:35840
	s_add_u32 s10, s10, 0x100000
	s_addc_u32 s11, s11, 0
	s_mov_b32 m0, s42
	ds_read_b128 v[146:149], v181 offset:32768
	ds_read_b128 v[150:153], v181 offset:33792
	ds_read_b128 v[154:157], v181 offset:34816
	ds_read_b128 v[170:173], v181 offset:35840
	ds_read_b128 v[174:177], v181 offset:36864
	ds_read_b128 v[184:187], v181 offset:37888
	ds_read_b128 v[188:191], v181 offset:38912
	ds_read_b128 v[206:209], v181 offset:39936
	global_load_lds_dwordx4 v164, s[10:11]
	s_mov_b32 m0, s54
	s_nop 0
	global_load_lds_dwordx4 v160, s[10:11]
	s_waitcnt lgkmcnt(8)
	s_setprio 1
	s_barrier
	s_waitcnt lgkmcnt(0)
	v_mfma_f32_16x16x32_bf16 v[126:129], v[130:133], v[146:149], v[126:129]
	v_mfma_f32_16x16x32_bf16 v[122:125], v[138:141], v[146:149], v[122:125]
	v_mfma_f32_16x16x32_bf16 v[110:113], v[130:133], v[154:157], v[110:113]
	v_mfma_f32_16x16x32_bf16 v[106:109], v[138:141], v[154:157], v[106:109]
	v_mfma_f32_16x16x32_bf16 v[94:97], v[130:133], v[174:177], v[94:97]
	v_mfma_f32_16x16x32_bf16 v[90:93], v[138:141], v[174:177], v[90:93]
	v_mfma_f32_16x16x32_bf16 v[78:81], v[130:133], v[188:191], v[78:81]
	v_mfma_f32_16x16x32_bf16 v[74:77], v[138:141], v[188:191], v[74:77]
	v_mfma_f32_16x16x32_bf16 v[126:129], v[134:137], v[150:153], v[126:129]
	v_mfma_f32_16x16x32_bf16 v[122:125], v[142:145], v[150:153], v[122:125]
	v_mfma_f32_16x16x32_bf16 v[110:113], v[134:137], v[170:173], v[110:113]
	v_mfma_f32_16x16x32_bf16 v[106:109], v[142:145], v[170:173], v[106:109]
	v_mfma_f32_16x16x32_bf16 v[94:97], v[134:137], v[184:187], v[94:97]
	v_mfma_f32_16x16x32_bf16 v[90:93], v[142:145], v[184:187], v[90:93]
	v_mfma_f32_16x16x32_bf16 v[78:81], v[134:137], v[206:209], v[78:81]
	v_mfma_f32_16x16x32_bf16 v[74:77], v[142:145], v[206:209], v[74:77]
	s_barrier
	s_setprio 0
	s_mov_b32 m0, s55
	ds_read_b128 v[210:213], v253 offset:49152
	ds_read_b128 v[214:217], v253 offset:50176
	v_lshl_add_u64 v[178:179], v[178:179], 0, s[76:77]
	ds_read_b128 v[218:221], v253 offset:51200
	ds_read_b128 v[222:225], v253 offset:52224
	global_load_lds_dwordx4 v[178:179], off
	v_lshl_add_u64 v[178:179], v[192:193], 0, s[76:77]
	s_mov_b32 m0, s56
	s_nop 0
	global_load_lds_dwordx4 v[178:179], off
	s_setprio 1
	s_barrier
	s_waitcnt lgkmcnt(0)
	v_mfma_f32_16x16x32_bf16 v[118:121], v[210:213], v[146:149], v[118:121]
	v_mfma_f32_16x16x32_bf16 v[114:117], v[218:221], v[146:149], v[114:117]
	v_mfma_f32_16x16x32_bf16 v[102:105], v[210:213], v[154:157], v[102:105]
	v_mfma_f32_16x16x32_bf16 v[98:101], v[218:221], v[154:157], v[98:101]
	v_mfma_f32_16x16x32_bf16 v[86:89], v[210:213], v[174:177], v[86:89]
	v_mfma_f32_16x16x32_bf16 v[82:85], v[218:221], v[174:177], v[82:85]
	v_mfma_f32_16x16x32_bf16 v[70:73], v[210:213], v[188:191], v[70:73]
	v_mfma_f32_16x16x32_bf16 v[66:69], v[218:221], v[188:191], v[66:69]
	v_mfma_f32_16x16x32_bf16 v[118:121], v[214:217], v[150:153], v[118:121]
	v_mfma_f32_16x16x32_bf16 v[114:117], v[222:225], v[150:153], v[114:117]
	v_mfma_f32_16x16x32_bf16 v[102:105], v[214:217], v[170:173], v[102:105]
	v_mfma_f32_16x16x32_bf16 v[98:101], v[222:225], v[170:173], v[98:101]
	v_mfma_f32_16x16x32_bf16 v[86:89], v[214:217], v[184:187], v[86:89]
	v_mfma_f32_16x16x32_bf16 v[82:85], v[222:225], v[184:187], v[82:85]
	s_mov_b32 m0, s57
	v_mfma_f32_16x16x32_bf16 v[70:73], v[214:217], v[206:209], v[70:73]
	v_lshl_add_u64 v[178:179], v[226:227], 0, s[76:77]
	v_mfma_f32_16x16x32_bf16 v[66:69], v[222:225], v[206:209], v[66:69]
	s_barrier
	s_setprio 0
	ds_read_b128 v[146:149], v181 offset:49152
	ds_read_b128 v[150:153], v181 offset:50176
	ds_read_b128 v[154:157], v181 offset:51200
	ds_read_b128 v[170:173], v181 offset:52224
	ds_read_b128 v[174:177], v181 offset:53248
	ds_read_b128 v[184:187], v181 offset:54272
	ds_read_b128 v[188:191], v181 offset:55296
	ds_read_b128 v[206:209], v181 offset:56320
	global_load_lds_dwordx4 v[178:179], off
	v_lshl_add_u64 v[178:179], v[228:229], 0, s[76:77]
	s_mov_b32 m0, s58
	s_nop 0
	global_load_lds_dwordx4 v[178:179], off
	s_setprio 1
	s_barrier
	s_waitcnt lgkmcnt(0)
	v_mfma_f32_16x16x32_bf16 v[62:65], v[130:133], v[146:149], v[62:65]
	v_mfma_f32_16x16x32_bf16 v[58:61], v[138:141], v[146:149], v[58:61]
	v_mfma_f32_16x16x32_bf16 v[46:49], v[130:133], v[154:157], v[46:49]
	v_mfma_f32_16x16x32_bf16 v[42:45], v[138:141], v[154:157], v[42:45]
	v_mfma_f32_16x16x32_bf16 v[30:33], v[130:133], v[174:177], v[30:33]
	v_mfma_f32_16x16x32_bf16 v[26:29], v[138:141], v[174:177], v[26:29]
	v_mfma_f32_16x16x32_bf16 v[14:17], v[130:133], v[188:191], v[14:17]
	v_mfma_f32_16x16x32_bf16 v[10:13], v[138:141], v[188:191], v[10:13]
	v_mfma_f32_16x16x32_bf16 v[62:65], v[134:137], v[150:153], v[62:65]
	v_mfma_f32_16x16x32_bf16 v[58:61], v[142:145], v[150:153], v[58:61]
	v_mfma_f32_16x16x32_bf16 v[46:49], v[134:137], v[170:173], v[46:49]
	v_mfma_f32_16x16x32_bf16 v[42:45], v[142:145], v[170:173], v[42:45]
	v_mfma_f32_16x16x32_bf16 v[30:33], v[134:137], v[184:187], v[30:33]
	v_mfma_f32_16x16x32_bf16 v[26:29], v[142:145], v[184:187], v[26:29]
	v_mfma_f32_16x16x32_bf16 v[14:17], v[134:137], v[206:209], v[14:17]
	v_mfma_f32_16x16x32_bf16 v[10:13], v[142:145], v[206:209], v[10:13]
	s_barrier
	s_setprio 0
	s_add_u32 s8, s8, 0x100080
	s_addc_u32 s9, s9, 0
	s_mov_b32 m0, s59
	global_load_lds_dwordx4 v162, s[8:9]
	s_mov_b32 m0, s67
	s_nop 0
	global_load_lds_dwordx4 v158, s[8:9]
	s_waitcnt vmcnt(6)
	s_setprio 1
	s_barrier
	v_mfma_f32_16x16x32_bf16 v[54:57], v[210:213], v[146:149], v[54:57]
	v_mfma_f32_16x16x32_bf16 v[50:53], v[218:221], v[146:149], v[50:53]
	v_mfma_f32_16x16x32_bf16 v[38:41], v[210:213], v[154:157], v[38:41]
	v_mfma_f32_16x16x32_bf16 v[34:37], v[218:221], v[154:157], v[34:37]
	v_mfma_f32_16x16x32_bf16 v[22:25], v[210:213], v[174:177], v[22:25]
	v_mfma_f32_16x16x32_bf16 v[18:21], v[218:221], v[174:177], v[18:21]
	v_mfma_f32_16x16x32_bf16 v[6:9], v[210:213], v[188:191], v[6:9]
	v_mfma_f32_16x16x32_bf16 v[2:5], v[218:221], v[188:191], v[2:5]
	v_mfma_f32_16x16x32_bf16 v[54:57], v[214:217], v[150:153], v[54:57]
	v_mfma_f32_16x16x32_bf16 v[50:53], v[222:225], v[150:153], v[50:53]
	v_mfma_f32_16x16x32_bf16 v[38:41], v[214:217], v[170:173], v[38:41]
	v_mfma_f32_16x16x32_bf16 v[34:37], v[222:225], v[170:173], v[34:37]
	v_mfma_f32_16x16x32_bf16 v[22:25], v[214:217], v[184:187], v[22:25]
	v_mfma_f32_16x16x32_bf16 v[18:21], v[222:225], v[184:187], v[18:21]
	v_mfma_f32_16x16x32_bf16 v[6:9], v[214:217], v[206:209], v[6:9]
	v_mfma_f32_16x16x32_bf16 v[2:5], v[222:225], v[206:209], v[2:5]
	s_setprio 0
	s_add_i32 s79, s79, 2
	s_add_u32 s6, s6, 0x100
	s_addc_u32 s7, s7, 0
	s_add_u32 s1, s1, 0x100
	s_addc_u32 s78, s78, 0
	s_cmp_gt_u32 s79, 61
	s_barrier
	s_cbranch_scc0 .LBB0_255
	s_lshl_b32 s1, s28, 9
	s_and_b32 s1, s1, 0xfffff800
	s_lshl_b32 s6, s29, 8
	s_add_i32 s1, s1, s6
	v_add_u32_e32 v172, s1, v180
	s_lshl_b32 s1, s28, 8
	s_and_b32 s1, s1, 0x300
	v_or_b32_e32 v132, s1, v183
	v_mov_b64_e32 v[170:171], s[50:51]
	v_mad_i64_i32 v[130:131], s[6:7], v172, s37, v[170:171]
	v_lshlrev_b32_e32 v194, 1, v132
	v_lshl_add_u64 v[130:131], v[130:131], 0, v[194:195]
	v_lshl_add_u64 v[132:133], v[130:131], 0, s[84:85]
	v_add_co_u32_e32 v130, vcc, s16, v130
	v_or_b32_e32 v178, 16, v172
	s_nop 0
	v_addc_co_u32_e32 v131, vcc, 0, v131, vcc
	global_load_dwordx4 v[184:187], v[130:131], off offset:2048
	global_load_dwordx4 v[154:157], v[132:133], off offset:256
	v_mad_i64_i32 v[130:131], s[6:7], v178, s37, v[170:171]
	v_lshl_add_u64 v[130:131], v[130:131], 0, v[194:195]
	v_lshl_add_u64 v[132:133], v[130:131], 0, s[84:85]
	v_add_co_u32_e32 v130, vcc, s16, v130
	v_or_b32_e32 v176, 32, v172
	s_nop 0
	v_addc_co_u32_e32 v131, vcc, 0, v131, vcc
	global_load_dwordx4 v[150:153], v[130:131], off offset:2048
	global_load_dwordx4 v[146:149], v[132:133], off offset:256
	v_mad_i64_i32 v[130:131], s[6:7], v176, s37, v[170:171]
	v_lshl_add_u64 v[130:131], v[130:131], 0, v[194:195]
	v_lshl_add_u64 v[132:133], v[130:131], 0, s[84:85]
	v_add_co_u32_e32 v130, vcc, s16, v130
	v_or_b32_e32 v174, 48, v172
	s_nop 0
	v_addc_co_u32_e32 v131, vcc, 0, v131, vcc
	global_load_dwordx4 v[142:145], v[130:131], off offset:2048
	global_load_dwordx4 v[138:141], v[132:133], off offset:256
	v_mad_i64_i32 v[130:131], s[6:7], v174, s37, v[170:171]
	v_lshl_add_u64 v[130:131], v[130:131], 0, v[194:195]
	v_lshl_add_u64 v[132:133], v[130:131], 0, s[84:85]
	v_add_co_u32_e32 v130, vcc, s16, v130
	v_pk_mul_f32 v[126:127], v[126:127], s[72:73] op_sel_hi:[1,0]
	s_nop 0
	v_addc_co_u32_e32 v131, vcc, 0, v131, vcc
	global_load_dwordx4 v[134:137], v[130:131], off offset:2048
	s_nop 0
	global_load_dwordx4 v[130:133], v[132:133], off offset:256
	v_pk_mul_f32 v[190:191], v[124:125], s[72:73] op_sel_hi:[1,0]
	v_pk_mul_f32 v[128:129], v[128:129], s[72:73] op_sel_hi:[1,0]
	v_pk_mul_f32 v[122:123], v[122:123], s[72:73] op_sel_hi:[1,0]
	v_ashrrev_i32_e32 v173, 31, v172
	v_lshlrev_b64 v[188:189], 11, v[172:173]
	v_pk_mul_f32 v[118:119], v[118:119], s[72:73] op_sel_hi:[1,0]
	v_pk_mul_f32 v[120:121], v[120:121], s[72:73] op_sel_hi:[1,0]
	v_pk_mul_f32 v[110:111], v[110:111], s[72:73] op_sel_hi:[1,0]
	v_pk_mul_f32 v[112:113], v[112:113], s[72:73] op_sel_hi:[1,0]
	v_ashrrev_i32_e32 v179, 31, v178
	v_pk_mul_f32 v[102:103], v[102:103], s[72:73] op_sel_hi:[1,0]
	v_pk_mul_f32 v[104:105], v[104:105], s[72:73] op_sel_hi:[1,0]
	v_pk_mul_f32 v[94:95], v[94:95], s[72:73] op_sel_hi:[1,0]
	v_pk_mul_f32 v[96:97], v[96:97], s[72:73] op_sel_hi:[1,0]
	v_ashrrev_i32_e32 v177, 31, v176
	v_pk_mul_f32 v[86:87], v[86:87], s[72:73] op_sel_hi:[1,0]
	v_pk_mul_f32 v[88:89], v[88:89], s[72:73] op_sel_hi:[1,0]
	v_pk_mul_f32 v[78:79], v[78:79], s[72:73] op_sel_hi:[1,0]
	v_pk_mul_f32 v[80:81], v[80:81], s[72:73] op_sel_hi:[1,0]
	v_ashrrev_i32_e32 v175, 31, v174
	v_pk_mul_f32 v[70:71], v[70:71], s[72:73] op_sel_hi:[1,0]
	v_pk_mul_f32 v[72:73], v[72:73], s[72:73] op_sel_hi:[1,0]
	s_waitcnt vmcnt(0)
	v_lshlrev_b32_e32 v124, 16, v184
	v_and_b32_e32 v125, 0xffff0000, v184
	v_mul_f32_e32 v124, v126, v124
	v_mul_f32_e32 v125, v127, v125
	v_cvt_pk_bf16_f32 v124, v124, v125
	v_lshlrev_b32_e32 v125, 16, v185
	v_and_b32_e32 v126, 0xffff0000, v185
	v_mul_f32_e32 v125, v128, v125
	v_mul_f32_e32 v126, v129, v126
	v_cvt_pk_bf16_f32 v125, v125, v126
	v_lshlrev_b32_e32 v126, 16, v186
	v_mul_f32_e32 v122, v122, v126
	v_and_b32_e32 v126, 0xffff0000, v186
	v_mul_f32_e32 v123, v123, v126
	v_cvt_pk_bf16_f32 v126, v122, v123
	v_lshlrev_b32_e32 v122, 16, v187
	v_and_b32_e32 v123, 0xffff0000, v187
	v_mul_f32_e32 v122, v190, v122
	v_mul_f32_e32 v123, v191, v123
	v_cvt_pk_bf16_f32 v127, v122, v123
	v_lshl_add_u64 v[122:123], s[74:75], 0, v[188:189]
	v_lshl_add_u64 v[122:123], v[122:123], 0, v[194:195]
	global_store_dwordx4 v[122:123], v[124:127], off
	s_nop 1
	v_pk_mul_f32 v[124:125], v[116:117], s[72:73] op_sel_hi:[1,0]
	v_pk_mul_f32 v[116:117], v[114:115], s[72:73] op_sel_hi:[1,0]
	v_lshlrev_b32_e32 v114, 16, v154
	v_and_b32_e32 v115, 0xffff0000, v154
	v_mul_f32_e32 v114, v118, v114
	v_mul_f32_e32 v115, v119, v115
	v_cvt_pk_bf16_f32 v114, v114, v115
	v_lshlrev_b32_e32 v115, 16, v155
	v_and_b32_e32 v118, 0xffff0000, v155
	v_mul_f32_e32 v115, v120, v115
	v_mul_f32_e32 v118, v121, v118
	v_cvt_pk_bf16_f32 v115, v115, v118
	v_lshlrev_b32_e32 v118, 16, v156
	v_mul_f32_e32 v116, v116, v118
	v_and_b32_e32 v118, 0xffff0000, v156
	v_mul_f32_e32 v117, v117, v118
	v_cvt_pk_bf16_f32 v116, v116, v117
	v_lshlrev_b32_e32 v117, 16, v157
	v_mul_f32_e32 v117, v124, v117
	v_and_b32_e32 v118, 0xffff0000, v157
	v_mul_f32_e32 v118, v125, v118
	v_cvt_pk_bf16_f32 v117, v117, v118
	global_store_dwordx4 v[122:123], v[114:117], off offset:256
	s_nop 1
	v_pk_mul_f32 v[116:117], v[108:109], s[72:73] op_sel_hi:[1,0]
	v_pk_mul_f32 v[108:109], v[106:107], s[72:73] op_sel_hi:[1,0]
	v_lshlrev_b32_e32 v106, 16, v150
	v_and_b32_e32 v107, 0xffff0000, v150
	v_mul_f32_e32 v106, v110, v106
	v_mul_f32_e32 v107, v111, v107
	v_cvt_pk_bf16_f32 v106, v106, v107
	v_lshlrev_b32_e32 v107, 16, v151
	v_and_b32_e32 v110, 0xffff0000, v151
	v_mul_f32_e32 v107, v112, v107
	v_mul_f32_e32 v110, v113, v110
	v_cvt_pk_bf16_f32 v107, v107, v110
	v_lshlrev_b32_e32 v110, 16, v152
	v_mul_f32_e32 v108, v108, v110
	v_and_b32_e32 v110, 0xffff0000, v152
	v_mul_f32_e32 v109, v109, v110
	v_cvt_pk_bf16_f32 v108, v108, v109
	v_lshlrev_b32_e32 v109, 16, v153
	v_and_b32_e32 v110, 0xffff0000, v153
	v_lshlrev_b64 v[114:115], 11, v[178:179]
	v_mul_f32_e32 v109, v116, v109
	v_mul_f32_e32 v110, v117, v110
	v_cvt_pk_bf16_f32 v109, v109, v110
	v_lshl_add_u64 v[110:111], s[74:75], 0, v[114:115]
	v_lshl_add_u64 v[110:111], v[110:111], 0, v[194:195]
	global_store_dwordx4 v[110:111], v[106:109], off
	s_nop 1
	v_pk_mul_f32 v[106:107], v[100:101], s[72:73] op_sel_hi:[1,0]
	v_pk_mul_f32 v[100:101], v[98:99], s[72:73] op_sel_hi:[1,0]
	v_lshlrev_b32_e32 v98, 16, v146
	v_and_b32_e32 v99, 0xffff0000, v146
	v_mul_f32_e32 v98, v102, v98
	v_mul_f32_e32 v99, v103, v99
	v_cvt_pk_bf16_f32 v98, v98, v99
	v_lshlrev_b32_e32 v99, 16, v147
	v_and_b32_e32 v102, 0xffff0000, v147
	v_mul_f32_e32 v99, v104, v99
	v_mul_f32_e32 v102, v105, v102
	v_cvt_pk_bf16_f32 v99, v99, v102
	v_lshlrev_b32_e32 v102, 16, v148
	v_mul_f32_e32 v100, v100, v102
	v_and_b32_e32 v102, 0xffff0000, v148
	v_mul_f32_e32 v101, v101, v102
	v_cvt_pk_bf16_f32 v100, v100, v101
	v_lshlrev_b32_e32 v101, 16, v149
	v_mul_f32_e32 v101, v106, v101
	v_and_b32_e32 v102, 0xffff0000, v149
	v_mul_f32_e32 v102, v107, v102
	v_cvt_pk_bf16_f32 v101, v101, v102
	global_store_dwordx4 v[110:111], v[98:101], off offset:256
	s_nop 1
	v_pk_mul_f32 v[100:101], v[92:93], s[72:73] op_sel_hi:[1,0]
	v_pk_mul_f32 v[92:93], v[90:91], s[72:73] op_sel_hi:[1,0]
	v_lshlrev_b32_e32 v90, 16, v142
	v_and_b32_e32 v91, 0xffff0000, v142
	v_mul_f32_e32 v90, v94, v90
	v_mul_f32_e32 v91, v95, v91
	v_cvt_pk_bf16_f32 v90, v90, v91
	v_lshlrev_b32_e32 v91, 16, v143
	v_and_b32_e32 v94, 0xffff0000, v143
	v_mul_f32_e32 v91, v96, v91
	v_mul_f32_e32 v94, v97, v94
	v_cvt_pk_bf16_f32 v91, v91, v94
	v_lshlrev_b32_e32 v94, 16, v144
	v_mul_f32_e32 v92, v92, v94
	v_and_b32_e32 v94, 0xffff0000, v144
	v_mul_f32_e32 v93, v93, v94
	v_cvt_pk_bf16_f32 v92, v92, v93
	v_lshlrev_b32_e32 v93, 16, v145
	v_and_b32_e32 v94, 0xffff0000, v145
	v_lshlrev_b64 v[98:99], 11, v[176:177]
	v_mul_f32_e32 v93, v100, v93
	v_mul_f32_e32 v94, v101, v94
	v_cvt_pk_bf16_f32 v93, v93, v94
	v_lshl_add_u64 v[94:95], s[74:75], 0, v[98:99]
	v_lshl_add_u64 v[94:95], v[94:95], 0, v[194:195]
	global_store_dwordx4 v[94:95], v[90:93], off
	s_nop 1
	v_pk_mul_f32 v[90:91], v[84:85], s[72:73] op_sel_hi:[1,0]
	v_pk_mul_f32 v[84:85], v[82:83], s[72:73] op_sel_hi:[1,0]
	v_lshlrev_b32_e32 v82, 16, v138
	v_and_b32_e32 v83, 0xffff0000, v138
	v_mul_f32_e32 v82, v86, v82
	v_mul_f32_e32 v83, v87, v83
	v_cvt_pk_bf16_f32 v82, v82, v83
	v_lshlrev_b32_e32 v83, 16, v139
	v_and_b32_e32 v86, 0xffff0000, v139
	v_mul_f32_e32 v83, v88, v83
	v_mul_f32_e32 v86, v89, v86
	v_cvt_pk_bf16_f32 v83, v83, v86
	v_lshlrev_b32_e32 v86, 16, v140
	v_mul_f32_e32 v84, v84, v86
	v_and_b32_e32 v86, 0xffff0000, v140
	v_mul_f32_e32 v85, v85, v86
	v_cvt_pk_bf16_f32 v84, v84, v85
	v_lshlrev_b32_e32 v85, 16, v141
	v_mul_f32_e32 v85, v90, v85
	v_and_b32_e32 v86, 0xffff0000, v141
	v_mul_f32_e32 v86, v91, v86
	v_cvt_pk_bf16_f32 v85, v85, v86
	global_store_dwordx4 v[94:95], v[82:85], off offset:256
	s_nop 1
	v_pk_mul_f32 v[84:85], v[76:77], s[72:73] op_sel_hi:[1,0]
	v_pk_mul_f32 v[76:77], v[74:75], s[72:73] op_sel_hi:[1,0]
	v_lshlrev_b32_e32 v74, 16, v134
	v_and_b32_e32 v75, 0xffff0000, v134
	v_mul_f32_e32 v74, v78, v74
	v_mul_f32_e32 v75, v79, v75
	v_cvt_pk_bf16_f32 v74, v74, v75
	v_lshlrev_b32_e32 v75, 16, v135
	v_and_b32_e32 v78, 0xffff0000, v135
	v_mul_f32_e32 v75, v80, v75
	v_mul_f32_e32 v78, v81, v78
	v_cvt_pk_bf16_f32 v75, v75, v78
	v_lshlrev_b32_e32 v78, 16, v136
	v_mul_f32_e32 v76, v76, v78
	v_and_b32_e32 v78, 0xffff0000, v136
	v_mul_f32_e32 v77, v77, v78
	v_cvt_pk_bf16_f32 v76, v76, v77
	v_lshlrev_b32_e32 v77, 16, v137
	v_and_b32_e32 v78, 0xffff0000, v137
	v_lshlrev_b64 v[82:83], 11, v[174:175]
	v_mul_f32_e32 v77, v84, v77
	v_mul_f32_e32 v78, v85, v78
	v_cvt_pk_bf16_f32 v77, v77, v78
	v_lshl_add_u64 v[78:79], s[74:75], 0, v[82:83]
	v_lshl_add_u64 v[78:79], v[78:79], 0, v[194:195]
	global_store_dwordx4 v[78:79], v[74:77], off
	s_nop 1
	v_pk_mul_f32 v[74:75], v[68:69], s[72:73] op_sel_hi:[1,0]
	v_pk_mul_f32 v[68:69], v[66:67], s[72:73] op_sel_hi:[1,0]
	v_lshlrev_b32_e32 v66, 16, v130
	v_and_b32_e32 v67, 0xffff0000, v130
	v_mul_f32_e32 v66, v70, v66
	v_mul_f32_e32 v67, v71, v67
	v_cvt_pk_bf16_f32 v66, v66, v67
	v_lshlrev_b32_e32 v67, 16, v131
	v_and_b32_e32 v70, 0xffff0000, v131
	v_mul_f32_e32 v67, v72, v67
	v_mul_f32_e32 v70, v73, v70
	v_cvt_pk_bf16_f32 v67, v67, v70
	v_lshlrev_b32_e32 v70, 16, v132
	v_mul_f32_e32 v68, v68, v70
	v_and_b32_e32 v70, 0xffff0000, v132
	v_mul_f32_e32 v69, v69, v70
	v_cvt_pk_bf16_f32 v68, v68, v69
	v_lshlrev_b32_e32 v69, 16, v133
	v_mul_f32_e32 v69, v74, v69
	v_and_b32_e32 v70, 0xffff0000, v133
	v_mul_f32_e32 v70, v75, v70
	v_cvt_pk_bf16_f32 v69, v69, v70
	global_store_dwordx4 v[78:79], v[66:69], off offset:256
	v_add_u32_e32 v78, 0x80, v172
	s_nop 0
	v_mad_i64_i32 v[66:67], s[6:7], v78, s37, v[170:171]
	v_lshl_add_u64 v[66:67], v[66:67], 0, v[194:195]
	v_add_co_u32_e32 v68, vcc, s16, v66
	v_add_u32_e32 v86, 0x90, v172
	s_nop 0
	v_addc_co_u32_e32 v69, vcc, 0, v67, vcc
	global_load_dwordx4 v[70:73], v[68:69], off offset:2048
	v_lshl_add_u64 v[66:67], v[66:67], 0, s[84:85]
	global_load_dwordx4 v[74:77], v[66:67], off offset:256
	v_pk_mul_f32 v[96:97], v[56:57], s[72:73] op_sel_hi:[1,0]
	v_mad_i64_i32 v[56:57], s[6:7], v86, s37, v[170:171]
	v_lshl_add_u64 v[56:57], v[56:57], 0, v[194:195]
	v_pk_mul_f32 v[94:95], v[58:59], s[72:73] op_sel_hi:[1,0]
	v_add_co_u32_e32 v58, vcc, s16, v56
	v_pk_mul_f32 v[92:93], v[60:61], s[72:73] op_sel_hi:[1,0]
	s_nop 0
	v_addc_co_u32_e32 v59, vcc, 0, v57, vcc
	global_load_dwordx4 v[58:61], v[58:59], off offset:2048
	v_add_u32_e32 v68, 0xa0, v172
	v_pk_mul_f32 v[102:103], v[50:51], s[72:73] op_sel_hi:[1,0]
	v_mad_i64_i32 v[50:51], s[6:7], v68, s37, v[170:171]
	v_add_u32_e32 v66, 0xb0, v172
	v_lshl_add_u64 v[50:51], v[50:51], 0, v[194:195]
	v_pk_mul_f32 v[100:101], v[52:53], s[72:73] op_sel_hi:[1,0]
	v_mad_i64_i32 v[52:53], s[6:7], v66, s37, v[170:171]
	v_lshl_add_u64 v[82:83], v[50:51], 0, s[84:85]
	v_add_co_u32_e32 v50, vcc, s16, v50
	v_lshl_add_u64 v[52:53], v[52:53], 0, v[194:195]
	s_nop 0
	v_addc_co_u32_e32 v51, vcc, 0, v51, vcc
	v_ashrrev_i32_e32 v79, 31, v78
	v_lshl_add_u64 v[104:105], v[52:53], 0, s[84:85]
	v_add_co_u32_e32 v52, vcc, s16, v52
	v_pk_mul_f32 v[98:99], v[54:55], s[72:73] op_sel_hi:[1,0]
	v_lshlrev_b64 v[54:55], 11, v[78:79]
	v_lshl_add_u64 v[56:57], v[56:57], 0, s[84:85]
	v_addc_co_u32_e32 v53, vcc, 0, v53, vcc
	v_pk_mul_f32 v[88:89], v[64:65], s[72:73] op_sel_hi:[1,0]
	v_pk_mul_f32 v[90:91], v[62:63], s[72:73] op_sel_hi:[1,0]
	v_lshl_add_u64 v[106:107], s[74:75], 0, v[54:55]
	global_load_dwordx4 v[62:65], v[56:57], off offset:256
	global_load_dwordx4 v[78:81], v[50:51], off offset:2048
	s_nop 0
	global_load_dwordx4 v[82:85], v[82:83], off offset:256
	s_nop 0
	global_load_dwordx4 v[54:57], v[52:53], off offset:2048
	s_nop 0
	global_load_dwordx4 v[50:53], v[104:105], off offset:256
	v_lshl_add_u64 v[104:105], v[106:107], 0, v[194:195]
	v_pk_mul_f32 v[46:47], v[46:47], s[72:73] op_sel_hi:[1,0]
	v_pk_mul_f32 v[48:49], v[48:49], s[72:73] op_sel_hi:[1,0]
	v_ashrrev_i32_e32 v87, 31, v86
	v_pk_mul_f32 v[38:39], v[38:39], s[72:73] op_sel_hi:[1,0]
	v_pk_mul_f32 v[40:41], v[40:41], s[72:73] op_sel_hi:[1,0]
	v_pk_mul_f32 v[30:31], v[30:31], s[72:73] op_sel_hi:[1,0]
	v_pk_mul_f32 v[32:33], v[32:33], s[72:73] op_sel_hi:[1,0]
	v_ashrrev_i32_e32 v69, 31, v68
	v_pk_mul_f32 v[22:23], v[22:23], s[72:73] op_sel_hi:[1,0]
	v_pk_mul_f32 v[24:25], v[24:25], s[72:73] op_sel_hi:[1,0]
	v_pk_mul_f32 v[14:15], v[14:15], s[72:73] op_sel_hi:[1,0]
	v_pk_mul_f32 v[16:17], v[16:17], s[72:73] op_sel_hi:[1,0]
	v_ashrrev_i32_e32 v67, 31, v66
	v_pk_mul_f32 v[6:7], v[6:7], s[72:73] op_sel_hi:[1,0]
	v_pk_mul_f32 v[8:9], v[8:9], s[72:73] op_sel_hi:[1,0]
	s_waitcnt vmcnt(0)
	v_lshlrev_b32_e32 v106, 16, v70
	v_and_b32_e32 v70, 0xffff0000, v70
	v_lshlrev_b32_e32 v107, 16, v71
	v_and_b32_e32 v71, 0xffff0000, v71
	v_lshlrev_b32_e32 v108, 16, v72
	v_and_b32_e32 v72, 0xffff0000, v72
	v_lshlrev_b32_e32 v109, 16, v73
	v_and_b32_e32 v73, 0xffff0000, v73
	v_mul_f32_e32 v70, v91, v70
	v_mul_f32_e32 v71, v89, v71
	v_mul_f32_e32 v72, v95, v72
	v_mul_f32_e32 v73, v93, v73
	v_mul_f32_e32 v90, v90, v106
	v_mul_f32_e32 v88, v88, v107
	v_mul_f32_e32 v89, v94, v108
	v_mul_f32_e32 v91, v92, v109
	v_cvt_pk_bf16_f32 v70, v90, v70
	v_cvt_pk_bf16_f32 v71, v88, v71
	v_cvt_pk_bf16_f32 v72, v89, v72
	v_cvt_pk_bf16_f32 v73, v91, v73
	v_lshlrev_b32_e32 v111, 16, v75
	v_and_b32_e32 v75, 0xffff0000, v75
	global_store_dwordx4 v[104:105], v[70:73], off
	v_lshlrev_b32_e32 v110, 16, v74
	v_and_b32_e32 v74, 0xffff0000, v74
	v_lshlrev_b32_e32 v72, 16, v76
	v_and_b32_e32 v73, 0xffff0000, v76
	v_mul_f32_e32 v71, v97, v75
	v_mul_f32_e32 v72, v102, v72
	v_mul_f32_e32 v73, v103, v73
	v_mul_f32_e32 v92, v98, v110
	v_mul_f32_e32 v74, v99, v74
	v_mul_f32_e32 v93, v96, v111
	v_cvt_pk_bf16_f32 v70, v92, v74
	v_cvt_pk_bf16_f32 v71, v93, v71
	v_cvt_pk_bf16_f32 v72, v72, v73
	v_lshlrev_b32_e32 v73, 16, v77
	v_mul_f32_e32 v73, v100, v73
	v_and_b32_e32 v74, 0xffff0000, v77
	v_mul_f32_e32 v74, v101, v74
	v_cvt_pk_bf16_f32 v73, v73, v74
	global_store_dwordx4 v[104:105], v[70:73], off offset:256
	s_nop 1
	v_pk_mul_f32 v[72:73], v[44:45], s[72:73] op_sel_hi:[1,0]
	v_pk_mul_f32 v[44:45], v[42:43], s[72:73] op_sel_hi:[1,0]
	v_lshlrev_b32_e32 v42, 16, v58
	v_and_b32_e32 v43, 0xffff0000, v58
	v_mul_f32_e32 v42, v46, v42
	v_mul_f32_e32 v43, v47, v43
	v_cvt_pk_bf16_f32 v42, v42, v43
	v_lshlrev_b32_e32 v43, 16, v59
	v_and_b32_e32 v46, 0xffff0000, v59
	v_mul_f32_e32 v43, v48, v43
	v_mul_f32_e32 v46, v49, v46
	v_cvt_pk_bf16_f32 v43, v43, v46
	v_lshlrev_b32_e32 v46, 16, v60
	v_mul_f32_e32 v44, v44, v46
	v_and_b32_e32 v46, 0xffff0000, v60
	v_mul_f32_e32 v45, v45, v46
	v_cvt_pk_bf16_f32 v44, v44, v45
	v_lshlrev_b32_e32 v45, 16, v61
	v_and_b32_e32 v46, 0xffff0000, v61
	v_lshlrev_b64 v[70:71], 11, v[86:87]
	v_mul_f32_e32 v45, v72, v45
	v_mul_f32_e32 v46, v73, v46
	v_cvt_pk_bf16_f32 v45, v45, v46
	v_lshl_add_u64 v[46:47], s[74:75], 0, v[70:71]
	v_lshl_add_u64 v[46:47], v[46:47], 0, v[194:195]
	global_store_dwordx4 v[46:47], v[42:45], off
	s_nop 1
	v_pk_mul_f32 v[42:43], v[36:37], s[72:73] op_sel_hi:[1,0]
	v_pk_mul_f32 v[36:37], v[34:35], s[72:73] op_sel_hi:[1,0]
	v_lshlrev_b32_e32 v34, 16, v62
	v_and_b32_e32 v35, 0xffff0000, v62
	v_mul_f32_e32 v34, v38, v34
	v_mul_f32_e32 v35, v39, v35
	v_cvt_pk_bf16_f32 v34, v34, v35
	v_lshlrev_b32_e32 v35, 16, v63
	v_and_b32_e32 v38, 0xffff0000, v63
	v_mul_f32_e32 v35, v40, v35
	v_mul_f32_e32 v38, v41, v38
	v_cvt_pk_bf16_f32 v35, v35, v38
	v_lshlrev_b32_e32 v38, 16, v64
	v_mul_f32_e32 v36, v36, v38
	v_and_b32_e32 v38, 0xffff0000, v64
	v_mul_f32_e32 v37, v37, v38
	v_cvt_pk_bf16_f32 v36, v36, v37
	v_lshlrev_b32_e32 v37, 16, v65
	v_mul_f32_e32 v37, v42, v37
	v_and_b32_e32 v38, 0xffff0000, v65
	v_mul_f32_e32 v38, v43, v38
	v_cvt_pk_bf16_f32 v37, v37, v38
	global_store_dwordx4 v[46:47], v[34:37], off offset:256
	s_nop 1
	v_pk_mul_f32 v[36:37], v[28:29], s[72:73] op_sel_hi:[1,0]
	v_pk_mul_f32 v[28:29], v[26:27], s[72:73] op_sel_hi:[1,0]
	v_lshlrev_b32_e32 v26, 16, v78
	v_and_b32_e32 v27, 0xffff0000, v78
	v_mul_f32_e32 v26, v30, v26
	v_mul_f32_e32 v27, v31, v27
	v_cvt_pk_bf16_f32 v26, v26, v27
	v_lshlrev_b32_e32 v27, 16, v79
	v_and_b32_e32 v30, 0xffff0000, v79
	v_mul_f32_e32 v27, v32, v27
	v_mul_f32_e32 v30, v33, v30
	v_cvt_pk_bf16_f32 v27, v27, v30
	v_lshlrev_b32_e32 v30, 16, v80
	v_mul_f32_e32 v28, v28, v30
	v_and_b32_e32 v30, 0xffff0000, v80
	v_mul_f32_e32 v29, v29, v30
	v_cvt_pk_bf16_f32 v28, v28, v29
	v_lshlrev_b32_e32 v29, 16, v81
	v_and_b32_e32 v30, 0xffff0000, v81
	v_lshlrev_b64 v[34:35], 11, v[68:69]
	v_mul_f32_e32 v29, v36, v29
	v_mul_f32_e32 v30, v37, v30
	v_cvt_pk_bf16_f32 v29, v29, v30
	v_lshl_add_u64 v[30:31], s[74:75], 0, v[34:35]
	v_lshl_add_u64 v[30:31], v[30:31], 0, v[194:195]
	global_store_dwordx4 v[30:31], v[26:29], off
	s_nop 1
	v_pk_mul_f32 v[26:27], v[20:21], s[72:73] op_sel_hi:[1,0]
	v_pk_mul_f32 v[20:21], v[18:19], s[72:73] op_sel_hi:[1,0]
	v_lshlrev_b32_e32 v18, 16, v82
	v_and_b32_e32 v19, 0xffff0000, v82
	v_mul_f32_e32 v18, v22, v18
	v_mul_f32_e32 v19, v23, v19
	v_cvt_pk_bf16_f32 v18, v18, v19
	v_lshlrev_b32_e32 v19, 16, v83
	v_and_b32_e32 v22, 0xffff0000, v83
	v_mul_f32_e32 v19, v24, v19
	v_mul_f32_e32 v22, v25, v22
	v_cvt_pk_bf16_f32 v19, v19, v22
	v_lshlrev_b32_e32 v22, 16, v84
	v_mul_f32_e32 v20, v20, v22
	v_and_b32_e32 v22, 0xffff0000, v84
	v_mul_f32_e32 v21, v21, v22
	v_cvt_pk_bf16_f32 v20, v20, v21
	v_lshlrev_b32_e32 v21, 16, v85
	v_mul_f32_e32 v21, v26, v21
	v_and_b32_e32 v22, 0xffff0000, v85
	v_mul_f32_e32 v22, v27, v22
	v_cvt_pk_bf16_f32 v21, v21, v22
	global_store_dwordx4 v[30:31], v[18:21], off offset:256
	s_nop 1
	v_pk_mul_f32 v[20:21], v[12:13], s[72:73] op_sel_hi:[1,0]
	v_pk_mul_f32 v[12:13], v[10:11], s[72:73] op_sel_hi:[1,0]
	v_lshlrev_b32_e32 v10, 16, v54
	v_and_b32_e32 v11, 0xffff0000, v54
	v_mul_f32_e32 v10, v14, v10
	v_mul_f32_e32 v11, v15, v11
	v_cvt_pk_bf16_f32 v10, v10, v11
	v_lshlrev_b32_e32 v11, 16, v55
	v_and_b32_e32 v14, 0xffff0000, v55
	v_mul_f32_e32 v11, v16, v11
	v_mul_f32_e32 v14, v17, v14
	v_cvt_pk_bf16_f32 v11, v11, v14
	v_lshlrev_b32_e32 v14, 16, v56
	v_mul_f32_e32 v12, v12, v14
	v_and_b32_e32 v14, 0xffff0000, v56
	v_mul_f32_e32 v13, v13, v14
	v_cvt_pk_bf16_f32 v12, v12, v13
	v_lshlrev_b32_e32 v13, 16, v57
	v_and_b32_e32 v14, 0xffff0000, v57
	v_lshlrev_b64 v[18:19], 11, v[66:67]
	v_mul_f32_e32 v13, v20, v13
	v_mul_f32_e32 v14, v21, v14
	v_cvt_pk_bf16_f32 v13, v13, v14
	v_lshl_add_u64 v[14:15], s[74:75], 0, v[18:19]
	v_lshl_add_u64 v[14:15], v[14:15], 0, v[194:195]
	global_store_dwordx4 v[14:15], v[10:13], off
	s_nop 1
	v_pk_mul_f32 v[10:11], v[4:5], s[72:73] op_sel_hi:[1,0]
	v_pk_mul_f32 v[4:5], v[2:3], s[72:73] op_sel_hi:[1,0]
	v_lshlrev_b32_e32 v2, 16, v50
	v_and_b32_e32 v3, 0xffff0000, v50
	v_mul_f32_e32 v2, v6, v2
	v_mul_f32_e32 v3, v7, v3
	v_cvt_pk_bf16_f32 v2, v2, v3
	v_lshlrev_b32_e32 v3, 16, v51
	v_and_b32_e32 v6, 0xffff0000, v51
	v_mul_f32_e32 v3, v8, v3
	v_mul_f32_e32 v6, v9, v6
	v_cvt_pk_bf16_f32 v3, v3, v6
	v_lshlrev_b32_e32 v6, 16, v52
	v_mul_f32_e32 v4, v4, v6
	v_and_b32_e32 v6, 0xffff0000, v52
	v_mul_f32_e32 v5, v5, v6
	v_cvt_pk_bf16_f32 v4, v4, v5
	v_lshlrev_b32_e32 v5, 16, v53
	v_mul_f32_e32 v5, v10, v5
	v_and_b32_e32 v6, 0xffff0000, v53
	v_mul_f32_e32 v6, v11, v6
	v_cvt_pk_bf16_f32 v5, v5, v6
	global_store_dwordx4 v[14:15], v[2:5], off offset:256
	s_and_b64 vcc, exec, s[62:63]
	s_mov_b32 s29, s71
	s_mov_b32 s28, s0
	s_mov_b64 s[8:9], s[60:61]
	s_mov_b64 s[6:7], s[52:53]
	s_cbranch_vccz .LBB0_252
	s_waitcnt vmcnt(0)
	v_readlane_b32 s28, v250, 12
	s_cmpk_gt_u32 s4, 0xff
	v_readlane_b32 s29, v250, 13
	s_mov_b32 s70, 0x800000
	s_cbranch_scc1 .LBB0_259
	s_barrier

.LBB0_266:
	s_add_u32 s8, s6, 0x100
	s_addc_u32 s9, s7, 0
	v_add_u32_e32 v253, 0x10000, v147
	s_add_u32 s10, s71, s6
	ds_read_b128 v[142:145], v253
	ds_read_b128 v[150:153], v253 offset:1024
	ds_read_b128 v[154:157], v253 offset:2048
	ds_read_b128 v[158:161], v253 offset:3072
	s_addc_u32 s11, s78, s7
	s_cmp_eq_u32 s79, 4
	s_cselect_b32 s81, 0, s8
	s_cselect_b32 s80, 0, s9
	s_cselect_b32 s54, s29, s10
	s_cselect_b32 s55, s5, s11
	s_add_u32 s10, s18, s81
	s_addc_u32 s11, s19, s80
	v_lshl_add_u64 v[206:207], v[138:139], 0, s[6:7]
	s_add_i32 m0, s17, 0xc000
	ds_read_b128 v[162:165], v146
	ds_read_b128 v[166:169], v146 offset:1024
	ds_read_b128 v[170:173], v146 offset:2048
	ds_read_b128 v[174:177], v146 offset:3072
	ds_read_b128 v[178:181], v146 offset:4096
	ds_read_b128 v[182:185], v146 offset:5120
	ds_read_b128 v[186:189], v146 offset:6144
	ds_read_b128 v[190:193], v146 offset:7168
	global_load_lds_dwordx4 v[206:207], off
	v_lshl_add_u64 v[206:207], v[140:141], 0, s[6:7]
	s_add_i32 m0, s17, 0xe000
	s_nop 0
	global_load_lds_dwordx4 v[206:207], off
	s_waitcnt lgkmcnt(8)
	s_setprio 1
	s_barrier
	s_waitcnt lgkmcnt(0)
	v_mfma_f32_16x16x32_bf16 v[126:129], v[142:145], v[162:165], v[126:129]
	v_mfma_f32_16x16x32_bf16 v[122:125], v[154:157], v[162:165], v[122:125]
	v_mfma_f32_16x16x32_bf16 v[110:113], v[142:145], v[170:173], v[110:113]
	v_mfma_f32_16x16x32_bf16 v[106:109], v[154:157], v[170:173], v[106:109]
	v_mfma_f32_16x16x32_bf16 v[94:97], v[142:145], v[178:181], v[94:97]
	v_mfma_f32_16x16x32_bf16 v[90:93], v[154:157], v[178:181], v[90:93]
	v_mfma_f32_16x16x32_bf16 v[78:81], v[142:145], v[186:189], v[78:81]
	v_mfma_f32_16x16x32_bf16 v[74:77], v[154:157], v[186:189], v[74:77]
	v_mfma_f32_16x16x32_bf16 v[126:129], v[150:153], v[166:169], v[126:129]
	v_mfma_f32_16x16x32_bf16 v[122:125], v[158:161], v[166:169], v[122:125]
	v_mfma_f32_16x16x32_bf16 v[110:113], v[150:153], v[174:177], v[110:113]
	v_mfma_f32_16x16x32_bf16 v[106:109], v[158:161], v[174:177], v[106:109]
	v_mfma_f32_16x16x32_bf16 v[94:97], v[150:153], v[182:185], v[94:97]
	v_mfma_f32_16x16x32_bf16 v[90:93], v[158:161], v[182:185], v[90:93]
	v_mfma_f32_16x16x32_bf16 v[78:81], v[150:153], v[190:193], v[78:81]
	v_mfma_f32_16x16x32_bf16 v[74:77], v[158:161], v[190:193], v[74:77]
	s_barrier
	s_setprio 0
	s_mov_b32 m0, s26
	ds_read_b128 v[206:209], v253 offset:16384
	ds_read_b128 v[210:213], v253 offset:17408
	v_lshl_add_u64 v[222:223], s[54:55], 0, v[134:135]
	ds_read_b128 v[214:217], v253 offset:18432
	ds_read_b128 v[218:221], v253 offset:19456
	global_load_lds_dwordx4 v[222:223], off
	v_lshl_add_u64 v[224:225], s[54:55], 0, v[130:131]
	s_mov_b32 m0, s34
	s_nop 0
	global_load_lds_dwordx4 v[224:225], off
	s_setprio 1
	s_barrier
	s_waitcnt lgkmcnt(0)
	v_mfma_f32_16x16x32_bf16 v[118:121], v[206:209], v[162:165], v[118:121]
	v_mfma_f32_16x16x32_bf16 v[114:117], v[214:217], v[162:165], v[114:117]
	v_mfma_f32_16x16x32_bf16 v[102:105], v[206:209], v[170:173], v[102:105]
	v_mfma_f32_16x16x32_bf16 v[98:101], v[214:217], v[170:173], v[98:101]
	v_mfma_f32_16x16x32_bf16 v[86:89], v[206:209], v[178:181], v[86:89]
	v_mfma_f32_16x16x32_bf16 v[82:85], v[214:217], v[178:181], v[82:85]
	v_mfma_f32_16x16x32_bf16 v[70:73], v[206:209], v[186:189], v[70:73]
	v_mfma_f32_16x16x32_bf16 v[66:69], v[214:217], v[186:189], v[66:69]
	v_mfma_f32_16x16x32_bf16 v[118:121], v[210:213], v[166:169], v[118:121]
	v_mfma_f32_16x16x32_bf16 v[114:117], v[218:221], v[166:169], v[114:117]
	v_mfma_f32_16x16x32_bf16 v[102:105], v[210:213], v[174:177], v[102:105]
	v_mfma_f32_16x16x32_bf16 v[98:101], v[218:221], v[174:177], v[98:101]
	v_mfma_f32_16x16x32_bf16 v[86:89], v[210:213], v[182:185], v[86:89]
	v_mfma_f32_16x16x32_bf16 v[82:85], v[218:221], v[182:185], v[82:85]
	s_mov_b32 m0, s17
	v_mfma_f32_16x16x32_bf16 v[70:73], v[210:213], v[190:193], v[70:73]
	v_lshl_add_u64 v[226:227], s[10:11], 0, v[136:137]
	v_mfma_f32_16x16x32_bf16 v[66:69], v[218:221], v[190:193], v[66:69]
	s_barrier
	s_setprio 0
	ds_read_b128 v[162:165], v146 offset:16384
	ds_read_b128 v[166:169], v146 offset:17408
	ds_read_b128 v[170:173], v146 offset:18432
	ds_read_b128 v[174:177], v146 offset:19456
	ds_read_b128 v[178:181], v146 offset:20480
	ds_read_b128 v[182:185], v146 offset:21504
	ds_read_b128 v[186:189], v146 offset:22528
	ds_read_b128 v[190:193], v146 offset:23552
	global_load_lds_dwordx4 v[226:227], off
	v_lshl_add_u64 v[228:229], s[10:11], 0, v[132:133]
	s_mov_b32 m0, s35
	s_nop 0
	global_load_lds_dwordx4 v[228:229], off
	s_setprio 1
	s_barrier
	s_waitcnt lgkmcnt(0)
	v_mfma_f32_16x16x32_bf16 v[62:65], v[142:145], v[162:165], v[62:65]
	v_mfma_f32_16x16x32_bf16 v[58:61], v[154:157], v[162:165], v[58:61]
	v_mfma_f32_16x16x32_bf16 v[46:49], v[142:145], v[170:173], v[46:49]
	v_mfma_f32_16x16x32_bf16 v[42:45], v[154:157], v[170:173], v[42:45]
	v_mfma_f32_16x16x32_bf16 v[30:33], v[142:145], v[178:181], v[30:33]
	v_mfma_f32_16x16x32_bf16 v[26:29], v[154:157], v[178:181], v[26:29]
	v_mfma_f32_16x16x32_bf16 v[14:17], v[142:145], v[186:189], v[14:17]
	v_mfma_f32_16x16x32_bf16 v[10:13], v[154:157], v[186:189], v[10:13]
	v_mfma_f32_16x16x32_bf16 v[62:65], v[150:153], v[166:169], v[62:65]
	v_mfma_f32_16x16x32_bf16 v[58:61], v[158:161], v[166:169], v[58:61]
	v_mfma_f32_16x16x32_bf16 v[46:49], v[150:153], v[174:177], v[46:49]
	v_mfma_f32_16x16x32_bf16 v[42:45], v[158:161], v[174:177], v[42:45]
	v_mfma_f32_16x16x32_bf16 v[30:33], v[150:153], v[182:185], v[30:33]
	v_mfma_f32_16x16x32_bf16 v[26:29], v[158:161], v[182:185], v[26:29]
	v_mfma_f32_16x16x32_bf16 v[14:17], v[150:153], v[190:193], v[14:17]
	v_mfma_f32_16x16x32_bf16 v[10:13], v[158:161], v[190:193], v[10:13]
	s_barrier
	s_setprio 0
	s_add_u32 s6, s54, 0x20000
	s_addc_u32 s7, s55, 0
	s_mov_b32 m0, s42
	global_load_lds_dwordx4 v134, s[6:7]
	s_mov_b32 m0, s56
	s_nop 0
	global_load_lds_dwordx4 v130, s[6:7]
	s_waitcnt vmcnt(6)
	s_setprio 1
	s_barrier
	v_mfma_f32_16x16x32_bf16 v[54:57], v[206:209], v[162:165], v[54:57]
	v_mfma_f32_16x16x32_bf16 v[50:53], v[214:217], v[162:165], v[50:53]
	v_mfma_f32_16x16x32_bf16 v[38:41], v[206:209], v[170:173], v[38:41]
	v_mfma_f32_16x16x32_bf16 v[34:37], v[214:217], v[170:173], v[34:37]
	v_mfma_f32_16x16x32_bf16 v[22:25], v[206:209], v[178:181], v[22:25]
	v_mfma_f32_16x16x32_bf16 v[18:21], v[214:217], v[178:181], v[18:21]
	v_mfma_f32_16x16x32_bf16 v[6:9], v[206:209], v[186:189], v[6:9]
	v_mfma_f32_16x16x32_bf16 v[2:5], v[214:217], v[186:189], v[2:5]
	v_mfma_f32_16x16x32_bf16 v[54:57], v[210:213], v[166:169], v[54:57]
	v_mfma_f32_16x16x32_bf16 v[50:53], v[218:221], v[166:169], v[50:53]
	v_mfma_f32_16x16x32_bf16 v[38:41], v[210:213], v[174:177], v[38:41]
	v_mfma_f32_16x16x32_bf16 v[34:37], v[218:221], v[174:177], v[34:37]
	v_mfma_f32_16x16x32_bf16 v[22:25], v[210:213], v[182:185], v[22:25]
	v_mfma_f32_16x16x32_bf16 v[18:21], v[218:221], v[182:185], v[18:21]
	v_mfma_f32_16x16x32_bf16 v[6:9], v[210:213], v[190:193], v[6:9]
	v_mfma_f32_16x16x32_bf16 v[2:5], v[218:221], v[190:193], v[2:5]
	s_barrier
	s_setprio 0
	ds_read_b128 v[142:145], v253 offset:32768
	ds_read_b128 v[150:153], v253 offset:33792
	ds_read_b128 v[154:157], v253 offset:34816
	ds_read_b128 v[158:161], v253 offset:35840
	s_add_u32 s6, s10, 0x20000
	s_addc_u32 s7, s11, 0
	s_mov_b32 m0, s57
	ds_read_b128 v[162:165], v146 offset:32768
	ds_read_b128 v[166:169], v146 offset:33792
	ds_read_b128 v[170:173], v146 offset:34816
	ds_read_b128 v[174:177], v146 offset:35840
	ds_read_b128 v[178:181], v146 offset:36864
	ds_read_b128 v[182:185], v146 offset:37888
	ds_read_b128 v[186:189], v146 offset:38912
	ds_read_b128 v[190:193], v146 offset:39936
	global_load_lds_dwordx4 v136, s[6:7]
	s_mov_b32 m0, s58
	s_nop 0
	global_load_lds_dwordx4 v132, s[6:7]
	s_waitcnt lgkmcnt(8)
	s_setprio 1
	s_barrier
	s_waitcnt lgkmcnt(0)
	v_mfma_f32_16x16x32_bf16 v[126:129], v[142:145], v[162:165], v[126:129]
	v_mfma_f32_16x16x32_bf16 v[122:125], v[154:157], v[162:165], v[122:125]
	v_mfma_f32_16x16x32_bf16 v[110:113], v[142:145], v[170:173], v[110:113]
	v_mfma_f32_16x16x32_bf16 v[106:109], v[154:157], v[170:173], v[106:109]
	v_mfma_f32_16x16x32_bf16 v[94:97], v[142:145], v[178:181], v[94:97]
	v_mfma_f32_16x16x32_bf16 v[90:93], v[154:157], v[178:181], v[90:93]
	v_mfma_f32_16x16x32_bf16 v[78:81], v[142:145], v[186:189], v[78:81]
	v_mfma_f32_16x16x32_bf16 v[74:77], v[154:157], v[186:189], v[74:77]
	v_mfma_f32_16x16x32_bf16 v[126:129], v[150:153], v[166:169], v[126:129]
	v_mfma_f32_16x16x32_bf16 v[122:125], v[158:161], v[166:169], v[122:125]
	v_mfma_f32_16x16x32_bf16 v[110:113], v[150:153], v[174:177], v[110:113]
	v_mfma_f32_16x16x32_bf16 v[106:109], v[158:161], v[174:177], v[106:109]
	v_mfma_f32_16x16x32_bf16 v[94:97], v[150:153], v[182:185], v[94:97]
	v_mfma_f32_16x16x32_bf16 v[90:93], v[158:161], v[182:185], v[90:93]
	v_mfma_f32_16x16x32_bf16 v[78:81], v[150:153], v[190:193], v[78:81]
	v_mfma_f32_16x16x32_bf16 v[74:77], v[158:161], v[190:193], v[74:77]
	s_barrier
	s_setprio 0
	s_mov_b32 m0, s59
	ds_read_b128 v[206:209], v253 offset:49152
	ds_read_b128 v[210:213], v253 offset:50176
	v_lshl_add_u64 v[222:223], v[222:223], 0, s[76:77]
	ds_read_b128 v[214:217], v253 offset:51200
	ds_read_b128 v[218:221], v253 offset:52224
	global_load_lds_dwordx4 v[222:223], off
	v_lshl_add_u64 v[222:223], v[224:225], 0, s[76:77]
	s_mov_b32 m0, s60
	s_nop 0
	global_load_lds_dwordx4 v[222:223], off
	s_setprio 1
	s_barrier
	s_waitcnt lgkmcnt(0)
	v_mfma_f32_16x16x32_bf16 v[118:121], v[206:209], v[162:165], v[118:121]
	v_mfma_f32_16x16x32_bf16 v[114:117], v[214:217], v[162:165], v[114:117]
	v_mfma_f32_16x16x32_bf16 v[102:105], v[206:209], v[170:173], v[102:105]
	v_mfma_f32_16x16x32_bf16 v[98:101], v[214:217], v[170:173], v[98:101]
	v_mfma_f32_16x16x32_bf16 v[86:89], v[206:209], v[178:181], v[86:89]
	v_mfma_f32_16x16x32_bf16 v[82:85], v[214:217], v[178:181], v[82:85]
	v_mfma_f32_16x16x32_bf16 v[70:73], v[206:209], v[186:189], v[70:73]
	v_mfma_f32_16x16x32_bf16 v[66:69], v[214:217], v[186:189], v[66:69]
	v_mfma_f32_16x16x32_bf16 v[118:121], v[210:213], v[166:169], v[118:121]
	v_mfma_f32_16x16x32_bf16 v[114:117], v[218:221], v[166:169], v[114:117]
	v_mfma_f32_16x16x32_bf16 v[102:105], v[210:213], v[174:177], v[102:105]
	v_mfma_f32_16x16x32_bf16 v[98:101], v[218:221], v[174:177], v[98:101]
	v_mfma_f32_16x16x32_bf16 v[86:89], v[210:213], v[182:185], v[86:89]
	v_mfma_f32_16x16x32_bf16 v[82:85], v[218:221], v[182:185], v[82:85]
	s_mov_b32 m0, s61
	v_mfma_f32_16x16x32_bf16 v[70:73], v[210:213], v[190:193], v[70:73]
	v_lshl_add_u64 v[222:223], v[226:227], 0, s[76:77]
	v_mfma_f32_16x16x32_bf16 v[66:69], v[218:221], v[190:193], v[66:69]
	s_barrier
	s_setprio 0
	ds_read_b128 v[162:165], v146 offset:49152
	ds_read_b128 v[166:169], v146 offset:50176
	ds_read_b128 v[170:173], v146 offset:51200
	ds_read_b128 v[174:177], v146 offset:52224
	ds_read_b128 v[178:181], v146 offset:53248
	ds_read_b128 v[182:185], v146 offset:54272
	ds_read_b128 v[186:189], v146 offset:55296
	ds_read_b128 v[190:193], v146 offset:56320
	global_load_lds_dwordx4 v[222:223], off
	v_lshl_add_u64 v[222:223], v[228:229], 0, s[76:77]
	s_mov_b32 m0, s62
	s_nop 0
	global_load_lds_dwordx4 v[222:223], off
	s_setprio 1
	s_barrier
	s_waitcnt lgkmcnt(0)
	v_mfma_f32_16x16x32_bf16 v[62:65], v[142:145], v[162:165], v[62:65]
	v_mfma_f32_16x16x32_bf16 v[58:61], v[154:157], v[162:165], v[58:61]
	v_mfma_f32_16x16x32_bf16 v[46:49], v[142:145], v[170:173], v[46:49]
	v_mfma_f32_16x16x32_bf16 v[42:45], v[154:157], v[170:173], v[42:45]
	v_mfma_f32_16x16x32_bf16 v[30:33], v[142:145], v[178:181], v[30:33]
	v_mfma_f32_16x16x32_bf16 v[26:29], v[154:157], v[178:181], v[26:29]
	v_mfma_f32_16x16x32_bf16 v[14:17], v[142:145], v[186:189], v[14:17]
	v_mfma_f32_16x16x32_bf16 v[10:13], v[154:157], v[186:189], v[10:13]
	v_mfma_f32_16x16x32_bf16 v[62:65], v[150:153], v[166:169], v[62:65]
	v_mfma_f32_16x16x32_bf16 v[58:61], v[158:161], v[166:169], v[58:61]
	v_mfma_f32_16x16x32_bf16 v[46:49], v[150:153], v[174:177], v[46:49]
	v_mfma_f32_16x16x32_bf16 v[42:45], v[158:161], v[174:177], v[42:45]
	v_mfma_f32_16x16x32_bf16 v[30:33], v[150:153], v[182:185], v[30:33]
	v_mfma_f32_16x16x32_bf16 v[26:29], v[158:161], v[182:185], v[26:29]
	v_mfma_f32_16x16x32_bf16 v[14:17], v[150:153], v[190:193], v[14:17]
	v_mfma_f32_16x16x32_bf16 v[10:13], v[158:161], v[190:193], v[10:13]
	s_barrier
	s_setprio 0
	s_add_u32 s6, s54, 0x20080
	s_addc_u32 s7, s55, 0
	s_mov_b32 m0, s63
	global_load_lds_dwordx4 v134, s[6:7]
	s_mov_b32 m0, s67
	s_nop 0
	global_load_lds_dwordx4 v130, s[6:7]
	s_waitcnt vmcnt(6)
	s_setprio 1
	s_barrier
	v_mfma_f32_16x16x32_bf16 v[54:57], v[206:209], v[162:165], v[54:57]
	v_mfma_f32_16x16x32_bf16 v[50:53], v[214:217], v[162:165], v[50:53]
	v_mfma_f32_16x16x32_bf16 v[38:41], v[206:209], v[170:173], v[38:41]
	v_mfma_f32_16x16x32_bf16 v[34:37], v[214:217], v[170:173], v[34:37]
	v_mfma_f32_16x16x32_bf16 v[22:25], v[206:209], v[178:181], v[22:25]
	v_mfma_f32_16x16x32_bf16 v[18:21], v[214:217], v[178:181], v[18:21]
	v_mfma_f32_16x16x32_bf16 v[6:9], v[206:209], v[186:189], v[6:9]
	v_mfma_f32_16x16x32_bf16 v[2:5], v[214:217], v[186:189], v[2:5]
	v_mfma_f32_16x16x32_bf16 v[54:57], v[210:213], v[166:169], v[54:57]
	v_mfma_f32_16x16x32_bf16 v[50:53], v[218:221], v[166:169], v[50:53]
	v_mfma_f32_16x16x32_bf16 v[38:41], v[210:213], v[174:177], v[38:41]
	v_mfma_f32_16x16x32_bf16 v[34:37], v[218:221], v[174:177], v[34:37]
	v_mfma_f32_16x16x32_bf16 v[22:25], v[210:213], v[182:185], v[22:25]
	v_mfma_f32_16x16x32_bf16 v[18:21], v[218:221], v[182:185], v[18:21]
	v_mfma_f32_16x16x32_bf16 v[6:9], v[210:213], v[190:193], v[6:9]
	v_mfma_f32_16x16x32_bf16 v[2:5], v[218:221], v[190:193], v[2:5]
	s_setprio 0
	s_add_i32 s79, s79, 2
	s_cmp_gt_u32 s79, 5
	s_mov_b64 s[6:7], s[8:9]
	s_barrier
	s_cbranch_scc0 .LBB0_266
	s_lshl_b32 s5, s28, 6
	s_and_b32 s5, s5, 0xffffff00
	v_add_u32_e32 v144, s5, v148
	s_lshl_b32 s5, s28, 8
	s_and_b32 s5, s5, 0x300
	v_or_b32_e32 v145, s5, v149
	v_mov_b64_e32 v[142:143], s[50:51]
	v_mad_i64_i32 v[150:151], s[6:7], v144, s37, v[142:143]
	v_lshlrev_b32_e32 v194, 1, v145
	v_lshl_add_u64 v[154:155], v[150:151], 0, v[194:195]
	v_add_co_u32_e32 v150, vcc, 0x1000, v154
	v_or_b32_e32 v184, 16, v144
	s_nop 0
	v_addc_co_u32_e32 v151, vcc, 0, v155, vcc
	global_load_dwordx4 v[150:153], v[150:151], off offset:2048
	v_lshl_add_u64 v[154:155], v[154:155], 0, s[84:85]
	global_load_dwordx4 v[154:157], v[154:155], off offset:256
	v_pk_mul_f32 v[182:183], v[114:115], s[36:37] op_sel_hi:[1,0]
	v_mad_i64_i32 v[114:115], s[6:7], v184, s37, v[142:143]
	v_lshl_add_u64 v[114:115], v[114:115], 0, v[194:195]
	v_pk_mul_f32 v[180:181], v[116:117], s[36:37] op_sel_hi:[1,0]
	v_add_co_u32_e32 v116, vcc, 0x1000, v114
	v_pk_mul_f32 v[170:171], v[126:127], s[36:37] op_sel_hi:[1,0]
	s_nop 0
	v_addc_co_u32_e32 v117, vcc, 0, v115, vcc
	v_pk_mul_f32 v[172:173], v[124:125], s[36:37] op_sel_hi:[1,0]
	global_load_dwordx4 v[124:127], v[116:117], off offset:2048
	v_lshl_add_u64 v[114:115], v[114:115], 0, s[84:85]
	global_load_dwordx4 v[158:161], v[114:115], off offset:256
	v_or_b32_e32 v186, 32, v144
	v_mad_i64_i32 v[116:117], s[6:7], v186, s37, v[142:143]
	v_lshl_add_u64 v[116:117], v[116:117], 0, v[194:195]
	v_lshl_add_u64 v[166:167], v[116:117], 0, s[84:85]
	v_add_co_u32_e32 v116, vcc, 0x1000, v116
	v_pk_mul_f32 v[174:175], v[122:123], s[36:37] op_sel_hi:[1,0]
	s_nop 0
	v_addc_co_u32_e32 v117, vcc, 0, v117, vcc
	global_load_dwordx4 v[162:165], v[116:117], off offset:2048
	s_nop 0
	global_load_dwordx4 v[166:169], v[166:167], off offset:256
	v_or_b32_e32 v122, 48, v144
	v_pk_mul_f32 v[178:179], v[118:119], s[36:37] op_sel_hi:[1,0]
	v_mad_i64_i32 v[118:119], s[6:7], v122, s37, v[142:143]
	v_ashrrev_i32_e32 v145, 31, v144
	v_lshl_add_u64 v[118:119], v[118:119], 0, v[194:195]
	v_pk_mul_f32 v[176:177], v[120:121], s[36:37] op_sel_hi:[1,0]
	v_lshlrev_b64 v[120:121], 11, v[144:145]
	v_add_co_u32_e32 v114, vcc, 0x1000, v118
	v_lshl_add_u64 v[120:121], s[74:75], 0, v[120:121]
	s_nop 0
	v_addc_co_u32_e32 v115, vcc, 0, v119, vcc
	v_lshl_add_u64 v[188:189], v[118:119], 0, s[84:85]
	v_lshl_add_u64 v[190:191], v[120:121], 0, v[194:195]
	global_load_dwordx4 v[118:121], v[114:115], off offset:2048
	s_nop 0
	global_load_dwordx4 v[114:117], v[188:189], off offset:256
	v_pk_mul_f32 v[128:129], v[128:129], s[36:37] op_sel_hi:[1,0]
	v_pk_mul_f32 v[110:111], v[110:111], s[36:37] op_sel_hi:[1,0]
	v_pk_mul_f32 v[112:113], v[112:113], s[36:37] op_sel_hi:[1,0]
	v_ashrrev_i32_e32 v185, 31, v184
	v_pk_mul_f32 v[102:103], v[102:103], s[36:37] op_sel_hi:[1,0]
	v_pk_mul_f32 v[104:105], v[104:105], s[36:37] op_sel_hi:[1,0]
	v_pk_mul_f32 v[94:95], v[94:95], s[36:37] op_sel_hi:[1,0]
	v_pk_mul_f32 v[96:97], v[96:97], s[36:37] op_sel_hi:[1,0]
	v_ashrrev_i32_e32 v187, 31, v186
	v_pk_mul_f32 v[86:87], v[86:87], s[36:37] op_sel_hi:[1,0]
	v_pk_mul_f32 v[88:89], v[88:89], s[36:37] op_sel_hi:[1,0]
	v_pk_mul_f32 v[78:79], v[78:79], s[36:37] op_sel_hi:[1,0]
	v_pk_mul_f32 v[80:81], v[80:81], s[36:37] op_sel_hi:[1,0]
	v_ashrrev_i32_e32 v123, 31, v122
	v_pk_mul_f32 v[70:71], v[70:71], s[36:37] op_sel_hi:[1,0]
	v_pk_mul_f32 v[72:73], v[72:73], s[36:37] op_sel_hi:[1,0]
	s_waitcnt vmcnt(0)
	v_lshlrev_b32_e32 v145, 16, v150
	v_and_b32_e32 v150, 0xffff0000, v150
	v_lshlrev_b32_e32 v188, 16, v151
	v_and_b32_e32 v151, 0xffff0000, v151
	v_mul_f32_e32 v150, v171, v150
	v_mul_f32_e32 v128, v128, v188
	v_mul_f32_e32 v129, v129, v151
	v_lshlrev_b32_e32 v189, 16, v152
	v_and_b32_e32 v152, 0xffff0000, v152
	v_lshlrev_b32_e32 v192, 16, v153
	v_and_b32_e32 v153, 0xffff0000, v153
	v_mul_f32_e32 v145, v170, v145
	v_cvt_pk_bf16_f32 v150, v145, v150
	v_cvt_pk_bf16_f32 v151, v128, v129
	v_lshlrev_b32_e32 v128, 16, v154
	v_and_b32_e32 v129, 0xffff0000, v154
	v_mul_f32_e32 v152, v175, v152
	v_mul_f32_e32 v153, v173, v153
	v_mul_f32_e32 v128, v178, v128
	v_mul_f32_e32 v129, v179, v129
	v_mul_f32_e32 v170, v174, v189
	v_mul_f32_e32 v171, v172, v192
	v_cvt_pk_bf16_f32 v152, v170, v152
	v_cvt_pk_bf16_f32 v153, v171, v153
	global_store_dwordx4 v[190:191], v[150:153], off
	s_nop 1
	v_cvt_pk_bf16_f32 v150, v128, v129
	v_lshlrev_b32_e32 v128, 16, v155
	v_and_b32_e32 v129, 0xffff0000, v155
	v_mul_f32_e32 v128, v176, v128
	v_mul_f32_e32 v129, v177, v129
	v_cvt_pk_bf16_f32 v151, v128, v129
	v_lshlrev_b32_e32 v128, 16, v156
	v_and_b32_e32 v129, 0xffff0000, v156
	v_mul_f32_e32 v128, v182, v128
	v_mul_f32_e32 v129, v183, v129
	v_cvt_pk_bf16_f32 v152, v128, v129
	v_lshlrev_b32_e32 v128, 16, v157
	v_and_b32_e32 v129, 0xffff0000, v157
	v_mul_f32_e32 v128, v180, v128
	v_mul_f32_e32 v129, v181, v129
	v_cvt_pk_bf16_f32 v153, v128, v129
	global_store_dwordx4 v[190:191], v[150:153], off offset:256
	v_lshlrev_b64 v[128:129], 11, v[184:185]
	s_nop 0
	v_pk_mul_f32 v[150:151], v[108:109], s[36:37] op_sel_hi:[1,0]
	v_pk_mul_f32 v[108:109], v[106:107], s[36:37] op_sel_hi:[1,0]
	v_lshlrev_b32_e32 v106, 16, v124
	v_and_b32_e32 v107, 0xffff0000, v124
	v_mul_f32_e32 v106, v110, v106
	v_mul_f32_e32 v107, v111, v107
	v_cvt_pk_bf16_f32 v106, v106, v107
	v_lshlrev_b32_e32 v107, 16, v125
	v_and_b32_e32 v110, 0xffff0000, v125
	v_mul_f32_e32 v107, v112, v107
	v_mul_f32_e32 v110, v113, v110
	v_cvt_pk_bf16_f32 v107, v107, v110
	v_lshlrev_b32_e32 v110, 16, v126
	v_mul_f32_e32 v108, v108, v110
	v_and_b32_e32 v110, 0xffff0000, v126
	v_mul_f32_e32 v109, v109, v110
	v_cvt_pk_bf16_f32 v108, v108, v109
	v_lshlrev_b32_e32 v109, 16, v127
	v_and_b32_e32 v110, 0xffff0000, v127
	v_mul_f32_e32 v109, v150, v109
	v_mul_f32_e32 v110, v151, v110
	v_cvt_pk_bf16_f32 v109, v109, v110
	v_lshl_add_u64 v[110:111], s[74:75], 0, v[128:129]
	v_lshl_add_u64 v[110:111], v[110:111], 0, v[194:195]
	global_store_dwordx4 v[110:111], v[106:109], off
	s_nop 1
	v_pk_mul_f32 v[106:107], v[100:101], s[36:37] op_sel_hi:[1,0]
	v_pk_mul_f32 v[100:101], v[98:99], s[36:37] op_sel_hi:[1,0]
	v_lshlrev_b32_e32 v98, 16, v158
	v_and_b32_e32 v99, 0xffff0000, v158
	v_mul_f32_e32 v98, v102, v98
	v_mul_f32_e32 v99, v103, v99
	v_cvt_pk_bf16_f32 v98, v98, v99
	v_lshlrev_b32_e32 v99, 16, v159
	v_and_b32_e32 v102, 0xffff0000, v159
	v_mul_f32_e32 v99, v104, v99
	v_mul_f32_e32 v102, v105, v102
	v_cvt_pk_bf16_f32 v99, v99, v102
	v_lshlrev_b32_e32 v102, 16, v160
	v_mul_f32_e32 v100, v100, v102
	v_and_b32_e32 v102, 0xffff0000, v160
	v_mul_f32_e32 v101, v101, v102
	v_cvt_pk_bf16_f32 v100, v100, v101
	v_lshlrev_b32_e32 v101, 16, v161
	v_mul_f32_e32 v101, v106, v101
	v_and_b32_e32 v102, 0xffff0000, v161
	v_mul_f32_e32 v102, v107, v102
	v_cvt_pk_bf16_f32 v101, v101, v102
	global_store_dwordx4 v[110:111], v[98:101], off offset:256
	s_nop 1
	v_pk_mul_f32 v[100:101], v[92:93], s[36:37] op_sel_hi:[1,0]
	v_pk_mul_f32 v[92:93], v[90:91], s[36:37] op_sel_hi:[1,0]
	v_lshlrev_b32_e32 v90, 16, v162
	v_and_b32_e32 v91, 0xffff0000, v162
	v_mul_f32_e32 v90, v94, v90
	v_mul_f32_e32 v91, v95, v91
	v_cvt_pk_bf16_f32 v90, v90, v91
	v_lshlrev_b32_e32 v91, 16, v163
	v_and_b32_e32 v94, 0xffff0000, v163
	v_mul_f32_e32 v91, v96, v91
	v_mul_f32_e32 v94, v97, v94
	v_cvt_pk_bf16_f32 v91, v91, v94
	v_lshlrev_b32_e32 v94, 16, v164
	v_mul_f32_e32 v92, v92, v94
	v_and_b32_e32 v94, 0xffff0000, v164
	v_mul_f32_e32 v93, v93, v94
	v_cvt_pk_bf16_f32 v92, v92, v93
	v_lshlrev_b32_e32 v93, 16, v165
	v_and_b32_e32 v94, 0xffff0000, v165
	v_lshlrev_b64 v[98:99], 11, v[186:187]
	v_mul_f32_e32 v93, v100, v93
	v_mul_f32_e32 v94, v101, v94
	v_cvt_pk_bf16_f32 v93, v93, v94
	v_lshl_add_u64 v[94:95], s[74:75], 0, v[98:99]
	v_lshl_add_u64 v[94:95], v[94:95], 0, v[194:195]
	global_store_dwordx4 v[94:95], v[90:93], off
	s_nop 1
	v_pk_mul_f32 v[90:91], v[84:85], s[36:37] op_sel_hi:[1,0]
	v_pk_mul_f32 v[84:85], v[82:83], s[36:37] op_sel_hi:[1,0]
	v_lshlrev_b32_e32 v82, 16, v166
	v_and_b32_e32 v83, 0xffff0000, v166
	v_mul_f32_e32 v82, v86, v82
	v_mul_f32_e32 v83, v87, v83
	v_cvt_pk_bf16_f32 v82, v82, v83
	v_lshlrev_b32_e32 v83, 16, v167
	v_and_b32_e32 v86, 0xffff0000, v167
	v_mul_f32_e32 v83, v88, v83
	v_mul_f32_e32 v86, v89, v86
	v_cvt_pk_bf16_f32 v83, v83, v86
	v_lshlrev_b32_e32 v86, 16, v168
	v_mul_f32_e32 v84, v84, v86
	v_and_b32_e32 v86, 0xffff0000, v168
	v_mul_f32_e32 v85, v85, v86
	v_cvt_pk_bf16_f32 v84, v84, v85
	v_lshlrev_b32_e32 v85, 16, v169
	v_mul_f32_e32 v85, v90, v85
	v_and_b32_e32 v86, 0xffff0000, v169
	v_mul_f32_e32 v86, v91, v86
	v_cvt_pk_bf16_f32 v85, v85, v86
	global_store_dwordx4 v[94:95], v[82:85], off offset:256
	s_nop 1
	v_pk_mul_f32 v[84:85], v[76:77], s[36:37] op_sel_hi:[1,0]
	v_pk_mul_f32 v[76:77], v[74:75], s[36:37] op_sel_hi:[1,0]
	v_lshlrev_b32_e32 v74, 16, v118
	v_and_b32_e32 v75, 0xffff0000, v118
	v_mul_f32_e32 v74, v78, v74
	v_mul_f32_e32 v75, v79, v75
	v_cvt_pk_bf16_f32 v74, v74, v75
	v_lshlrev_b32_e32 v75, 16, v119
	v_and_b32_e32 v78, 0xffff0000, v119
	v_mul_f32_e32 v75, v80, v75
	v_mul_f32_e32 v78, v81, v78
	v_cvt_pk_bf16_f32 v75, v75, v78
	v_lshlrev_b32_e32 v78, 16, v120
	v_mul_f32_e32 v76, v76, v78
	v_and_b32_e32 v78, 0xffff0000, v120
	v_mul_f32_e32 v77, v77, v78
	v_cvt_pk_bf16_f32 v76, v76, v77
	v_lshlrev_b32_e32 v77, 16, v121
	v_and_b32_e32 v78, 0xffff0000, v121
	v_lshlrev_b64 v[82:83], 11, v[122:123]
	v_mul_f32_e32 v77, v84, v77
	v_mul_f32_e32 v78, v85, v78
	v_cvt_pk_bf16_f32 v77, v77, v78
	v_lshl_add_u64 v[78:79], s[74:75], 0, v[82:83]
	v_lshl_add_u64 v[78:79], v[78:79], 0, v[194:195]
	global_store_dwordx4 v[78:79], v[74:77], off
	s_nop 1
	v_pk_mul_f32 v[74:75], v[68:69], s[36:37] op_sel_hi:[1,0]
	v_pk_mul_f32 v[68:69], v[66:67], s[36:37] op_sel_hi:[1,0]
	v_lshlrev_b32_e32 v66, 16, v114
	v_and_b32_e32 v67, 0xffff0000, v114
	v_mul_f32_e32 v66, v70, v66
	v_mul_f32_e32 v67, v71, v67
	v_cvt_pk_bf16_f32 v66, v66, v67
	v_lshlrev_b32_e32 v67, 16, v115
	v_and_b32_e32 v70, 0xffff0000, v115
	v_mul_f32_e32 v67, v72, v67
	v_mul_f32_e32 v70, v73, v70
	v_cvt_pk_bf16_f32 v67, v67, v70
	v_lshlrev_b32_e32 v70, 16, v116
	v_mul_f32_e32 v68, v68, v70
	v_and_b32_e32 v70, 0xffff0000, v116
	v_mul_f32_e32 v69, v69, v70
	v_cvt_pk_bf16_f32 v68, v68, v69
	v_lshlrev_b32_e32 v69, 16, v117
	v_mul_f32_e32 v69, v74, v69
	v_and_b32_e32 v70, 0xffff0000, v117
	v_mul_f32_e32 v70, v75, v70
	v_cvt_pk_bf16_f32 v69, v69, v70
	global_store_dwordx4 v[78:79], v[66:69], off offset:256
	v_add_u32_e32 v78, 0x80, v144
	s_nop 0
	v_mad_i64_i32 v[66:67], s[6:7], v78, s37, v[142:143]
	v_lshl_add_u64 v[66:67], v[66:67], 0, v[194:195]
	v_add_co_u32_e32 v68, vcc, s16, v66
	v_add_u32_e32 v86, 0x90, v144
	s_nop 0
	v_addc_co_u32_e32 v69, vcc, 0, v67, vcc
	global_load_dwordx4 v[70:73], v[68:69], off offset:2048
	v_lshl_add_u64 v[66:67], v[66:67], 0, s[84:85]
	global_load_dwordx4 v[74:77], v[66:67], off offset:256
	v_pk_mul_f32 v[96:97], v[56:57], s[36:37] op_sel_hi:[1,0]
	v_mad_i64_i32 v[56:57], s[6:7], v86, s37, v[142:143]
	v_lshl_add_u64 v[56:57], v[56:57], 0, v[194:195]
	v_pk_mul_f32 v[94:95], v[58:59], s[36:37] op_sel_hi:[1,0]
	v_add_co_u32_e32 v58, vcc, s16, v56
	v_pk_mul_f32 v[92:93], v[60:61], s[36:37] op_sel_hi:[1,0]
	s_nop 0
	v_addc_co_u32_e32 v59, vcc, 0, v57, vcc
	global_load_dwordx4 v[58:61], v[58:59], off offset:2048
	v_add_u32_e32 v68, 0xa0, v144
	v_pk_mul_f32 v[102:103], v[50:51], s[36:37] op_sel_hi:[1,0]
	v_mad_i64_i32 v[50:51], s[6:7], v68, s37, v[142:143]
	v_add_u32_e32 v66, 0xb0, v144
	v_lshl_add_u64 v[50:51], v[50:51], 0, v[194:195]
	v_pk_mul_f32 v[100:101], v[52:53], s[36:37] op_sel_hi:[1,0]
	v_mad_i64_i32 v[52:53], s[6:7], v66, s37, v[142:143]
	v_lshl_add_u64 v[82:83], v[50:51], 0, s[84:85]
	v_add_co_u32_e32 v50, vcc, s16, v50
	v_lshl_add_u64 v[52:53], v[52:53], 0, v[194:195]
	s_nop 0
	v_addc_co_u32_e32 v51, vcc, 0, v51, vcc
	v_ashrrev_i32_e32 v79, 31, v78
	v_lshl_add_u64 v[104:105], v[52:53], 0, s[84:85]
	v_add_co_u32_e32 v52, vcc, s16, v52
	v_pk_mul_f32 v[98:99], v[54:55], s[36:37] op_sel_hi:[1,0]
	v_lshlrev_b64 v[54:55], 11, v[78:79]
	v_lshl_add_u64 v[56:57], v[56:57], 0, s[84:85]
	v_addc_co_u32_e32 v53, vcc, 0, v53, vcc
	v_pk_mul_f32 v[88:89], v[64:65], s[36:37] op_sel_hi:[1,0]
	v_pk_mul_f32 v[90:91], v[62:63], s[36:37] op_sel_hi:[1,0]
	v_lshl_add_u64 v[106:107], s[74:75], 0, v[54:55]
	global_load_dwordx4 v[62:65], v[56:57], off offset:256
	global_load_dwordx4 v[78:81], v[50:51], off offset:2048
	s_nop 0
	global_load_dwordx4 v[82:85], v[82:83], off offset:256
	s_nop 0
	global_load_dwordx4 v[54:57], v[52:53], off offset:2048
	s_nop 0
	global_load_dwordx4 v[50:53], v[104:105], off offset:256
	v_lshl_add_u64 v[104:105], v[106:107], 0, v[194:195]
	v_pk_mul_f32 v[46:47], v[46:47], s[36:37] op_sel_hi:[1,0]
	v_pk_mul_f32 v[48:49], v[48:49], s[36:37] op_sel_hi:[1,0]
	v_ashrrev_i32_e32 v87, 31, v86
	v_pk_mul_f32 v[38:39], v[38:39], s[36:37] op_sel_hi:[1,0]
	v_pk_mul_f32 v[40:41], v[40:41], s[36:37] op_sel_hi:[1,0]
	v_pk_mul_f32 v[30:31], v[30:31], s[36:37] op_sel_hi:[1,0]
	v_pk_mul_f32 v[32:33], v[32:33], s[36:37] op_sel_hi:[1,0]
	v_ashrrev_i32_e32 v69, 31, v68
	v_pk_mul_f32 v[22:23], v[22:23], s[36:37] op_sel_hi:[1,0]
	v_pk_mul_f32 v[24:25], v[24:25], s[36:37] op_sel_hi:[1,0]
	v_pk_mul_f32 v[14:15], v[14:15], s[36:37] op_sel_hi:[1,0]
	v_pk_mul_f32 v[16:17], v[16:17], s[36:37] op_sel_hi:[1,0]
	v_ashrrev_i32_e32 v67, 31, v66
	v_pk_mul_f32 v[6:7], v[6:7], s[36:37] op_sel_hi:[1,0]
	v_pk_mul_f32 v[8:9], v[8:9], s[36:37] op_sel_hi:[1,0]
	s_waitcnt vmcnt(0)
	v_lshlrev_b32_e32 v106, 16, v70
	v_and_b32_e32 v70, 0xffff0000, v70
	v_lshlrev_b32_e32 v107, 16, v71
	v_and_b32_e32 v71, 0xffff0000, v71
	v_lshlrev_b32_e32 v108, 16, v72
	v_and_b32_e32 v72, 0xffff0000, v72
	v_lshlrev_b32_e32 v109, 16, v73
	v_and_b32_e32 v73, 0xffff0000, v73
	v_mul_f32_e32 v70, v91, v70
	v_mul_f32_e32 v71, v89, v71
	v_mul_f32_e32 v72, v95, v72
	v_mul_f32_e32 v73, v93, v73
	v_mul_f32_e32 v90, v90, v106
	v_mul_f32_e32 v88, v88, v107
	v_mul_f32_e32 v89, v94, v108
	v_mul_f32_e32 v91, v92, v109
	v_cvt_pk_bf16_f32 v70, v90, v70
	v_cvt_pk_bf16_f32 v71, v88, v71
	v_cvt_pk_bf16_f32 v72, v89, v72
	v_cvt_pk_bf16_f32 v73, v91, v73
	v_lshlrev_b32_e32 v111, 16, v75
	v_and_b32_e32 v75, 0xffff0000, v75
	global_store_dwordx4 v[104:105], v[70:73], off
	v_lshlrev_b32_e32 v110, 16, v74
	v_and_b32_e32 v74, 0xffff0000, v74
	v_lshlrev_b32_e32 v72, 16, v76
	v_and_b32_e32 v73, 0xffff0000, v76
	v_mul_f32_e32 v71, v97, v75
	v_mul_f32_e32 v72, v102, v72
	v_mul_f32_e32 v73, v103, v73
	v_mul_f32_e32 v92, v98, v110
	v_mul_f32_e32 v74, v99, v74
	v_mul_f32_e32 v93, v96, v111
	v_cvt_pk_bf16_f32 v70, v92, v74
	v_cvt_pk_bf16_f32 v71, v93, v71
	v_cvt_pk_bf16_f32 v72, v72, v73
	v_lshlrev_b32_e32 v73, 16, v77
	v_mul_f32_e32 v73, v100, v73
	v_and_b32_e32 v74, 0xffff0000, v77
	v_mul_f32_e32 v74, v101, v74
	v_cvt_pk_bf16_f32 v73, v73, v74
	global_store_dwordx4 v[104:105], v[70:73], off offset:256
	s_nop 1
	v_pk_mul_f32 v[72:73], v[44:45], s[36:37] op_sel_hi:[1,0]
	v_pk_mul_f32 v[44:45], v[42:43], s[36:37] op_sel_hi:[1,0]
	v_lshlrev_b32_e32 v42, 16, v58
	v_and_b32_e32 v43, 0xffff0000, v58
	v_mul_f32_e32 v42, v46, v42
	v_mul_f32_e32 v43, v47, v43
	v_cvt_pk_bf16_f32 v42, v42, v43
	v_lshlrev_b32_e32 v43, 16, v59
	v_and_b32_e32 v46, 0xffff0000, v59
	v_mul_f32_e32 v43, v48, v43
	v_mul_f32_e32 v46, v49, v46
	v_cvt_pk_bf16_f32 v43, v43, v46
	v_lshlrev_b32_e32 v46, 16, v60
	v_mul_f32_e32 v44, v44, v46
	v_and_b32_e32 v46, 0xffff0000, v60
	v_mul_f32_e32 v45, v45, v46
	v_cvt_pk_bf16_f32 v44, v44, v45
	v_lshlrev_b32_e32 v45, 16, v61
	v_and_b32_e32 v46, 0xffff0000, v61
	v_lshlrev_b64 v[70:71], 11, v[86:87]
	v_mul_f32_e32 v45, v72, v45
	v_mul_f32_e32 v46, v73, v46
	v_cvt_pk_bf16_f32 v45, v45, v46
	v_lshl_add_u64 v[46:47], s[74:75], 0, v[70:71]
	v_lshl_add_u64 v[46:47], v[46:47], 0, v[194:195]
	global_store_dwordx4 v[46:47], v[42:45], off
	s_nop 1
	v_pk_mul_f32 v[42:43], v[36:37], s[36:37] op_sel_hi:[1,0]
	v_pk_mul_f32 v[36:37], v[34:35], s[36:37] op_sel_hi:[1,0]
	v_lshlrev_b32_e32 v34, 16, v62
	v_and_b32_e32 v35, 0xffff0000, v62
	v_mul_f32_e32 v34, v38, v34
	v_mul_f32_e32 v35, v39, v35
	v_cvt_pk_bf16_f32 v34, v34, v35
	v_lshlrev_b32_e32 v35, 16, v63
	v_and_b32_e32 v38, 0xffff0000, v63
	v_mul_f32_e32 v35, v40, v35
	v_mul_f32_e32 v38, v41, v38
	v_cvt_pk_bf16_f32 v35, v35, v38
	v_lshlrev_b32_e32 v38, 16, v64
	v_mul_f32_e32 v36, v36, v38
	v_and_b32_e32 v38, 0xffff0000, v64
	v_mul_f32_e32 v37, v37, v38
	v_cvt_pk_bf16_f32 v36, v36, v37
	v_lshlrev_b32_e32 v37, 16, v65
	v_mul_f32_e32 v37, v42, v37
	v_and_b32_e32 v38, 0xffff0000, v65
	v_mul_f32_e32 v38, v43, v38
	v_cvt_pk_bf16_f32 v37, v37, v38
	global_store_dwordx4 v[46:47], v[34:37], off offset:256
	s_nop 1
	v_pk_mul_f32 v[36:37], v[28:29], s[36:37] op_sel_hi:[1,0]
	v_pk_mul_f32 v[28:29], v[26:27], s[36:37] op_sel_hi:[1,0]
	v_lshlrev_b32_e32 v26, 16, v78
	v_and_b32_e32 v27, 0xffff0000, v78
	v_mul_f32_e32 v26, v30, v26
	v_mul_f32_e32 v27, v31, v27
	v_cvt_pk_bf16_f32 v26, v26, v27
	v_lshlrev_b32_e32 v27, 16, v79
	v_and_b32_e32 v30, 0xffff0000, v79
	v_mul_f32_e32 v27, v32, v27
	v_mul_f32_e32 v30, v33, v30
	v_cvt_pk_bf16_f32 v27, v27, v30
	v_lshlrev_b32_e32 v30, 16, v80
	v_mul_f32_e32 v28, v28, v30
	v_and_b32_e32 v30, 0xffff0000, v80
	v_mul_f32_e32 v29, v29, v30
	v_cvt_pk_bf16_f32 v28, v28, v29
	v_lshlrev_b32_e32 v29, 16, v81
	v_and_b32_e32 v30, 0xffff0000, v81
	v_lshlrev_b64 v[34:35], 11, v[68:69]
	v_mul_f32_e32 v29, v36, v29
	v_mul_f32_e32 v30, v37, v30
	v_cvt_pk_bf16_f32 v29, v29, v30
	v_lshl_add_u64 v[30:31], s[74:75], 0, v[34:35]
	v_lshl_add_u64 v[30:31], v[30:31], 0, v[194:195]
	global_store_dwordx4 v[30:31], v[26:29], off
	s_nop 1
	v_pk_mul_f32 v[26:27], v[20:21], s[36:37] op_sel_hi:[1,0]
	v_pk_mul_f32 v[20:21], v[18:19], s[36:37] op_sel_hi:[1,0]
	v_lshlrev_b32_e32 v18, 16, v82
	v_and_b32_e32 v19, 0xffff0000, v82
	v_mul_f32_e32 v18, v22, v18
	v_mul_f32_e32 v19, v23, v19
	v_cvt_pk_bf16_f32 v18, v18, v19
	v_lshlrev_b32_e32 v19, 16, v83
	v_and_b32_e32 v22, 0xffff0000, v83
	v_mul_f32_e32 v19, v24, v19
	v_mul_f32_e32 v22, v25, v22
	v_cvt_pk_bf16_f32 v19, v19, v22
	v_lshlrev_b32_e32 v22, 16, v84
	v_mul_f32_e32 v20, v20, v22
	v_and_b32_e32 v22, 0xffff0000, v84
	v_mul_f32_e32 v21, v21, v22
	v_cvt_pk_bf16_f32 v20, v20, v21
	v_lshlrev_b32_e32 v21, 16, v85
	v_mul_f32_e32 v21, v26, v21
	v_and_b32_e32 v22, 0xffff0000, v85
	v_mul_f32_e32 v22, v27, v22
	v_cvt_pk_bf16_f32 v21, v21, v22
	global_store_dwordx4 v[30:31], v[18:21], off offset:256
	s_nop 1
	v_pk_mul_f32 v[20:21], v[12:13], s[36:37] op_sel_hi:[1,0]
	v_pk_mul_f32 v[12:13], v[10:11], s[36:37] op_sel_hi:[1,0]
	v_lshlrev_b32_e32 v10, 16, v54
	v_and_b32_e32 v11, 0xffff0000, v54
	v_mul_f32_e32 v10, v14, v10
	v_mul_f32_e32 v11, v15, v11
	v_cvt_pk_bf16_f32 v10, v10, v11
	v_lshlrev_b32_e32 v11, 16, v55
	v_and_b32_e32 v14, 0xffff0000, v55
	v_mul_f32_e32 v11, v16, v11
	v_mul_f32_e32 v14, v17, v14
	v_cvt_pk_bf16_f32 v11, v11, v14
	v_lshlrev_b32_e32 v14, 16, v56
	v_mul_f32_e32 v12, v12, v14
	v_and_b32_e32 v14, 0xffff0000, v56
	v_mul_f32_e32 v13, v13, v14
	v_cvt_pk_bf16_f32 v12, v12, v13
	v_lshlrev_b32_e32 v13, 16, v57
	v_and_b32_e32 v14, 0xffff0000, v57
	v_lshlrev_b64 v[18:19], 11, v[66:67]
	v_mul_f32_e32 v13, v20, v13
	v_mul_f32_e32 v14, v21, v14
	v_cvt_pk_bf16_f32 v13, v13, v14
	v_lshl_add_u64 v[14:15], s[74:75], 0, v[18:19]
	v_lshl_add_u64 v[14:15], v[14:15], 0, v[194:195]
	global_store_dwordx4 v[14:15], v[10:13], off
	s_nop 1
	v_pk_mul_f32 v[10:11], v[4:5], s[36:37] op_sel_hi:[1,0]
	v_pk_mul_f32 v[4:5], v[2:3], s[36:37] op_sel_hi:[1,0]
	v_lshlrev_b32_e32 v2, 16, v50
	v_and_b32_e32 v3, 0xffff0000, v50
	v_mul_f32_e32 v2, v6, v2
	v_mul_f32_e32 v3, v7, v3
	v_cvt_pk_bf16_f32 v2, v2, v3
	v_lshlrev_b32_e32 v3, 16, v51
	v_and_b32_e32 v6, 0xffff0000, v51
	v_mul_f32_e32 v3, v8, v3
	v_mul_f32_e32 v6, v9, v6
	v_cvt_pk_bf16_f32 v3, v3, v6
	v_lshlrev_b32_e32 v6, 16, v52
	v_mul_f32_e32 v4, v4, v6
	v_and_b32_e32 v6, 0xffff0000, v52
	v_mul_f32_e32 v5, v5, v6
	v_cvt_pk_bf16_f32 v4, v4, v5
	v_lshlrev_b32_e32 v5, 16, v53
	v_mul_f32_e32 v5, v10, v5
	v_and_b32_e32 v6, 0xffff0000, v53
	v_mul_f32_e32 v6, v11, v6
	v_cvt_pk_bf16_f32 v5, v5, v6
	global_store_dwordx4 v[14:15], v[2:5], off offset:256
	s_and_b64 vcc, exec, s[52:53]
	s_mov_b32 s28, s4
	s_cbranch_vccz .LBB0_265
	s_waitcnt vmcnt(0)
	v_readlane_b32 s28, v250, 12
	s_cmpk_gt_u32 s12, 0xff
	v_readlane_b32 s29, v250, 13
	s_mov_b32 s70, 0x800000
	s_cbranch_scc1 .LBB0_270
	s_barrier

.LBB0_368:
	v_add_u32_e32 v253, 0x10000, v201
	ds_read_b128 v[130:133], v253
	ds_read_b128 v[134:137], v253 offset:1024
	ds_read_b128 v[138:141], v253 offset:2048
	ds_read_b128 v[142:145], v253 offset:3072
	s_add_u32 s10, s8, 0xfffc0080
	s_addc_u32 s11, s9, -1
	s_cmp_eq_u32 s29, 12
	s_cselect_b32 s11, s81, s11
	s_cselect_b32 s10, s80, s10
	s_cselect_b32 s53, s83, s28
	s_cselect_b32 s52, s82, s7
	s_add_i32 m0, s34, 0xc000
	ds_read_b128 v[146:149], v199
	ds_read_b128 v[150:153], v199 offset:1024
	ds_read_b128 v[154:157], v199 offset:2048
	ds_read_b128 v[158:161], v199 offset:3072
	ds_read_b128 v[162:165], v199 offset:4096
	ds_read_b128 v[166:169], v199 offset:5120
	ds_read_b128 v[170:173], v199 offset:6144
	ds_read_b128 v[174:177], v199 offset:7168
	global_load_lds_dwordx4 v212, s[8:9]
	s_add_i32 m0, s34, 0xe000
	s_nop 0
	global_load_lds_dwordx4 v214, s[8:9]
	s_waitcnt lgkmcnt(8)
	s_setprio 1
	s_barrier
	s_waitcnt lgkmcnt(0)
	v_mfma_f32_16x16x32_bf16 v[126:129], v[130:133], v[146:149], v[126:129]
	v_mfma_f32_16x16x32_bf16 v[122:125], v[138:141], v[146:149], v[122:125]
	v_mfma_f32_16x16x32_bf16 v[118:121], v[130:133], v[154:157], v[118:121]
	v_mfma_f32_16x16x32_bf16 v[114:117], v[138:141], v[154:157], v[114:117]
	v_mfma_f32_16x16x32_bf16 v[110:113], v[130:133], v[162:165], v[110:113]
	v_mfma_f32_16x16x32_bf16 v[106:109], v[138:141], v[162:165], v[106:109]
	v_mfma_f32_16x16x32_bf16 v[102:105], v[130:133], v[170:173], v[102:105]
	v_mfma_f32_16x16x32_bf16 v[98:101], v[138:141], v[170:173], v[98:101]
	v_mfma_f32_16x16x32_bf16 v[126:129], v[134:137], v[150:153], v[126:129]
	v_mfma_f32_16x16x32_bf16 v[122:125], v[142:145], v[150:153], v[122:125]
	v_mfma_f32_16x16x32_bf16 v[118:121], v[134:137], v[158:161], v[118:121]
	v_mfma_f32_16x16x32_bf16 v[114:117], v[142:145], v[158:161], v[114:117]
	v_mfma_f32_16x16x32_bf16 v[110:113], v[134:137], v[166:169], v[110:113]
	v_mfma_f32_16x16x32_bf16 v[106:109], v[142:145], v[166:169], v[106:109]
	v_mfma_f32_16x16x32_bf16 v[102:105], v[134:137], v[174:177], v[102:105]
	v_mfma_f32_16x16x32_bf16 v[98:101], v[142:145], v[174:177], v[98:101]
	s_barrier
	s_setprio 0
	s_mov_b32 m0, s35
	v_lshl_add_u64 v[216:217], s[52:53], 0, v[194:195]
	ds_read_b128 v[178:181], v253 offset:16384
	ds_read_b128 v[182:185], v253 offset:17408
	ds_read_b128 v[186:189], v253 offset:18432
	ds_read_b128 v[190:193], v253 offset:19456
	global_load_lds_dwordx4 v[216:217], off
	v_lshl_add_u64 v[218:219], s[52:53], 0, v[210:211]
	s_mov_b32 m0, s42
	s_nop 0
	global_load_lds_dwordx4 v[218:219], off
	s_setprio 1
	s_barrier
	s_waitcnt lgkmcnt(0)
	v_mfma_f32_16x16x32_bf16 v[94:97], v[178:181], v[146:149], v[94:97]
	v_mfma_f32_16x16x32_bf16 v[90:93], v[186:189], v[146:149], v[90:93]
	v_mfma_f32_16x16x32_bf16 v[86:89], v[178:181], v[154:157], v[86:89]
	v_mfma_f32_16x16x32_bf16 v[82:85], v[186:189], v[154:157], v[82:85]
	v_mfma_f32_16x16x32_bf16 v[78:81], v[178:181], v[162:165], v[78:81]
	v_mfma_f32_16x16x32_bf16 v[74:77], v[186:189], v[162:165], v[74:77]
	v_mfma_f32_16x16x32_bf16 v[70:73], v[178:181], v[170:173], v[70:73]
	v_mfma_f32_16x16x32_bf16 v[66:69], v[186:189], v[170:173], v[66:69]
	v_mfma_f32_16x16x32_bf16 v[94:97], v[182:185], v[150:153], v[94:97]
	v_mfma_f32_16x16x32_bf16 v[90:93], v[190:193], v[150:153], v[90:93]
	v_mfma_f32_16x16x32_bf16 v[86:89], v[182:185], v[158:161], v[86:89]
	v_mfma_f32_16x16x32_bf16 v[82:85], v[190:193], v[158:161], v[82:85]
	v_mfma_f32_16x16x32_bf16 v[78:81], v[182:185], v[166:169], v[78:81]
	v_mfma_f32_16x16x32_bf16 v[74:77], v[190:193], v[166:169], v[74:77]
	s_mov_b32 m0, s34
	v_mfma_f32_16x16x32_bf16 v[70:73], v[182:185], v[174:177], v[70:73]
	v_lshl_add_u64 v[220:221], s[10:11], 0, v[206:207]
	v_mfma_f32_16x16x32_bf16 v[66:69], v[190:193], v[174:177], v[66:69]
	s_barrier
	s_setprio 0
	ds_read_b128 v[146:149], v199 offset:16384
	ds_read_b128 v[150:153], v199 offset:17408
	ds_read_b128 v[154:157], v199 offset:18432
	ds_read_b128 v[158:161], v199 offset:19456
	ds_read_b128 v[162:165], v199 offset:20480
	ds_read_b128 v[166:169], v199 offset:21504
	ds_read_b128 v[170:173], v199 offset:22528
	ds_read_b128 v[174:177], v199 offset:23552
	global_load_lds_dwordx4 v[220:221], off
	v_lshl_add_u64 v[222:223], s[10:11], 0, v[208:209]
	s_mov_b32 m0, s56
	s_nop 0
	global_load_lds_dwordx4 v[222:223], off
	s_setprio 1
	s_barrier
	s_waitcnt lgkmcnt(0)
	v_mfma_f32_16x16x32_bf16 v[62:65], v[130:133], v[146:149], v[62:65]
	v_mfma_f32_16x16x32_bf16 v[58:61], v[138:141], v[146:149], v[58:61]
	v_mfma_f32_16x16x32_bf16 v[54:57], v[130:133], v[154:157], v[54:57]
	v_mfma_f32_16x16x32_bf16 v[50:53], v[138:141], v[154:157], v[50:53]
	v_mfma_f32_16x16x32_bf16 v[46:49], v[130:133], v[162:165], v[46:49]
	v_mfma_f32_16x16x32_bf16 v[42:45], v[138:141], v[162:165], v[42:45]
	v_mfma_f32_16x16x32_bf16 v[38:41], v[130:133], v[170:173], v[38:41]
	v_mfma_f32_16x16x32_bf16 v[34:37], v[138:141], v[170:173], v[34:37]
	v_mfma_f32_16x16x32_bf16 v[62:65], v[134:137], v[150:153], v[62:65]
	v_mfma_f32_16x16x32_bf16 v[58:61], v[142:145], v[150:153], v[58:61]
	v_mfma_f32_16x16x32_bf16 v[54:57], v[134:137], v[158:161], v[54:57]
	v_mfma_f32_16x16x32_bf16 v[50:53], v[142:145], v[158:161], v[50:53]
	v_mfma_f32_16x16x32_bf16 v[46:49], v[134:137], v[166:169], v[46:49]
	v_mfma_f32_16x16x32_bf16 v[42:45], v[142:145], v[166:169], v[42:45]
	v_mfma_f32_16x16x32_bf16 v[38:41], v[134:137], v[174:177], v[38:41]
	v_mfma_f32_16x16x32_bf16 v[34:37], v[142:145], v[174:177], v[34:37]
	s_barrier
	s_setprio 0
	s_add_u32 s86, s52, 0x40000
	s_addc_u32 s87, s53, 0
	s_mov_b32 m0, s57
	global_load_lds_dwordx4 v194, s[86:87]
	s_mov_b32 m0, s67
	s_nop 0
	global_load_lds_dwordx4 v210, s[86:87]
	s_waitcnt vmcnt(6)
	s_setprio 1
	s_barrier
	v_mfma_f32_16x16x32_bf16 v[30:33], v[178:181], v[146:149], v[30:33]
	v_mfma_f32_16x16x32_bf16 v[26:29], v[186:189], v[146:149], v[26:29]
	v_mfma_f32_16x16x32_bf16 v[22:25], v[178:181], v[154:157], v[22:25]
	v_mfma_f32_16x16x32_bf16 v[18:21], v[186:189], v[154:157], v[18:21]
	v_mfma_f32_16x16x32_bf16 v[14:17], v[178:181], v[162:165], v[14:17]
	v_mfma_f32_16x16x32_bf16 v[10:13], v[186:189], v[162:165], v[10:13]
	v_mfma_f32_16x16x32_bf16 v[6:9], v[178:181], v[170:173], v[6:9]
	v_mfma_f32_16x16x32_bf16 v[2:5], v[186:189], v[170:173], v[2:5]
	v_mfma_f32_16x16x32_bf16 v[30:33], v[182:185], v[150:153], v[30:33]
	v_mfma_f32_16x16x32_bf16 v[26:29], v[190:193], v[150:153], v[26:29]
	v_mfma_f32_16x16x32_bf16 v[22:25], v[182:185], v[158:161], v[22:25]
	v_mfma_f32_16x16x32_bf16 v[18:21], v[190:193], v[158:161], v[18:21]
	v_mfma_f32_16x16x32_bf16 v[14:17], v[182:185], v[166:169], v[14:17]
	v_mfma_f32_16x16x32_bf16 v[10:13], v[190:193], v[166:169], v[10:13]
	v_mfma_f32_16x16x32_bf16 v[6:9], v[182:185], v[174:177], v[6:9]
	v_mfma_f32_16x16x32_bf16 v[2:5], v[190:193], v[174:177], v[2:5]
	s_barrier
	s_setprio 0
	ds_read_b128 v[130:133], v253 offset:32768
	ds_read_b128 v[134:137], v253 offset:33792
	ds_read_b128 v[138:141], v253 offset:34816
	ds_read_b128 v[142:145], v253 offset:35840
	s_add_u32 s10, s10, 0x40000
	s_addc_u32 s11, s11, 0
	s_mov_b32 m0, s70
	ds_read_b128 v[146:149], v199 offset:32768
	ds_read_b128 v[150:153], v199 offset:33792
	ds_read_b128 v[154:157], v199 offset:34816
	ds_read_b128 v[158:161], v199 offset:35840
	ds_read_b128 v[162:165], v199 offset:36864
	ds_read_b128 v[166:169], v199 offset:37888
	ds_read_b128 v[170:173], v199 offset:38912
	ds_read_b128 v[174:177], v199 offset:39936
	global_load_lds_dwordx4 v206, s[10:11]
	s_mov_b32 m0, s71
	s_nop 0
	global_load_lds_dwordx4 v208, s[10:11]
	s_waitcnt lgkmcnt(8)
	s_setprio 1
	s_barrier
	s_waitcnt lgkmcnt(0)
	v_mfma_f32_16x16x32_bf16 v[126:129], v[130:133], v[146:149], v[126:129]
	v_mfma_f32_16x16x32_bf16 v[122:125], v[138:141], v[146:149], v[122:125]
	v_mfma_f32_16x16x32_bf16 v[118:121], v[130:133], v[154:157], v[118:121]
	v_mfma_f32_16x16x32_bf16 v[114:117], v[138:141], v[154:157], v[114:117]
	v_mfma_f32_16x16x32_bf16 v[110:113], v[130:133], v[162:165], v[110:113]
	v_mfma_f32_16x16x32_bf16 v[106:109], v[138:141], v[162:165], v[106:109]
	v_mfma_f32_16x16x32_bf16 v[102:105], v[130:133], v[170:173], v[102:105]
	v_mfma_f32_16x16x32_bf16 v[98:101], v[138:141], v[170:173], v[98:101]
	v_mfma_f32_16x16x32_bf16 v[126:129], v[134:137], v[150:153], v[126:129]
	v_mfma_f32_16x16x32_bf16 v[122:125], v[142:145], v[150:153], v[122:125]
	v_mfma_f32_16x16x32_bf16 v[118:121], v[134:137], v[158:161], v[118:121]
	v_mfma_f32_16x16x32_bf16 v[114:117], v[142:145], v[158:161], v[114:117]
	v_mfma_f32_16x16x32_bf16 v[110:113], v[134:137], v[166:169], v[110:113]
	v_mfma_f32_16x16x32_bf16 v[106:109], v[142:145], v[166:169], v[106:109]
	v_mfma_f32_16x16x32_bf16 v[102:105], v[134:137], v[174:177], v[102:105]
	v_mfma_f32_16x16x32_bf16 v[98:101], v[142:145], v[174:177], v[98:101]
	s_barrier
	s_setprio 0
	s_mov_b32 m0, s78
	v_lshl_add_u64 v[216:217], v[216:217], 0, s[76:77]
	ds_read_b128 v[178:181], v253 offset:49152
	ds_read_b128 v[182:185], v253 offset:50176
	ds_read_b128 v[186:189], v253 offset:51200
	ds_read_b128 v[190:193], v253 offset:52224
	global_load_lds_dwordx4 v[216:217], off
	v_lshl_add_u64 v[216:217], v[218:219], 0, s[76:77]
	s_mov_b32 m0, s79
	s_nop 0
	global_load_lds_dwordx4 v[216:217], off
	s_setprio 1
	s_barrier
	s_waitcnt lgkmcnt(0)
	v_mfma_f32_16x16x32_bf16 v[94:97], v[178:181], v[146:149], v[94:97]
	v_mfma_f32_16x16x32_bf16 v[90:93], v[186:189], v[146:149], v[90:93]
	v_mfma_f32_16x16x32_bf16 v[86:89], v[178:181], v[154:157], v[86:89]
	v_mfma_f32_16x16x32_bf16 v[82:85], v[186:189], v[154:157], v[82:85]
	v_mfma_f32_16x16x32_bf16 v[78:81], v[178:181], v[162:165], v[78:81]
	v_mfma_f32_16x16x32_bf16 v[74:77], v[186:189], v[162:165], v[74:77]
	v_mfma_f32_16x16x32_bf16 v[70:73], v[178:181], v[170:173], v[70:73]
	v_mfma_f32_16x16x32_bf16 v[66:69], v[186:189], v[170:173], v[66:69]
	v_mfma_f32_16x16x32_bf16 v[94:97], v[182:185], v[150:153], v[94:97]
	v_mfma_f32_16x16x32_bf16 v[90:93], v[190:193], v[150:153], v[90:93]
	v_mfma_f32_16x16x32_bf16 v[86:89], v[182:185], v[158:161], v[86:89]
	v_mfma_f32_16x16x32_bf16 v[82:85], v[190:193], v[158:161], v[82:85]
	v_mfma_f32_16x16x32_bf16 v[78:81], v[182:185], v[166:169], v[78:81]
	v_mfma_f32_16x16x32_bf16 v[74:77], v[190:193], v[166:169], v[74:77]
	s_mov_b32 m0, s26
	v_mfma_f32_16x16x32_bf16 v[70:73], v[182:185], v[174:177], v[70:73]
	v_lshl_add_u64 v[216:217], v[220:221], 0, s[76:77]
	v_mfma_f32_16x16x32_bf16 v[66:69], v[190:193], v[174:177], v[66:69]
	s_barrier
	s_setprio 0
	ds_read_b128 v[146:149], v199 offset:49152
	ds_read_b128 v[150:153], v199 offset:50176
	ds_read_b128 v[154:157], v199 offset:51200
	ds_read_b128 v[158:161], v199 offset:52224
	ds_read_b128 v[162:165], v199 offset:53248
	ds_read_b128 v[166:169], v199 offset:54272
	ds_read_b128 v[170:173], v199 offset:55296
	ds_read_b128 v[174:177], v199 offset:56320
	global_load_lds_dwordx4 v[216:217], off
	v_lshl_add_u64 v[216:217], v[222:223], 0, s[76:77]
	s_mov_b32 m0, s4
	s_nop 0
	global_load_lds_dwordx4 v[216:217], off
	s_setprio 1
	s_barrier
	s_waitcnt lgkmcnt(0)
	v_mfma_f32_16x16x32_bf16 v[62:65], v[130:133], v[146:149], v[62:65]
	v_mfma_f32_16x16x32_bf16 v[58:61], v[138:141], v[146:149], v[58:61]
	v_mfma_f32_16x16x32_bf16 v[54:57], v[130:133], v[154:157], v[54:57]
	v_mfma_f32_16x16x32_bf16 v[50:53], v[138:141], v[154:157], v[50:53]
	v_mfma_f32_16x16x32_bf16 v[46:49], v[130:133], v[162:165], v[46:49]
	v_mfma_f32_16x16x32_bf16 v[42:45], v[138:141], v[162:165], v[42:45]
	v_mfma_f32_16x16x32_bf16 v[38:41], v[130:133], v[170:173], v[38:41]
	v_mfma_f32_16x16x32_bf16 v[34:37], v[138:141], v[170:173], v[34:37]
	v_mfma_f32_16x16x32_bf16 v[62:65], v[134:137], v[150:153], v[62:65]
	v_mfma_f32_16x16x32_bf16 v[58:61], v[142:145], v[150:153], v[58:61]
	v_mfma_f32_16x16x32_bf16 v[54:57], v[134:137], v[158:161], v[54:57]
	v_mfma_f32_16x16x32_bf16 v[50:53], v[142:145], v[158:161], v[50:53]
	v_mfma_f32_16x16x32_bf16 v[46:49], v[134:137], v[166:169], v[46:49]
	v_mfma_f32_16x16x32_bf16 v[42:45], v[142:145], v[166:169], v[42:45]
	v_mfma_f32_16x16x32_bf16 v[38:41], v[134:137], v[174:177], v[38:41]
	v_mfma_f32_16x16x32_bf16 v[34:37], v[142:145], v[174:177], v[34:37]
	s_barrier
	s_setprio 0
	s_add_u32 s10, s52, 0x40080
	s_addc_u32 s11, s53, 0
	s_mov_b32 m0, s5
	global_load_lds_dwordx4 v194, s[10:11]
	s_mov_b32 m0, s58
	s_nop 0
	global_load_lds_dwordx4 v210, s[10:11]
	s_waitcnt vmcnt(6)
	s_setprio 1
	s_barrier
	v_mfma_f32_16x16x32_bf16 v[30:33], v[178:181], v[146:149], v[30:33]
	v_mfma_f32_16x16x32_bf16 v[26:29], v[186:189], v[146:149], v[26:29]
	v_mfma_f32_16x16x32_bf16 v[22:25], v[178:181], v[154:157], v[22:25]
	v_mfma_f32_16x16x32_bf16 v[18:21], v[186:189], v[154:157], v[18:21]
	v_mfma_f32_16x16x32_bf16 v[14:17], v[178:181], v[162:165], v[14:17]
	v_mfma_f32_16x16x32_bf16 v[10:13], v[186:189], v[162:165], v[10:13]
	v_mfma_f32_16x16x32_bf16 v[6:9], v[178:181], v[170:173], v[6:9]
	v_mfma_f32_16x16x32_bf16 v[2:5], v[186:189], v[170:173], v[2:5]
	v_mfma_f32_16x16x32_bf16 v[30:33], v[182:185], v[150:153], v[30:33]
	v_mfma_f32_16x16x32_bf16 v[26:29], v[190:193], v[150:153], v[26:29]
	v_mfma_f32_16x16x32_bf16 v[22:25], v[182:185], v[158:161], v[22:25]
	v_mfma_f32_16x16x32_bf16 v[18:21], v[190:193], v[158:161], v[18:21]
	v_mfma_f32_16x16x32_bf16 v[14:17], v[182:185], v[166:169], v[14:17]
	v_mfma_f32_16x16x32_bf16 v[10:13], v[190:193], v[166:169], v[10:13]
	v_mfma_f32_16x16x32_bf16 v[6:9], v[182:185], v[174:177], v[6:9]
	v_mfma_f32_16x16x32_bf16 v[2:5], v[190:193], v[174:177], v[2:5]
	s_setprio 0
	s_add_i32 s29, s29, 2
	s_add_u32 s8, s8, 0x100
	s_addc_u32 s9, s9, 0
	s_add_u32 s7, s7, 0x100
	s_addc_u32 s28, s28, 0
	s_cmp_gt_u32 s29, 13
	s_barrier
	s_cbranch_scc0 .LBB0_368
	s_cmp_gt_i32 s95, 1
	s_cselect_b64 s[52:53], -1, 0
	s_mul_i32 s7, s6, 0x680000
	s_lshl_b32 s8, s95, 12
	s_lshl_b32 s9, s54, 9
	s_add_i32 s7, s7, s8
	s_add_i32 s7, s7, s9
	s_add_i32 s7, s7, 0x3800
	s_add_u32 s20, s50, s7
	s_addc_u32 s21, s51, 0
	s_lshl_b32 s7, s6, 20
	s_add_i32 s7, s7, s9
	s_add_u32 s10, s96, s7
	s_addc_u32 s11, s97, 0
	s_mov_b32 s86, 0xbfb8aa3b
	s_mov_b32 s87, 0xbfb8aa3b
	v_mul_u32_u24_e32 v253, 0x6800, v197
	v_lshlrev_b32_e32 v255, 12, v197
	v_lshl_add_u32 v253, v203, 1, v253
	v_lshl_add_u32 v255, v203, 1, v255
	v_add_u32_e32 v254, 0x1000, v253
	s_cmp_eq_u32 s95, 2
	s_cbranch_scc1 .Lem_br2
	global_load_dwordx4 v[130:133], v253, s[20:21]
	global_load_dwordx4 v[134:137], v254, s[20:21]
	global_load_dwordx4 v[138:141], v253, s[20:21] offset:256
	global_load_dwordx4 v[142:145], v254, s[20:21] offset:256
	s_add_u32 s28, s20, 0x68000
	s_addc_u32 s29, s21, 0
	global_load_dwordx4 v[146:149], v253, s[28:29]
	global_load_dwordx4 v[150:153], v254, s[28:29]
	global_load_dwordx4 v[154:157], v253, s[28:29] offset:256
	global_load_dwordx4 v[158:161], v254, s[28:29] offset:256
	s_add_u32 s28, s20, 0xd0000
	s_addc_u32 s29, s21, 0
	global_load_dwordx4 v[162:165], v253, s[28:29]
	global_load_dwordx4 v[166:169], v254, s[28:29]
	global_load_dwordx4 v[170:173], v253, s[28:29] offset:256
	global_load_dwordx4 v[174:177], v254, s[28:29] offset:256
	s_add_u32 s28, s20, 0x138000
	s_addc_u32 s29, s21, 0
	global_load_dwordx4 v[178:181], v253, s[28:29]
	global_load_dwordx4 v[182:185], v254, s[28:29]
	global_load_dwordx4 v[186:189], v253, s[28:29] offset:256
	global_load_dwordx4 v[190:193], v254, s[28:29] offset:256
	s_waitcnt vmcnt(12)
	v_lshlrev_b32_e32 v216, 16, v130
	v_and_b32_e32 v217, 0xffff0000, v130
	v_lshlrev_b32_e32 v218, 16, v131
	v_and_b32_e32 v219, 0xffff0000, v131
	v_lshlrev_b32_e32 v220, 16, v132
	v_and_b32_e32 v221, 0xffff0000, v132
	v_lshlrev_b32_e32 v222, 16, v133
	v_and_b32_e32 v223, 0xffff0000, v133
	v_pk_mul_f32 v[216:217], v[216:217], s[86:87] op_sel_hi:[1,0]
	v_pk_mul_f32 v[218:219], v[218:219], s[86:87] op_sel_hi:[1,0]
	v_pk_mul_f32 v[220:221], v[220:221], s[86:87] op_sel_hi:[1,0]
	v_pk_mul_f32 v[222:223], v[222:223], s[86:87] op_sel_hi:[1,0]
	v_exp_f32_e32 v216, v216
	v_exp_f32_e32 v217, v217
	v_exp_f32_e32 v218, v218
	v_exp_f32_e32 v219, v219
	v_exp_f32_e32 v220, v220
	v_exp_f32_e32 v221, v221
	v_exp_f32_e32 v222, v222
	v_exp_f32_e32 v223, v223
	v_pk_add_f32 v[216:217], v[216:217], 1.0 op_sel_hi:[1,0]
	v_pk_add_f32 v[218:219], v[218:219], 1.0 op_sel_hi:[1,0]
	v_pk_add_f32 v[220:221], v[220:221], 1.0 op_sel_hi:[1,0]
	v_pk_add_f32 v[222:223], v[222:223], 1.0 op_sel_hi:[1,0]
	v_rcp_f32_e32 v216, v216
	v_rcp_f32_e32 v217, v217
	v_rcp_f32_e32 v218, v218
	v_rcp_f32_e32 v219, v219
	v_rcp_f32_e32 v220, v220
	v_rcp_f32_e32 v221, v221
	v_rcp_f32_e32 v222, v222
	v_rcp_f32_e32 v223, v223
	v_lshlrev_b32_e32 v242, 16, v134
	v_and_b32_e32 v243, 0xffff0000, v134
	v_lshlrev_b32_e32 v244, 16, v135
	v_and_b32_e32 v245, 0xffff0000, v135
	v_lshlrev_b32_e32 v246, 16, v136
	v_and_b32_e32 v247, 0xffff0000, v136
	v_lshlrev_b32_e32 v248, 16, v137
	v_and_b32_e32 v249, 0xffff0000, v137
	v_pk_mul_f32 v[242:243], v[242:243], s[86:87] op_sel_hi:[1,0]
	v_pk_mul_f32 v[244:245], v[244:245], s[86:87] op_sel_hi:[1,0]
	v_pk_mul_f32 v[246:247], v[246:247], s[86:87] op_sel_hi:[1,0]
	v_pk_mul_f32 v[248:249], v[248:249], s[86:87] op_sel_hi:[1,0]
	v_exp_f32_e32 v242, v242
	v_exp_f32_e32 v243, v243
	v_exp_f32_e32 v244, v244
	v_exp_f32_e32 v245, v245
	v_exp_f32_e32 v246, v246
	v_exp_f32_e32 v247, v247
	v_exp_f32_e32 v248, v248
	v_exp_f32_e32 v249, v249
	v_pk_add_f32 v[242:243], v[242:243], 1.0 op_sel_hi:[1,0]
	v_pk_add_f32 v[244:245], v[244:245], 1.0 op_sel_hi:[1,0]
	v_pk_add_f32 v[246:247], v[246:247], 1.0 op_sel_hi:[1,0]
	v_pk_add_f32 v[248:249], v[248:249], 1.0 op_sel_hi:[1,0]
	v_pk_mul_f32 v[216:217], v[216:217], v[242:243]
	v_pk_mul_f32 v[218:219], v[218:219], v[244:245]
	v_pk_mul_f32 v[220:221], v[220:221], v[246:247]
	v_pk_mul_f32 v[222:223], v[222:223], v[248:249]
	v_pk_mul_f32 v[126:127], v[126:127], v[216:217]
	v_pk_mul_f32 v[128:129], v[128:129], v[218:219]
	v_pk_mul_f32 v[122:123], v[122:123], v[220:221]
	v_pk_mul_f32 v[124:125], v[124:125], v[222:223]
	v_lshlrev_b32_e32 v216, 16, v138
	v_and_b32_e32 v217, 0xffff0000, v138
	v_lshlrev_b32_e32 v218, 16, v139
	v_and_b32_e32 v219, 0xffff0000, v139
	v_lshlrev_b32_e32 v220, 16, v140
	v_and_b32_e32 v221, 0xffff0000, v140
	v_lshlrev_b32_e32 v222, 16, v141
	v_and_b32_e32 v223, 0xffff0000, v141
	v_pk_mul_f32 v[216:217], v[216:217], s[86:87] op_sel_hi:[1,0]
	v_pk_mul_f32 v[218:219], v[218:219], s[86:87] op_sel_hi:[1,0]
	v_pk_mul_f32 v[220:221], v[220:221], s[86:87] op_sel_hi:[1,0]
	v_pk_mul_f32 v[222:223], v[222:223], s[86:87] op_sel_hi:[1,0]
	v_exp_f32_e32 v216, v216
	v_exp_f32_e32 v217, v217
	v_exp_f32_e32 v218, v218
	v_exp_f32_e32 v219, v219
	v_exp_f32_e32 v220, v220
	v_exp_f32_e32 v221, v221
	v_exp_f32_e32 v222, v222
	v_exp_f32_e32 v223, v223
	v_pk_add_f32 v[216:217], v[216:217], 1.0 op_sel_hi:[1,0]
	v_pk_add_f32 v[218:219], v[218:219], 1.0 op_sel_hi:[1,0]
	v_pk_add_f32 v[220:221], v[220:221], 1.0 op_sel_hi:[1,0]
	v_pk_add_f32 v[222:223], v[222:223], 1.0 op_sel_hi:[1,0]
	v_rcp_f32_e32 v216, v216
	v_rcp_f32_e32 v217, v217
	v_rcp_f32_e32 v218, v218
	v_rcp_f32_e32 v219, v219
	v_rcp_f32_e32 v220, v220
	v_rcp_f32_e32 v221, v221
	v_rcp_f32_e32 v222, v222
	v_rcp_f32_e32 v223, v223
	v_lshlrev_b32_e32 v242, 16, v142
	v_and_b32_e32 v243, 0xffff0000, v142
	v_lshlrev_b32_e32 v244, 16, v143
	v_and_b32_e32 v245, 0xffff0000, v143
	v_lshlrev_b32_e32 v246, 16, v144
	v_and_b32_e32 v247, 0xffff0000, v144
	v_lshlrev_b32_e32 v248, 16, v145
	v_and_b32_e32 v249, 0xffff0000, v145
	v_pk_mul_f32 v[242:243], v[242:243], s[86:87] op_sel_hi:[1,0]
	v_pk_mul_f32 v[244:245], v[244:245], s[86:87] op_sel_hi:[1,0]
	v_pk_mul_f32 v[246:247], v[246:247], s[86:87] op_sel_hi:[1,0]
	v_pk_mul_f32 v[248:249], v[248:249], s[86:87] op_sel_hi:[1,0]
	v_exp_f32_e32 v242, v242
	v_exp_f32_e32 v243, v243
	v_exp_f32_e32 v244, v244
	v_exp_f32_e32 v245, v245
	v_exp_f32_e32 v246, v246
	v_exp_f32_e32 v247, v247
	v_exp_f32_e32 v248, v248
	v_exp_f32_e32 v249, v249
	v_pk_add_f32 v[242:243], v[242:243], 1.0 op_sel_hi:[1,0]
	v_pk_add_f32 v[244:245], v[244:245], 1.0 op_sel_hi:[1,0]
	v_pk_add_f32 v[246:247], v[246:247], 1.0 op_sel_hi:[1,0]
	v_pk_add_f32 v[248:249], v[248:249], 1.0 op_sel_hi:[1,0]
	v_pk_mul_f32 v[216:217], v[216:217], v[242:243]
	v_pk_mul_f32 v[218:219], v[218:219], v[244:245]
	v_pk_mul_f32 v[220:221], v[220:221], v[246:247]
	v_pk_mul_f32 v[222:223], v[222:223], v[248:249]
	v_pk_mul_f32 v[94:95], v[94:95], v[216:217]
	v_pk_mul_f32 v[96:97], v[96:97], v[218:219]
	v_pk_mul_f32 v[90:91], v[90:91], v[220:221]
	v_pk_mul_f32 v[92:93], v[92:93], v[222:223]
	s_add_u32 s28, s20, 0x340000
	s_addc_u32 s29, s21, 0
	global_load_dwordx4 v[130:133], v253, s[28:29]
	global_load_dwordx4 v[134:137], v254, s[28:29]
	global_load_dwordx4 v[138:141], v253, s[28:29] offset:256
	global_load_dwordx4 v[142:145], v254, s[28:29] offset:256
	s_waitcnt vmcnt(12)
	v_lshlrev_b32_e32 v216, 16, v146
	v_and_b32_e32 v217, 0xffff0000, v146
	v_lshlrev_b32_e32 v218, 16, v147
	v_and_b32_e32 v219, 0xffff0000, v147
	v_lshlrev_b32_e32 v220, 16, v148
	v_and_b32_e32 v221, 0xffff0000, v148
	v_lshlrev_b32_e32 v222, 16, v149
	v_and_b32_e32 v223, 0xffff0000, v149
	v_pk_mul_f32 v[216:217], v[216:217], s[86:87] op_sel_hi:[1,0]
	v_pk_mul_f32 v[218:219], v[218:219], s[86:87] op_sel_hi:[1,0]
	v_pk_mul_f32 v[220:221], v[220:221], s[86:87] op_sel_hi:[1,0]
	v_pk_mul_f32 v[222:223], v[222:223], s[86:87] op_sel_hi:[1,0]
	v_exp_f32_e32 v216, v216
	v_exp_f32_e32 v217, v217
	v_exp_f32_e32 v218, v218
	v_exp_f32_e32 v219, v219
	v_exp_f32_e32 v220, v220
	v_exp_f32_e32 v221, v221
	v_exp_f32_e32 v222, v222
	v_exp_f32_e32 v223, v223
	v_pk_add_f32 v[216:217], v[216:217], 1.0 op_sel_hi:[1,0]
	v_pk_add_f32 v[218:219], v[218:219], 1.0 op_sel_hi:[1,0]
	v_pk_add_f32 v[220:221], v[220:221], 1.0 op_sel_hi:[1,0]
	v_pk_add_f32 v[222:223], v[222:223], 1.0 op_sel_hi:[1,0]
	v_rcp_f32_e32 v216, v216
	v_rcp_f32_e32 v217, v217
	v_rcp_f32_e32 v218, v218
	v_rcp_f32_e32 v219, v219
	v_rcp_f32_e32 v220, v220
	v_rcp_f32_e32 v221, v221
	v_rcp_f32_e32 v222, v222
	v_rcp_f32_e32 v223, v223
	v_lshlrev_b32_e32 v242, 16, v150
	v_and_b32_e32 v243, 0xffff0000, v150
	v_lshlrev_b32_e32 v244, 16, v151
	v_and_b32_e32 v245, 0xffff0000, v151
	v_lshlrev_b32_e32 v246, 16, v152
	v_and_b32_e32 v247, 0xffff0000, v152
	v_lshlrev_b32_e32 v248, 16, v153
	v_and_b32_e32 v249, 0xffff0000, v153
	v_pk_mul_f32 v[242:243], v[242:243], s[86:87] op_sel_hi:[1,0]
	v_pk_mul_f32 v[244:245], v[244:245], s[86:87] op_sel_hi:[1,0]
	v_pk_mul_f32 v[246:247], v[246:247], s[86:87] op_sel_hi:[1,0]
	v_pk_mul_f32 v[248:249], v[248:249], s[86:87] op_sel_hi:[1,0]
	v_exp_f32_e32 v242, v242
	v_exp_f32_e32 v243, v243
	v_exp_f32_e32 v244, v244
	v_exp_f32_e32 v245, v245
	v_exp_f32_e32 v246, v246
	v_exp_f32_e32 v247, v247
	v_exp_f32_e32 v248, v248
	v_exp_f32_e32 v249, v249
	v_pk_add_f32 v[242:243], v[242:243], 1.0 op_sel_hi:[1,0]
	v_pk_add_f32 v[244:245], v[244:245], 1.0 op_sel_hi:[1,0]
	v_pk_add_f32 v[246:247], v[246:247], 1.0 op_sel_hi:[1,0]
	v_pk_add_f32 v[248:249], v[248:249], 1.0 op_sel_hi:[1,0]
	v_pk_mul_f32 v[216:217], v[216:217], v[242:243]
	v_pk_mul_f32 v[218:219], v[218:219], v[244:245]
	v_pk_mul_f32 v[220:221], v[220:221], v[246:247]
	v_pk_mul_f32 v[222:223], v[222:223], v[248:249]
	v_pk_mul_f32 v[118:119], v[118:119], v[216:217]
	v_pk_mul_f32 v[120:121], v[120:121], v[218:219]
	v_pk_mul_f32 v[114:115], v[114:115], v[220:221]
	v_pk_mul_f32 v[116:117], v[116:117], v[222:223]
	v_lshlrev_b32_e32 v216, 16, v154
	v_and_b32_e32 v217, 0xffff0000, v154
	v_lshlrev_b32_e32 v218, 16, v155
	v_and_b32_e32 v219, 0xffff0000, v155
	v_lshlrev_b32_e32 v220, 16, v156
	v_and_b32_e32 v221, 0xffff0000, v156
	v_lshlrev_b32_e32 v222, 16, v157
	v_and_b32_e32 v223, 0xffff0000, v157
	v_pk_mul_f32 v[216:217], v[216:217], s[86:87] op_sel_hi:[1,0]
	v_pk_mul_f32 v[218:219], v[218:219], s[86:87] op_sel_hi:[1,0]
	v_pk_mul_f32 v[220:221], v[220:221], s[86:87] op_sel_hi:[1,0]
	v_pk_mul_f32 v[222:223], v[222:223], s[86:87] op_sel_hi:[1,0]
	v_exp_f32_e32 v216, v216
	v_exp_f32_e32 v217, v217
	v_exp_f32_e32 v218, v218
	v_exp_f32_e32 v219, v219
	v_exp_f32_e32 v220, v220
	v_exp_f32_e32 v221, v221
	v_exp_f32_e32 v222, v222
	v_exp_f32_e32 v223, v223
	v_pk_add_f32 v[216:217], v[216:217], 1.0 op_sel_hi:[1,0]
	v_pk_add_f32 v[218:219], v[218:219], 1.0 op_sel_hi:[1,0]
	v_pk_add_f32 v[220:221], v[220:221], 1.0 op_sel_hi:[1,0]
	v_pk_add_f32 v[222:223], v[222:223], 1.0 op_sel_hi:[1,0]
	v_rcp_f32_e32 v216, v216
	v_rcp_f32_e32 v217, v217
	v_rcp_f32_e32 v218, v218
	v_rcp_f32_e32 v219, v219
	v_rcp_f32_e32 v220, v220
	v_rcp_f32_e32 v221, v221
	v_rcp_f32_e32 v222, v222
	v_rcp_f32_e32 v223, v223
	v_lshlrev_b32_e32 v242, 16, v158
	v_and_b32_e32 v243, 0xffff0000, v158
	v_lshlrev_b32_e32 v244, 16, v159
	v_and_b32_e32 v245, 0xffff0000, v159
	v_lshlrev_b32_e32 v246, 16, v160
	v_and_b32_e32 v247, 0xffff0000, v160
	v_lshlrev_b32_e32 v248, 16, v161
	v_and_b32_e32 v249, 0xffff0000, v161
	v_pk_mul_f32 v[242:243], v[242:243], s[86:87] op_sel_hi:[1,0]
	v_pk_mul_f32 v[244:245], v[244:245], s[86:87] op_sel_hi:[1,0]
	v_pk_mul_f32 v[246:247], v[246:247], s[86:87] op_sel_hi:[1,0]
	v_pk_mul_f32 v[248:249], v[248:249], s[86:87] op_sel_hi:[1,0]
	v_exp_f32_e32 v242, v242
	v_exp_f32_e32 v243, v243
	v_exp_f32_e32 v244, v244
	v_exp_f32_e32 v245, v245
	v_exp_f32_e32 v246, v246
	v_exp_f32_e32 v247, v247
	v_exp_f32_e32 v248, v248
	v_exp_f32_e32 v249, v249
	v_pk_add_f32 v[242:243], v[242:243], 1.0 op_sel_hi:[1,0]
	v_pk_add_f32 v[244:245], v[244:245], 1.0 op_sel_hi:[1,0]
	v_pk_add_f32 v[246:247], v[246:247], 1.0 op_sel_hi:[1,0]
	v_pk_add_f32 v[248:249], v[248:249], 1.0 op_sel_hi:[1,0]
	v_pk_mul_f32 v[216:217], v[216:217], v[242:243]
	v_pk_mul_f32 v[218:219], v[218:219], v[244:245]
	v_pk_mul_f32 v[220:221], v[220:221], v[246:247]
	v_pk_mul_f32 v[222:223], v[222:223], v[248:249]
	v_pk_mul_f32 v[86:87], v[86:87], v[216:217]
	v_pk_mul_f32 v[88:89], v[88:89], v[218:219]
	v_pk_mul_f32 v[82:83], v[82:83], v[220:221]
	v_pk_mul_f32 v[84:85], v[84:85], v[222:223]
	s_add_u32 s28, s20, 0x3a8000
	s_addc_u32 s29, s21, 0
	global_load_dwordx4 v[146:149], v253, s[28:29]
	global_load_dwordx4 v[150:153], v254, s[28:29]
	global_load_dwordx4 v[154:157], v253, s[28:29] offset:256
	global_load_dwordx4 v[158:161], v254, s[28:29] offset:256
	s_waitcnt vmcnt(12)
	v_lshlrev_b32_e32 v216, 16, v162
	v_and_b32_e32 v217, 0xffff0000, v162
	v_lshlrev_b32_e32 v218, 16, v163
	v_and_b32_e32 v219, 0xffff0000, v163
	v_lshlrev_b32_e32 v220, 16, v164
	v_and_b32_e32 v221, 0xffff0000, v164
	v_lshlrev_b32_e32 v222, 16, v165
	v_and_b32_e32 v223, 0xffff0000, v165
	v_pk_mul_f32 v[216:217], v[216:217], s[86:87] op_sel_hi:[1,0]
	v_pk_mul_f32 v[218:219], v[218:219], s[86:87] op_sel_hi:[1,0]
	v_pk_mul_f32 v[220:221], v[220:221], s[86:87] op_sel_hi:[1,0]
	v_pk_mul_f32 v[222:223], v[222:223], s[86:87] op_sel_hi:[1,0]
	v_exp_f32_e32 v216, v216
	v_exp_f32_e32 v217, v217
	v_exp_f32_e32 v218, v218
	v_exp_f32_e32 v219, v219
	v_exp_f32_e32 v220, v220
	v_exp_f32_e32 v221, v221
	v_exp_f32_e32 v222, v222
	v_exp_f32_e32 v223, v223
	v_pk_add_f32 v[216:217], v[216:217], 1.0 op_sel_hi:[1,0]
	v_pk_add_f32 v[218:219], v[218:219], 1.0 op_sel_hi:[1,0]
	v_pk_add_f32 v[220:221], v[220:221], 1.0 op_sel_hi:[1,0]
	v_pk_add_f32 v[222:223], v[222:223], 1.0 op_sel_hi:[1,0]
	v_rcp_f32_e32 v216, v216
	v_rcp_f32_e32 v217, v217
	v_rcp_f32_e32 v218, v218
	v_rcp_f32_e32 v219, v219
	v_rcp_f32_e32 v220, v220
	v_rcp_f32_e32 v221, v221
	v_rcp_f32_e32 v222, v222
	v_rcp_f32_e32 v223, v223
	v_lshlrev_b32_e32 v242, 16, v166
	v_and_b32_e32 v243, 0xffff0000, v166
	v_lshlrev_b32_e32 v244, 16, v167
	v_and_b32_e32 v245, 0xffff0000, v167
	v_lshlrev_b32_e32 v246, 16, v168
	v_and_b32_e32 v247, 0xffff0000, v168
	v_lshlrev_b32_e32 v248, 16, v169
	v_and_b32_e32 v249, 0xffff0000, v169
	v_pk_mul_f32 v[242:243], v[242:243], s[86:87] op_sel_hi:[1,0]
	v_pk_mul_f32 v[244:245], v[244:245], s[86:87] op_sel_hi:[1,0]
	v_pk_mul_f32 v[246:247], v[246:247], s[86:87] op_sel_hi:[1,0]
	v_pk_mul_f32 v[248:249], v[248:249], s[86:87] op_sel_hi:[1,0]
	v_exp_f32_e32 v242, v242
	v_exp_f32_e32 v243, v243
	v_exp_f32_e32 v244, v244
	v_exp_f32_e32 v245, v245
	v_exp_f32_e32 v246, v246
	v_exp_f32_e32 v247, v247
	v_exp_f32_e32 v248, v248
	v_exp_f32_e32 v249, v249
	v_pk_add_f32 v[242:243], v[242:243], 1.0 op_sel_hi:[1,0]
	v_pk_add_f32 v[244:245], v[244:245], 1.0 op_sel_hi:[1,0]
	v_pk_add_f32 v[246:247], v[246:247], 1.0 op_sel_hi:[1,0]
	v_pk_add_f32 v[248:249], v[248:249], 1.0 op_sel_hi:[1,0]
	v_pk_mul_f32 v[216:217], v[216:217], v[242:243]
	v_pk_mul_f32 v[218:219], v[218:219], v[244:245]
	v_pk_mul_f32 v[220:221], v[220:221], v[246:247]
	v_pk_mul_f32 v[222:223], v[222:223], v[248:249]
	v_pk_mul_f32 v[110:111], v[110:111], v[216:217]
	v_pk_mul_f32 v[112:113], v[112:113], v[218:219]
	v_pk_mul_f32 v[106:107], v[106:107], v[220:221]
	v_pk_mul_f32 v[108:109], v[108:109], v[222:223]
	v_lshlrev_b32_e32 v216, 16, v170
	v_and_b32_e32 v217, 0xffff0000, v170
	v_lshlrev_b32_e32 v218, 16, v171
	v_and_b32_e32 v219, 0xffff0000, v171
	v_lshlrev_b32_e32 v220, 16, v172
	v_and_b32_e32 v221, 0xffff0000, v172
	v_lshlrev_b32_e32 v222, 16, v173
	v_and_b32_e32 v223, 0xffff0000, v173
	v_pk_mul_f32 v[216:217], v[216:217], s[86:87] op_sel_hi:[1,0]
	v_pk_mul_f32 v[218:219], v[218:219], s[86:87] op_sel_hi:[1,0]
	v_pk_mul_f32 v[220:221], v[220:221], s[86:87] op_sel_hi:[1,0]
	v_pk_mul_f32 v[222:223], v[222:223], s[86:87] op_sel_hi:[1,0]
	v_exp_f32_e32 v216, v216
	v_exp_f32_e32 v217, v217
	v_exp_f32_e32 v218, v218
	v_exp_f32_e32 v219, v219
	v_exp_f32_e32 v220, v220
	v_exp_f32_e32 v221, v221
	v_exp_f32_e32 v222, v222
	v_exp_f32_e32 v223, v223
	v_pk_add_f32 v[216:217], v[216:217], 1.0 op_sel_hi:[1,0]
	v_pk_add_f32 v[218:219], v[218:219], 1.0 op_sel_hi:[1,0]
	v_pk_add_f32 v[220:221], v[220:221], 1.0 op_sel_hi:[1,0]
	v_pk_add_f32 v[222:223], v[222:223], 1.0 op_sel_hi:[1,0]
	v_rcp_f32_e32 v216, v216
	v_rcp_f32_e32 v217, v217
	v_rcp_f32_e32 v218, v218
	v_rcp_f32_e32 v219, v219
	v_rcp_f32_e32 v220, v220
	v_rcp_f32_e32 v221, v221
	v_rcp_f32_e32 v222, v222
	v_rcp_f32_e32 v223, v223
	v_lshlrev_b32_e32 v242, 16, v174
	v_and_b32_e32 v243, 0xffff0000, v174
	v_lshlrev_b32_e32 v244, 16, v175
	v_and_b32_e32 v245, 0xffff0000, v175
	v_lshlrev_b32_e32 v246, 16, v176
	v_and_b32_e32 v247, 0xffff0000, v176
	v_lshlrev_b32_e32 v248, 16, v177
	v_and_b32_e32 v249, 0xffff0000, v177
	v_pk_mul_f32 v[242:243], v[242:243], s[86:87] op_sel_hi:[1,0]
	v_pk_mul_f32 v[244:245], v[244:245], s[86:87] op_sel_hi:[1,0]
	v_pk_mul_f32 v[246:247], v[246:247], s[86:87] op_sel_hi:[1,0]
	v_pk_mul_f32 v[248:249], v[248:249], s[86:87] op_sel_hi:[1,0]
	v_exp_f32_e32 v242, v242
	v_exp_f32_e32 v243, v243
	v_exp_f32_e32 v244, v244
	v_exp_f32_e32 v245, v245
	v_exp_f32_e32 v246, v246
	v_exp_f32_e32 v247, v247
	v_exp_f32_e32 v248, v248
	v_exp_f32_e32 v249, v249
	v_pk_add_f32 v[242:243], v[242:243], 1.0 op_sel_hi:[1,0]
	v_pk_add_f32 v[244:245], v[244:245], 1.0 op_sel_hi:[1,0]
	v_pk_add_f32 v[246:247], v[246:247], 1.0 op_sel_hi:[1,0]
	v_pk_add_f32 v[248:249], v[248:249], 1.0 op_sel_hi:[1,0]
	v_pk_mul_f32 v[216:217], v[216:217], v[242:243]
	v_pk_mul_f32 v[218:219], v[218:219], v[244:245]
	v_pk_mul_f32 v[220:221], v[220:221], v[246:247]
	v_pk_mul_f32 v[222:223], v[222:223], v[248:249]
	v_pk_mul_f32 v[78:79], v[78:79], v[216:217]
	v_pk_mul_f32 v[80:81], v[80:81], v[218:219]
	v_pk_mul_f32 v[74:75], v[74:75], v[220:221]
	v_pk_mul_f32 v[76:77], v[76:77], v[222:223]
	s_add_u32 s28, s20, 0x410000
	s_addc_u32 s29, s21, 0
	global_load_dwordx4 v[162:165], v253, s[28:29]
	global_load_dwordx4 v[166:169], v254, s[28:29]
	global_load_dwordx4 v[170:173], v253, s[28:29] offset:256
	global_load_dwordx4 v[174:177], v254, s[28:29] offset:256
	s_waitcnt vmcnt(12)
	v_lshlrev_b32_e32 v216, 16, v178
	v_and_b32_e32 v217, 0xffff0000, v178
	v_lshlrev_b32_e32 v218, 16, v179
	v_and_b32_e32 v219, 0xffff0000, v179
	v_lshlrev_b32_e32 v220, 16, v180
	v_and_b32_e32 v221, 0xffff0000, v180
	v_lshlrev_b32_e32 v222, 16, v181
	v_and_b32_e32 v223, 0xffff0000, v181
	v_pk_mul_f32 v[216:217], v[216:217], s[86:87] op_sel_hi:[1,0]
	v_pk_mul_f32 v[218:219], v[218:219], s[86:87] op_sel_hi:[1,0]
	v_pk_mul_f32 v[220:221], v[220:221], s[86:87] op_sel_hi:[1,0]
	v_pk_mul_f32 v[222:223], v[222:223], s[86:87] op_sel_hi:[1,0]
	v_exp_f32_e32 v216, v216
	v_exp_f32_e32 v217, v217
	v_exp_f32_e32 v218, v218
	v_exp_f32_e32 v219, v219
	v_exp_f32_e32 v220, v220
	v_exp_f32_e32 v221, v221
	v_exp_f32_e32 v222, v222
	v_exp_f32_e32 v223, v223
	v_pk_add_f32 v[216:217], v[216:217], 1.0 op_sel_hi:[1,0]
	v_pk_add_f32 v[218:219], v[218:219], 1.0 op_sel_hi:[1,0]
	v_pk_add_f32 v[220:221], v[220:221], 1.0 op_sel_hi:[1,0]
	v_pk_add_f32 v[222:223], v[222:223], 1.0 op_sel_hi:[1,0]
	v_rcp_f32_e32 v216, v216
	v_rcp_f32_e32 v217, v217
	v_rcp_f32_e32 v218, v218
	v_rcp_f32_e32 v219, v219
	v_rcp_f32_e32 v220, v220
	v_rcp_f32_e32 v221, v221
	v_rcp_f32_e32 v222, v222
	v_rcp_f32_e32 v223, v223
	v_lshlrev_b32_e32 v242, 16, v182
	v_and_b32_e32 v243, 0xffff0000, v182
	v_lshlrev_b32_e32 v244, 16, v183
	v_and_b32_e32 v245, 0xffff0000, v183
	v_lshlrev_b32_e32 v246, 16, v184
	v_and_b32_e32 v247, 0xffff0000, v184
	v_lshlrev_b32_e32 v248, 16, v185
	v_and_b32_e32 v249, 0xffff0000, v185
	v_pk_mul_f32 v[242:243], v[242:243], s[86:87] op_sel_hi:[1,0]
	v_pk_mul_f32 v[244:245], v[244:245], s[86:87] op_sel_hi:[1,0]
	v_pk_mul_f32 v[246:247], v[246:247], s[86:87] op_sel_hi:[1,0]
	v_pk_mul_f32 v[248:249], v[248:249], s[86:87] op_sel_hi:[1,0]
	v_exp_f32_e32 v242, v242
	v_exp_f32_e32 v243, v243
	v_exp_f32_e32 v244, v244
	v_exp_f32_e32 v245, v245
	v_exp_f32_e32 v246, v246
	v_exp_f32_e32 v247, v247
	v_exp_f32_e32 v248, v248
	v_exp_f32_e32 v249, v249
	v_pk_add_f32 v[242:243], v[242:243], 1.0 op_sel_hi:[1,0]
	v_pk_add_f32 v[244:245], v[244:245], 1.0 op_sel_hi:[1,0]
	v_pk_add_f32 v[246:247], v[246:247], 1.0 op_sel_hi:[1,0]
	v_pk_add_f32 v[248:249], v[248:249], 1.0 op_sel_hi:[1,0]
	v_pk_mul_f32 v[216:217], v[216:217], v[242:243]
	v_pk_mul_f32 v[218:219], v[218:219], v[244:245]
	v_pk_mul_f32 v[220:221], v[220:221], v[246:247]
	v_pk_mul_f32 v[222:223], v[222:223], v[248:249]
	v_pk_mul_f32 v[102:103], v[102:103], v[216:217]
	v_pk_mul_f32 v[104:105], v[104:105], v[218:219]
	v_pk_mul_f32 v[98:99], v[98:99], v[220:221]
	v_pk_mul_f32 v[100:101], v[100:101], v[222:223]
	v_lshlrev_b32_e32 v216, 16, v186
	v_and_b32_e32 v217, 0xffff0000, v186
	v_lshlrev_b32_e32 v218, 16, v187
	v_and_b32_e32 v219, 0xffff0000, v187
	v_lshlrev_b32_e32 v220, 16, v188
	v_and_b32_e32 v221, 0xffff0000, v188
	v_lshlrev_b32_e32 v222, 16, v189
	v_and_b32_e32 v223, 0xffff0000, v189
	v_pk_mul_f32 v[216:217], v[216:217], s[86:87] op_sel_hi:[1,0]
	v_pk_mul_f32 v[218:219], v[218:219], s[86:87] op_sel_hi:[1,0]
	v_pk_mul_f32 v[220:221], v[220:221], s[86:87] op_sel_hi:[1,0]
	v_pk_mul_f32 v[222:223], v[222:223], s[86:87] op_sel_hi:[1,0]
	v_exp_f32_e32 v216, v216
	v_exp_f32_e32 v217, v217
	v_exp_f32_e32 v218, v218
	v_exp_f32_e32 v219, v219
	v_exp_f32_e32 v220, v220
	v_exp_f32_e32 v221, v221
	v_exp_f32_e32 v222, v222
	v_exp_f32_e32 v223, v223
	v_pk_add_f32 v[216:217], v[216:217], 1.0 op_sel_hi:[1,0]
	v_pk_add_f32 v[218:219], v[218:219], 1.0 op_sel_hi:[1,0]
	v_pk_add_f32 v[220:221], v[220:221], 1.0 op_sel_hi:[1,0]
	v_pk_add_f32 v[222:223], v[222:223], 1.0 op_sel_hi:[1,0]
	v_rcp_f32_e32 v216, v216
	v_rcp_f32_e32 v217, v217
	v_rcp_f32_e32 v218, v218
	v_rcp_f32_e32 v219, v219
	v_rcp_f32_e32 v220, v220
	v_rcp_f32_e32 v221, v221
	v_rcp_f32_e32 v222, v222
	v_rcp_f32_e32 v223, v223
	v_lshlrev_b32_e32 v242, 16, v190
	v_and_b32_e32 v243, 0xffff0000, v190
	v_lshlrev_b32_e32 v244, 16, v191
	v_and_b32_e32 v245, 0xffff0000, v191
	v_lshlrev_b32_e32 v246, 16, v192
	v_and_b32_e32 v247, 0xffff0000, v192
	v_lshlrev_b32_e32 v248, 16, v193
	v_and_b32_e32 v249, 0xffff0000, v193
	v_pk_mul_f32 v[242:243], v[242:243], s[86:87] op_sel_hi:[1,0]
	v_pk_mul_f32 v[244:245], v[244:245], s[86:87] op_sel_hi:[1,0]
	v_pk_mul_f32 v[246:247], v[246:247], s[86:87] op_sel_hi:[1,0]
	v_pk_mul_f32 v[248:249], v[248:249], s[86:87] op_sel_hi:[1,0]
	v_exp_f32_e32 v242, v242
	v_exp_f32_e32 v243, v243
	v_exp_f32_e32 v244, v244
	v_exp_f32_e32 v245, v245
	v_exp_f32_e32 v246, v246
	v_exp_f32_e32 v247, v247
	v_exp_f32_e32 v248, v248
	v_exp_f32_e32 v249, v249
	v_pk_add_f32 v[242:243], v[242:243], 1.0 op_sel_hi:[1,0]
	v_pk_add_f32 v[244:245], v[244:245], 1.0 op_sel_hi:[1,0]
	v_pk_add_f32 v[246:247], v[246:247], 1.0 op_sel_hi:[1,0]
	v_pk_add_f32 v[248:249], v[248:249], 1.0 op_sel_hi:[1,0]
	v_pk_mul_f32 v[216:217], v[216:217], v[242:243]
	v_pk_mul_f32 v[218:219], v[218:219], v[244:245]
	v_pk_mul_f32 v[220:221], v[220:221], v[246:247]
	v_pk_mul_f32 v[222:223], v[222:223], v[248:249]
	v_pk_mul_f32 v[70:71], v[70:71], v[216:217]
	v_pk_mul_f32 v[72:73], v[72:73], v[218:219]
	v_pk_mul_f32 v[66:67], v[66:67], v[220:221]
	v_pk_mul_f32 v[68:69], v[68:69], v[222:223]
	s_add_u32 s28, s20, 0x478000
	s_addc_u32 s29, s21, 0
	global_load_dwordx4 v[178:181], v253, s[28:29]
	global_load_dwordx4 v[182:185], v254, s[28:29]
	global_load_dwordx4 v[186:189], v253, s[28:29] offset:256
	global_load_dwordx4 v[190:193], v254, s[28:29] offset:256
	s_waitcnt vmcnt(12)
	v_lshlrev_b32_e32 v216, 16, v130
	v_and_b32_e32 v217, 0xffff0000, v130
	v_lshlrev_b32_e32 v218, 16, v131
	v_and_b32_e32 v219, 0xffff0000, v131
	v_lshlrev_b32_e32 v220, 16, v132
	v_and_b32_e32 v221, 0xffff0000, v132
	v_lshlrev_b32_e32 v222, 16, v133
	v_and_b32_e32 v223, 0xffff0000, v133
	v_pk_mul_f32 v[216:217], v[216:217], s[86:87] op_sel_hi:[1,0]
	v_pk_mul_f32 v[218:219], v[218:219], s[86:87] op_sel_hi:[1,0]
	v_pk_mul_f32 v[220:221], v[220:221], s[86:87] op_sel_hi:[1,0]
	v_pk_mul_f32 v[222:223], v[222:223], s[86:87] op_sel_hi:[1,0]
	v_exp_f32_e32 v216, v216
	v_exp_f32_e32 v217, v217
	v_exp_f32_e32 v218, v218
	v_exp_f32_e32 v219, v219
	v_exp_f32_e32 v220, v220
	v_exp_f32_e32 v221, v221
	v_exp_f32_e32 v222, v222
	v_exp_f32_e32 v223, v223
	v_pk_add_f32 v[216:217], v[216:217], 1.0 op_sel_hi:[1,0]
	v_pk_add_f32 v[218:219], v[218:219], 1.0 op_sel_hi:[1,0]
	v_pk_add_f32 v[220:221], v[220:221], 1.0 op_sel_hi:[1,0]
	v_pk_add_f32 v[222:223], v[222:223], 1.0 op_sel_hi:[1,0]
	v_rcp_f32_e32 v216, v216
	v_rcp_f32_e32 v217, v217
	v_rcp_f32_e32 v218, v218
	v_rcp_f32_e32 v219, v219
	v_rcp_f32_e32 v220, v220
	v_rcp_f32_e32 v221, v221
	v_rcp_f32_e32 v222, v222
	v_rcp_f32_e32 v223, v223
	v_lshlrev_b32_e32 v242, 16, v134
	v_and_b32_e32 v243, 0xffff0000, v134
	v_lshlrev_b32_e32 v244, 16, v135
	v_and_b32_e32 v245, 0xffff0000, v135
	v_lshlrev_b32_e32 v246, 16, v136
	v_and_b32_e32 v247, 0xffff0000, v136
	v_lshlrev_b32_e32 v248, 16, v137
	v_and_b32_e32 v249, 0xffff0000, v137
	v_pk_mul_f32 v[242:243], v[242:243], s[86:87] op_sel_hi:[1,0]
	v_pk_mul_f32 v[244:245], v[244:245], s[86:87] op_sel_hi:[1,0]
	v_pk_mul_f32 v[246:247], v[246:247], s[86:87] op_sel_hi:[1,0]
	v_pk_mul_f32 v[248:249], v[248:249], s[86:87] op_sel_hi:[1,0]
	v_exp_f32_e32 v242, v242
	v_exp_f32_e32 v243, v243
	v_exp_f32_e32 v244, v244
	v_exp_f32_e32 v245, v245
	v_exp_f32_e32 v246, v246
	v_exp_f32_e32 v247, v247
	v_exp_f32_e32 v248, v248
	v_exp_f32_e32 v249, v249
	v_pk_add_f32 v[242:243], v[242:243], 1.0 op_sel_hi:[1,0]
	v_pk_add_f32 v[244:245], v[244:245], 1.0 op_sel_hi:[1,0]
	v_pk_add_f32 v[246:247], v[246:247], 1.0 op_sel_hi:[1,0]
	v_pk_add_f32 v[248:249], v[248:249], 1.0 op_sel_hi:[1,0]
	v_pk_mul_f32 v[216:217], v[216:217], v[242:243]
	v_pk_mul_f32 v[218:219], v[218:219], v[244:245]
	v_pk_mul_f32 v[220:221], v[220:221], v[246:247]
	v_pk_mul_f32 v[222:223], v[222:223], v[248:249]
	v_pk_mul_f32 v[62:63], v[62:63], v[216:217]
	v_pk_mul_f32 v[64:65], v[64:65], v[218:219]
	v_pk_mul_f32 v[58:59], v[58:59], v[220:221]
	v_pk_mul_f32 v[60:61], v[60:61], v[222:223]
	v_lshlrev_b32_e32 v216, 16, v138
	v_and_b32_e32 v217, 0xffff0000, v138
	v_lshlrev_b32_e32 v218, 16, v139
	v_and_b32_e32 v219, 0xffff0000, v139
	v_lshlrev_b32_e32 v220, 16, v140
	v_and_b32_e32 v221, 0xffff0000, v140
	v_lshlrev_b32_e32 v222, 16, v141
	v_and_b32_e32 v223, 0xffff0000, v141
	v_pk_mul_f32 v[216:217], v[216:217], s[86:87] op_sel_hi:[1,0]
	v_pk_mul_f32 v[218:219], v[218:219], s[86:87] op_sel_hi:[1,0]
	v_pk_mul_f32 v[220:221], v[220:221], s[86:87] op_sel_hi:[1,0]
	v_pk_mul_f32 v[222:223], v[222:223], s[86:87] op_sel_hi:[1,0]
	v_exp_f32_e32 v216, v216
	v_exp_f32_e32 v217, v217
	v_exp_f32_e32 v218, v218
	v_exp_f32_e32 v219, v219
	v_exp_f32_e32 v220, v220
	v_exp_f32_e32 v221, v221
	v_exp_f32_e32 v222, v222
	v_exp_f32_e32 v223, v223
	v_pk_add_f32 v[216:217], v[216:217], 1.0 op_sel_hi:[1,0]
	v_pk_add_f32 v[218:219], v[218:219], 1.0 op_sel_hi:[1,0]
	v_pk_add_f32 v[220:221], v[220:221], 1.0 op_sel_hi:[1,0]
	v_pk_add_f32 v[222:223], v[222:223], 1.0 op_sel_hi:[1,0]
	v_rcp_f32_e32 v216, v216
	v_rcp_f32_e32 v217, v217
	v_rcp_f32_e32 v218, v218
	v_rcp_f32_e32 v219, v219
	v_rcp_f32_e32 v220, v220
	v_rcp_f32_e32 v221, v221
	v_rcp_f32_e32 v222, v222
	v_rcp_f32_e32 v223, v223
	v_lshlrev_b32_e32 v242, 16, v142
	v_and_b32_e32 v243, 0xffff0000, v142
	v_lshlrev_b32_e32 v244, 16, v143
	v_and_b32_e32 v245, 0xffff0000, v143
	v_lshlrev_b32_e32 v246, 16, v144
	v_and_b32_e32 v247, 0xffff0000, v144
	v_lshlrev_b32_e32 v248, 16, v145
	v_and_b32_e32 v249, 0xffff0000, v145
	v_pk_mul_f32 v[242:243], v[242:243], s[86:87] op_sel_hi:[1,0]
	v_pk_mul_f32 v[244:245], v[244:245], s[86:87] op_sel_hi:[1,0]
	v_pk_mul_f32 v[246:247], v[246:247], s[86:87] op_sel_hi:[1,0]
	v_pk_mul_f32 v[248:249], v[248:249], s[86:87] op_sel_hi:[1,0]
	v_exp_f32_e32 v242, v242
	v_exp_f32_e32 v243, v243
	v_exp_f32_e32 v244, v244
	v_exp_f32_e32 v245, v245
	v_exp_f32_e32 v246, v246
	v_exp_f32_e32 v247, v247
	v_exp_f32_e32 v248, v248
	v_exp_f32_e32 v249, v249
	v_pk_add_f32 v[242:243], v[242:243], 1.0 op_sel_hi:[1,0]
	v_pk_add_f32 v[244:245], v[244:245], 1.0 op_sel_hi:[1,0]
	v_pk_add_f32 v[246:247], v[246:247], 1.0 op_sel_hi:[1,0]
	v_pk_add_f32 v[248:249], v[248:249], 1.0 op_sel_hi:[1,0]
	v_pk_mul_f32 v[216:217], v[216:217], v[242:243]
	v_pk_mul_f32 v[218:219], v[218:219], v[244:245]
	v_pk_mul_f32 v[220:221], v[220:221], v[246:247]
	v_pk_mul_f32 v[222:223], v[222:223], v[248:249]
	v_pk_mul_f32 v[30:31], v[30:31], v[216:217]
	v_pk_mul_f32 v[32:33], v[32:33], v[218:219]
	v_pk_mul_f32 v[26:27], v[26:27], v[220:221]
	v_pk_mul_f32 v[28:29], v[28:29], v[222:223]
	s_waitcnt vmcnt(8)
	v_lshlrev_b32_e32 v216, 16, v146
	v_and_b32_e32 v217, 0xffff0000, v146
	v_lshlrev_b32_e32 v218, 16, v147
	v_and_b32_e32 v219, 0xffff0000, v147
	v_lshlrev_b32_e32 v220, 16, v148
	v_and_b32_e32 v221, 0xffff0000, v148
	v_lshlrev_b32_e32 v222, 16, v149
	v_and_b32_e32 v223, 0xffff0000, v149
	v_pk_mul_f32 v[216:217], v[216:217], s[86:87] op_sel_hi:[1,0]
	v_pk_mul_f32 v[218:219], v[218:219], s[86:87] op_sel_hi:[1,0]
	v_pk_mul_f32 v[220:221], v[220:221], s[86:87] op_sel_hi:[1,0]
	v_pk_mul_f32 v[222:223], v[222:223], s[86:87] op_sel_hi:[1,0]
	v_exp_f32_e32 v216, v216
	v_exp_f32_e32 v217, v217
	v_exp_f32_e32 v218, v218
	v_exp_f32_e32 v219, v219
	v_exp_f32_e32 v220, v220
	v_exp_f32_e32 v221, v221
	v_exp_f32_e32 v222, v222
	v_exp_f32_e32 v223, v223
	v_pk_add_f32 v[216:217], v[216:217], 1.0 op_sel_hi:[1,0]
	v_pk_add_f32 v[218:219], v[218:219], 1.0 op_sel_hi:[1,0]
	v_pk_add_f32 v[220:221], v[220:221], 1.0 op_sel_hi:[1,0]
	v_pk_add_f32 v[222:223], v[222:223], 1.0 op_sel_hi:[1,0]
	v_rcp_f32_e32 v216, v216
	v_rcp_f32_e32 v217, v217
	v_rcp_f32_e32 v218, v218
	v_rcp_f32_e32 v219, v219
	v_rcp_f32_e32 v220, v220
	v_rcp_f32_e32 v221, v221
	v_rcp_f32_e32 v222, v222
	v_rcp_f32_e32 v223, v223
	v_lshlrev_b32_e32 v242, 16, v150
	v_and_b32_e32 v243, 0xffff0000, v150
	v_lshlrev_b32_e32 v244, 16, v151
	v_and_b32_e32 v245, 0xffff0000, v151
	v_lshlrev_b32_e32 v246, 16, v152
	v_and_b32_e32 v247, 0xffff0000, v152
	v_lshlrev_b32_e32 v248, 16, v153
	v_and_b32_e32 v249, 0xffff0000, v153
	v_pk_mul_f32 v[242:243], v[242:243], s[86:87] op_sel_hi:[1,0]
	v_pk_mul_f32 v[244:245], v[244:245], s[86:87] op_sel_hi:[1,0]
	v_pk_mul_f32 v[246:247], v[246:247], s[86:87] op_sel_hi:[1,0]
	v_pk_mul_f32 v[248:249], v[248:249], s[86:87] op_sel_hi:[1,0]
	v_exp_f32_e32 v242, v242
	v_exp_f32_e32 v243, v243
	v_exp_f32_e32 v244, v244
	v_exp_f32_e32 v245, v245
	v_exp_f32_e32 v246, v246
	v_exp_f32_e32 v247, v247
	v_exp_f32_e32 v248, v248
	v_exp_f32_e32 v249, v249
	v_pk_add_f32 v[242:243], v[242:243], 1.0 op_sel_hi:[1,0]
	v_pk_add_f32 v[244:245], v[244:245], 1.0 op_sel_hi:[1,0]
	v_pk_add_f32 v[246:247], v[246:247], 1.0 op_sel_hi:[1,0]
	v_pk_add_f32 v[248:249], v[248:249], 1.0 op_sel_hi:[1,0]
	v_pk_mul_f32 v[216:217], v[216:217], v[242:243]
	v_pk_mul_f32 v[218:219], v[218:219], v[244:245]
	v_pk_mul_f32 v[220:221], v[220:221], v[246:247]
	v_pk_mul_f32 v[222:223], v[222:223], v[248:249]
	v_pk_mul_f32 v[54:55], v[54:55], v[216:217]
	v_pk_mul_f32 v[56:57], v[56:57], v[218:219]
	v_pk_mul_f32 v[50:51], v[50:51], v[220:221]
	v_pk_mul_f32 v[52:53], v[52:53], v[222:223]
	v_lshlrev_b32_e32 v216, 16, v154
	v_and_b32_e32 v217, 0xffff0000, v154
	v_lshlrev_b32_e32 v218, 16, v155
	v_and_b32_e32 v219, 0xffff0000, v155
	v_lshlrev_b32_e32 v220, 16, v156
	v_and_b32_e32 v221, 0xffff0000, v156
	v_lshlrev_b32_e32 v222, 16, v157
	v_and_b32_e32 v223, 0xffff0000, v157
	v_pk_mul_f32 v[216:217], v[216:217], s[86:87] op_sel_hi:[1,0]
	v_pk_mul_f32 v[218:219], v[218:219], s[86:87] op_sel_hi:[1,0]
	v_pk_mul_f32 v[220:221], v[220:221], s[86:87] op_sel_hi:[1,0]
	v_pk_mul_f32 v[222:223], v[222:223], s[86:87] op_sel_hi:[1,0]
	v_exp_f32_e32 v216, v216
	v_exp_f32_e32 v217, v217
	v_exp_f32_e32 v218, v218
	v_exp_f32_e32 v219, v219
	v_exp_f32_e32 v220, v220
	v_exp_f32_e32 v221, v221
	v_exp_f32_e32 v222, v222
	v_exp_f32_e32 v223, v223
	v_pk_add_f32 v[216:217], v[216:217], 1.0 op_sel_hi:[1,0]
	v_pk_add_f32 v[218:219], v[218:219], 1.0 op_sel_hi:[1,0]
	v_pk_add_f32 v[220:221], v[220:221], 1.0 op_sel_hi:[1,0]
	v_pk_add_f32 v[222:223], v[222:223], 1.0 op_sel_hi:[1,0]
	v_rcp_f32_e32 v216, v216
	v_rcp_f32_e32 v217, v217
	v_rcp_f32_e32 v218, v218
	v_rcp_f32_e32 v219, v219
	v_rcp_f32_e32 v220, v220
	v_rcp_f32_e32 v221, v221
	v_rcp_f32_e32 v222, v222
	v_rcp_f32_e32 v223, v223
	v_lshlrev_b32_e32 v242, 16, v158
	v_and_b32_e32 v243, 0xffff0000, v158
	v_lshlrev_b32_e32 v244, 16, v159
	v_and_b32_e32 v245, 0xffff0000, v159
	v_lshlrev_b32_e32 v246, 16, v160
	v_and_b32_e32 v247, 0xffff0000, v160
	v_lshlrev_b32_e32 v248, 16, v161
	v_and_b32_e32 v249, 0xffff0000, v161
	v_pk_mul_f32 v[242:243], v[242:243], s[86:87] op_sel_hi:[1,0]
	v_pk_mul_f32 v[244:245], v[244:245], s[86:87] op_sel_hi:[1,0]
	v_pk_mul_f32 v[246:247], v[246:247], s[86:87] op_sel_hi:[1,0]
	v_pk_mul_f32 v[248:249], v[248:249], s[86:87] op_sel_hi:[1,0]
	v_exp_f32_e32 v242, v242
	v_exp_f32_e32 v243, v243
	v_exp_f32_e32 v244, v244
	v_exp_f32_e32 v245, v245
	v_exp_f32_e32 v246, v246
	v_exp_f32_e32 v247, v247
	v_exp_f32_e32 v248, v248
	v_exp_f32_e32 v249, v249
	v_pk_add_f32 v[242:243], v[242:243], 1.0 op_sel_hi:[1,0]
	v_pk_add_f32 v[244:245], v[244:245], 1.0 op_sel_hi:[1,0]
	v_pk_add_f32 v[246:247], v[246:247], 1.0 op_sel_hi:[1,0]
	v_pk_add_f32 v[248:249], v[248:249], 1.0 op_sel_hi:[1,0]
	v_pk_mul_f32 v[216:217], v[216:217], v[242:243]
	v_pk_mul_f32 v[218:219], v[218:219], v[244:245]
	v_pk_mul_f32 v[220:221], v[220:221], v[246:247]
	v_pk_mul_f32 v[222:223], v[222:223], v[248:249]
	v_pk_mul_f32 v[22:23], v[22:23], v[216:217]
	v_pk_mul_f32 v[24:25], v[24:25], v[218:219]
	v_pk_mul_f32 v[18:19], v[18:19], v[220:221]
	v_pk_mul_f32 v[20:21], v[20:21], v[222:223]
	s_waitcnt vmcnt(4)
	v_lshlrev_b32_e32 v216, 16, v162
	v_and_b32_e32 v217, 0xffff0000, v162
	v_lshlrev_b32_e32 v218, 16, v163
	v_and_b32_e32 v219, 0xffff0000, v163
	v_lshlrev_b32_e32 v220, 16, v164
	v_and_b32_e32 v221, 0xffff0000, v164
	v_lshlrev_b32_e32 v222, 16, v165
	v_and_b32_e32 v223, 0xffff0000, v165
	v_pk_mul_f32 v[216:217], v[216:217], s[86:87] op_sel_hi:[1,0]
	v_pk_mul_f32 v[218:219], v[218:219], s[86:87] op_sel_hi:[1,0]
	v_pk_mul_f32 v[220:221], v[220:221], s[86:87] op_sel_hi:[1,0]
	v_pk_mul_f32 v[222:223], v[222:223], s[86:87] op_sel_hi:[1,0]
	v_exp_f32_e32 v216, v216
	v_exp_f32_e32 v217, v217
	v_exp_f32_e32 v218, v218
	v_exp_f32_e32 v219, v219
	v_exp_f32_e32 v220, v220
	v_exp_f32_e32 v221, v221
	v_exp_f32_e32 v222, v222
	v_exp_f32_e32 v223, v223
	v_pk_add_f32 v[216:217], v[216:217], 1.0 op_sel_hi:[1,0]
	v_pk_add_f32 v[218:219], v[218:219], 1.0 op_sel_hi:[1,0]
	v_pk_add_f32 v[220:221], v[220:221], 1.0 op_sel_hi:[1,0]
	v_pk_add_f32 v[222:223], v[222:223], 1.0 op_sel_hi:[1,0]
	v_rcp_f32_e32 v216, v216
	v_rcp_f32_e32 v217, v217
	v_rcp_f32_e32 v218, v218
	v_rcp_f32_e32 v219, v219
	v_rcp_f32_e32 v220, v220
	v_rcp_f32_e32 v221, v221
	v_rcp_f32_e32 v222, v222
	v_rcp_f32_e32 v223, v223
	v_lshlrev_b32_e32 v242, 16, v166
	v_and_b32_e32 v243, 0xffff0000, v166
	v_lshlrev_b32_e32 v244, 16, v167
	v_and_b32_e32 v245, 0xffff0000, v167
	v_lshlrev_b32_e32 v246, 16, v168
	v_and_b32_e32 v247, 0xffff0000, v168
	v_lshlrev_b32_e32 v248, 16, v169
	v_and_b32_e32 v249, 0xffff0000, v169
	v_pk_mul_f32 v[242:243], v[242:243], s[86:87] op_sel_hi:[1,0]
	v_pk_mul_f32 v[244:245], v[244:245], s[86:87] op_sel_hi:[1,0]
	v_pk_mul_f32 v[246:247], v[246:247], s[86:87] op_sel_hi:[1,0]
	v_pk_mul_f32 v[248:249], v[248:249], s[86:87] op_sel_hi:[1,0]
	v_exp_f32_e32 v242, v242
	v_exp_f32_e32 v243, v243
	v_exp_f32_e32 v244, v244
	v_exp_f32_e32 v245, v245
	v_exp_f32_e32 v246, v246
	v_exp_f32_e32 v247, v247
	v_exp_f32_e32 v248, v248
	v_exp_f32_e32 v249, v249
	v_pk_add_f32 v[242:243], v[242:243], 1.0 op_sel_hi:[1,0]
	v_pk_add_f32 v[244:245], v[244:245], 1.0 op_sel_hi:[1,0]
	v_pk_add_f32 v[246:247], v[246:247], 1.0 op_sel_hi:[1,0]
	v_pk_add_f32 v[248:249], v[248:249], 1.0 op_sel_hi:[1,0]
	v_pk_mul_f32 v[216:217], v[216:217], v[242:243]
	v_pk_mul_f32 v[218:219], v[218:219], v[244:245]
	v_pk_mul_f32 v[220:221], v[220:221], v[246:247]
	v_pk_mul_f32 v[222:223], v[222:223], v[248:249]
	v_pk_mul_f32 v[46:47], v[46:47], v[216:217]
	v_pk_mul_f32 v[48:49], v[48:49], v[218:219]
	v_pk_mul_f32 v[42:43], v[42:43], v[220:221]
	v_pk_mul_f32 v[44:45], v[44:45], v[222:223]
	v_lshlrev_b32_e32 v216, 16, v170
	v_and_b32_e32 v217, 0xffff0000, v170
	v_lshlrev_b32_e32 v218, 16, v171
	v_and_b32_e32 v219, 0xffff0000, v171
	v_lshlrev_b32_e32 v220, 16, v172
	v_and_b32_e32 v221, 0xffff0000, v172
	v_lshlrev_b32_e32 v222, 16, v173
	v_and_b32_e32 v223, 0xffff0000, v173
	v_pk_mul_f32 v[216:217], v[216:217], s[86:87] op_sel_hi:[1,0]
	v_pk_mul_f32 v[218:219], v[218:219], s[86:87] op_sel_hi:[1,0]
	v_pk_mul_f32 v[220:221], v[220:221], s[86:87] op_sel_hi:[1,0]
	v_pk_mul_f32 v[222:223], v[222:223], s[86:87] op_sel_hi:[1,0]
	v_exp_f32_e32 v216, v216
	v_exp_f32_e32 v217, v217
	v_exp_f32_e32 v218, v218
	v_exp_f32_e32 v219, v219
	v_exp_f32_e32 v220, v220
	v_exp_f32_e32 v221, v221
	v_exp_f32_e32 v222, v222
	v_exp_f32_e32 v223, v223
	v_pk_add_f32 v[216:217], v[216:217], 1.0 op_sel_hi:[1,0]
	v_pk_add_f32 v[218:219], v[218:219], 1.0 op_sel_hi:[1,0]
	v_pk_add_f32 v[220:221], v[220:221], 1.0 op_sel_hi:[1,0]
	v_pk_add_f32 v[222:223], v[222:223], 1.0 op_sel_hi:[1,0]
	v_rcp_f32_e32 v216, v216
	v_rcp_f32_e32 v217, v217
	v_rcp_f32_e32 v218, v218
	v_rcp_f32_e32 v219, v219
	v_rcp_f32_e32 v220, v220
	v_rcp_f32_e32 v221, v221
	v_rcp_f32_e32 v222, v222
	v_rcp_f32_e32 v223, v223
	v_lshlrev_b32_e32 v242, 16, v174
	v_and_b32_e32 v243, 0xffff0000, v174
	v_lshlrev_b32_e32 v244, 16, v175
	v_and_b32_e32 v245, 0xffff0000, v175
	v_lshlrev_b32_e32 v246, 16, v176
	v_and_b32_e32 v247, 0xffff0000, v176
	v_lshlrev_b32_e32 v248, 16, v177
	v_and_b32_e32 v249, 0xffff0000, v177
	v_pk_mul_f32 v[242:243], v[242:243], s[86:87] op_sel_hi:[1,0]
	v_pk_mul_f32 v[244:245], v[244:245], s[86:87] op_sel_hi:[1,0]
	v_pk_mul_f32 v[246:247], v[246:247], s[86:87] op_sel_hi:[1,0]
	v_pk_mul_f32 v[248:249], v[248:249], s[86:87] op_sel_hi:[1,0]
	v_exp_f32_e32 v242, v242
	v_exp_f32_e32 v243, v243
	v_exp_f32_e32 v244, v244
	v_exp_f32_e32 v245, v245
	v_exp_f32_e32 v246, v246
	v_exp_f32_e32 v247, v247
	v_exp_f32_e32 v248, v248
	v_exp_f32_e32 v249, v249
	v_pk_add_f32 v[242:243], v[242:243], 1.0 op_sel_hi:[1,0]
	v_pk_add_f32 v[244:245], v[244:245], 1.0 op_sel_hi:[1,0]
	v_pk_add_f32 v[246:247], v[246:247], 1.0 op_sel_hi:[1,0]
	v_pk_add_f32 v[248:249], v[248:249], 1.0 op_sel_hi:[1,0]
	v_pk_mul_f32 v[216:217], v[216:217], v[242:243]
	v_pk_mul_f32 v[218:219], v[218:219], v[244:245]
	v_pk_mul_f32 v[220:221], v[220:221], v[246:247]
	v_pk_mul_f32 v[222:223], v[222:223], v[248:249]
	v_pk_mul_f32 v[14:15], v[14:15], v[216:217]
	v_pk_mul_f32 v[16:17], v[16:17], v[218:219]
	v_pk_mul_f32 v[10:11], v[10:11], v[220:221]
	v_pk_mul_f32 v[12:13], v[12:13], v[222:223]
	s_waitcnt vmcnt(0)
	v_lshlrev_b32_e32 v216, 16, v178
	v_and_b32_e32 v217, 0xffff0000, v178
	v_lshlrev_b32_e32 v218, 16, v179
	v_and_b32_e32 v219, 0xffff0000, v179
	v_lshlrev_b32_e32 v220, 16, v180
	v_and_b32_e32 v221, 0xffff0000, v180
	v_lshlrev_b32_e32 v222, 16, v181
	v_and_b32_e32 v223, 0xffff0000, v181
	v_pk_mul_f32 v[216:217], v[216:217], s[86:87] op_sel_hi:[1,0]
	v_pk_mul_f32 v[218:219], v[218:219], s[86:87] op_sel_hi:[1,0]
	v_pk_mul_f32 v[220:221], v[220:221], s[86:87] op_sel_hi:[1,0]
	v_pk_mul_f32 v[222:223], v[222:223], s[86:87] op_sel_hi:[1,0]
	v_exp_f32_e32 v216, v216
	v_exp_f32_e32 v217, v217
	v_exp_f32_e32 v218, v218
	v_exp_f32_e32 v219, v219
	v_exp_f32_e32 v220, v220
	v_exp_f32_e32 v221, v221
	v_exp_f32_e32 v222, v222
	v_exp_f32_e32 v223, v223
	v_pk_add_f32 v[216:217], v[216:217], 1.0 op_sel_hi:[1,0]
	v_pk_add_f32 v[218:219], v[218:219], 1.0 op_sel_hi:[1,0]
	v_pk_add_f32 v[220:221], v[220:221], 1.0 op_sel_hi:[1,0]
	v_pk_add_f32 v[222:223], v[222:223], 1.0 op_sel_hi:[1,0]
	v_rcp_f32_e32 v216, v216
	v_rcp_f32_e32 v217, v217
	v_rcp_f32_e32 v218, v218
	v_rcp_f32_e32 v219, v219
	v_rcp_f32_e32 v220, v220
	v_rcp_f32_e32 v221, v221
	v_rcp_f32_e32 v222, v222
	v_rcp_f32_e32 v223, v223
	v_lshlrev_b32_e32 v242, 16, v182
	v_and_b32_e32 v243, 0xffff0000, v182
	v_lshlrev_b32_e32 v244, 16, v183
	v_and_b32_e32 v245, 0xffff0000, v183
	v_lshlrev_b32_e32 v246, 16, v184
	v_and_b32_e32 v247, 0xffff0000, v184
	v_lshlrev_b32_e32 v248, 16, v185
	v_and_b32_e32 v249, 0xffff0000, v185
	v_pk_mul_f32 v[242:243], v[242:243], s[86:87] op_sel_hi:[1,0]
	v_pk_mul_f32 v[244:245], v[244:245], s[86:87] op_sel_hi:[1,0]
	v_pk_mul_f32 v[246:247], v[246:247], s[86:87] op_sel_hi:[1,0]
	v_pk_mul_f32 v[248:249], v[248:249], s[86:87] op_sel_hi:[1,0]
	v_exp_f32_e32 v242, v242
	v_exp_f32_e32 v243, v243
	v_exp_f32_e32 v244, v244
	v_exp_f32_e32 v245, v245
	v_exp_f32_e32 v246, v246
	v_exp_f32_e32 v247, v247
	v_exp_f32_e32 v248, v248
	v_exp_f32_e32 v249, v249
	v_pk_add_f32 v[242:243], v[242:243], 1.0 op_sel_hi:[1,0]
	v_pk_add_f32 v[244:245], v[244:245], 1.0 op_sel_hi:[1,0]
	v_pk_add_f32 v[246:247], v[246:247], 1.0 op_sel_hi:[1,0]
	v_pk_add_f32 v[248:249], v[248:249], 1.0 op_sel_hi:[1,0]
	v_pk_mul_f32 v[216:217], v[216:217], v[242:243]
	v_pk_mul_f32 v[218:219], v[218:219], v[244:245]
	v_pk_mul_f32 v[220:221], v[220:221], v[246:247]
	v_pk_mul_f32 v[222:223], v[222:223], v[248:249]
	v_pk_mul_f32 v[38:39], v[38:39], v[216:217]
	v_pk_mul_f32 v[40:41], v[40:41], v[218:219]
	v_pk_mul_f32 v[34:35], v[34:35], v[220:221]
	v_pk_mul_f32 v[36:37], v[36:37], v[222:223]
	v_lshlrev_b32_e32 v216, 16, v186
	v_and_b32_e32 v217, 0xffff0000, v186
	v_lshlrev_b32_e32 v218, 16, v187
	v_and_b32_e32 v219, 0xffff0000, v187
	v_lshlrev_b32_e32 v220, 16, v188
	v_and_b32_e32 v221, 0xffff0000, v188
	v_lshlrev_b32_e32 v222, 16, v189
	v_and_b32_e32 v223, 0xffff0000, v189
	v_pk_mul_f32 v[216:217], v[216:217], s[86:87] op_sel_hi:[1,0]
	v_pk_mul_f32 v[218:219], v[218:219], s[86:87] op_sel_hi:[1,0]
	v_pk_mul_f32 v[220:221], v[220:221], s[86:87] op_sel_hi:[1,0]
	v_pk_mul_f32 v[222:223], v[222:223], s[86:87] op_sel_hi:[1,0]
	v_exp_f32_e32 v216, v216
	v_exp_f32_e32 v217, v217
	v_exp_f32_e32 v218, v218
	v_exp_f32_e32 v219, v219
	v_exp_f32_e32 v220, v220
	v_exp_f32_e32 v221, v221
	v_exp_f32_e32 v222, v222
	v_exp_f32_e32 v223, v223
	v_pk_add_f32 v[216:217], v[216:217], 1.0 op_sel_hi:[1,0]
	v_pk_add_f32 v[218:219], v[218:219], 1.0 op_sel_hi:[1,0]
	v_pk_add_f32 v[220:221], v[220:221], 1.0 op_sel_hi:[1,0]
	v_pk_add_f32 v[222:223], v[222:223], 1.0 op_sel_hi:[1,0]
	v_rcp_f32_e32 v216, v216
	v_rcp_f32_e32 v217, v217
	v_rcp_f32_e32 v218, v218
	v_rcp_f32_e32 v219, v219
	v_rcp_f32_e32 v220, v220
	v_rcp_f32_e32 v221, v221
	v_rcp_f32_e32 v222, v222
	v_rcp_f32_e32 v223, v223
	v_lshlrev_b32_e32 v242, 16, v190
	v_and_b32_e32 v243, 0xffff0000, v190
	v_lshlrev_b32_e32 v244, 16, v191
	v_and_b32_e32 v245, 0xffff0000, v191
	v_lshlrev_b32_e32 v246, 16, v192
	v_and_b32_e32 v247, 0xffff0000, v192
	v_lshlrev_b32_e32 v248, 16, v193
	v_and_b32_e32 v249, 0xffff0000, v193
	v_pk_mul_f32 v[242:243], v[242:243], s[86:87] op_sel_hi:[1,0]
	v_pk_mul_f32 v[244:245], v[244:245], s[86:87] op_sel_hi:[1,0]
	v_pk_mul_f32 v[246:247], v[246:247], s[86:87] op_sel_hi:[1,0]
	v_pk_mul_f32 v[248:249], v[248:249], s[86:87] op_sel_hi:[1,0]
	v_exp_f32_e32 v242, v242
	v_exp_f32_e32 v243, v243
	v_exp_f32_e32 v244, v244
	v_exp_f32_e32 v245, v245
	v_exp_f32_e32 v246, v246
	v_exp_f32_e32 v247, v247
	v_exp_f32_e32 v248, v248
	v_exp_f32_e32 v249, v249
	v_pk_add_f32 v[242:243], v[242:243], 1.0 op_sel_hi:[1,0]
	v_pk_add_f32 v[244:245], v[244:245], 1.0 op_sel_hi:[1,0]
	v_pk_add_f32 v[246:247], v[246:247], 1.0 op_sel_hi:[1,0]
	v_pk_add_f32 v[248:249], v[248:249], 1.0 op_sel_hi:[1,0]
	v_pk_mul_f32 v[216:217], v[216:217], v[242:243]
	v_pk_mul_f32 v[218:219], v[218:219], v[244:245]
	v_pk_mul_f32 v[220:221], v[220:221], v[246:247]
	v_pk_mul_f32 v[222:223], v[222:223], v[248:249]
	v_pk_mul_f32 v[6:7], v[6:7], v[216:217]
	v_pk_mul_f32 v[8:9], v[8:9], v[218:219]
	v_pk_mul_f32 v[2:3], v[2:3], v[220:221]
	v_pk_mul_f32 v[4:5], v[4:5], v[222:223]
	s_branch .Lem_done

.LBB0_504:
	v_add_u32_e32 v253, 0x10000, v163
	ds_read_b128 v[130:133], v253
	ds_read_b128 v[134:137], v253 offset:1024
	ds_read_b128 v[150:153], v253 offset:2048
	ds_read_b128 v[154:157], v253 offset:3072
	s_add_u32 s10, s52, 0xfff80080
	s_addc_u32 s11, s53, -1
	s_cmp_eq_u32 s29, 28
	s_cselect_b32 s11, s9, s11
	s_cselect_b32 s10, s8, s10
	s_cselect_b32 s55, s35, s7
	s_cselect_b32 s54, s34, s5
	s_add_i32 m0, s42, 0xc000
	ds_read_b128 v[158:161], v162
	ds_read_b128 v[166:169], v162 offset:1024
	ds_read_b128 v[170:173], v162 offset:2048
	ds_read_b128 v[174:177], v162 offset:3072
	ds_read_b128 v[178:181], v162 offset:4096
	ds_read_b128 v[182:185], v162 offset:5120
	ds_read_b128 v[186:189], v162 offset:6144
	ds_read_b128 v[190:193], v162 offset:7168
	global_load_lds_dwordx4 v146, s[52:53]
	s_add_i32 m0, s42, 0xe000
	s_nop 0
	global_load_lds_dwordx4 v148, s[52:53]
	s_waitcnt lgkmcnt(8)
	s_setprio 1
	s_barrier
	s_waitcnt lgkmcnt(0)
	v_mfma_f32_16x16x32_bf16 v[126:129], v[130:133], v[158:161], v[126:129]
	v_mfma_f32_16x16x32_bf16 v[122:125], v[150:153], v[158:161], v[122:125]
	v_mfma_f32_16x16x32_bf16 v[118:121], v[130:133], v[170:173], v[118:121]
	v_mfma_f32_16x16x32_bf16 v[114:117], v[150:153], v[170:173], v[114:117]
	v_mfma_f32_16x16x32_bf16 v[110:113], v[130:133], v[178:181], v[110:113]
	v_mfma_f32_16x16x32_bf16 v[106:109], v[150:153], v[178:181], v[106:109]
	v_mfma_f32_16x16x32_bf16 v[102:105], v[130:133], v[186:189], v[102:105]
	v_mfma_f32_16x16x32_bf16 v[98:101], v[150:153], v[186:189], v[98:101]
	v_mfma_f32_16x16x32_bf16 v[126:129], v[134:137], v[166:169], v[126:129]
	v_mfma_f32_16x16x32_bf16 v[122:125], v[154:157], v[166:169], v[122:125]
	v_mfma_f32_16x16x32_bf16 v[118:121], v[134:137], v[174:177], v[118:121]
	v_mfma_f32_16x16x32_bf16 v[114:117], v[154:157], v[174:177], v[114:117]
	v_mfma_f32_16x16x32_bf16 v[110:113], v[134:137], v[182:185], v[110:113]
	v_mfma_f32_16x16x32_bf16 v[106:109], v[154:157], v[182:185], v[106:109]
	v_mfma_f32_16x16x32_bf16 v[102:105], v[134:137], v[190:193], v[102:105]
	v_mfma_f32_16x16x32_bf16 v[98:101], v[154:157], v[190:193], v[98:101]
	s_barrier
	s_setprio 0
	s_mov_b32 m0, s41
	ds_read_b128 v[206:209], v253 offset:16384
	ds_read_b128 v[210:213], v253 offset:17408
	v_lshl_add_u64 v[222:223], s[54:55], 0, v[194:195]
	ds_read_b128 v[214:217], v253 offset:18432
	ds_read_b128 v[218:221], v253 offset:19456
	global_load_lds_dwordx4 v[222:223], off
	v_lshl_add_u64 v[224:225], s[54:55], 0, v[138:139]
	s_mov_b32 m0, s57
	s_nop 0
	global_load_lds_dwordx4 v[224:225], off
	s_setprio 1
	s_barrier
	s_waitcnt lgkmcnt(0)
	v_mfma_f32_16x16x32_bf16 v[62:65], v[206:209], v[158:161], v[62:65]
	v_mfma_f32_16x16x32_bf16 v[58:61], v[214:217], v[158:161], v[58:61]
	v_mfma_f32_16x16x32_bf16 v[54:57], v[206:209], v[170:173], v[54:57]
	v_mfma_f32_16x16x32_bf16 v[46:49], v[214:217], v[170:173], v[46:49]
	v_mfma_f32_16x16x32_bf16 v[50:53], v[206:209], v[178:181], v[50:53]
	v_mfma_f32_16x16x32_bf16 v[42:45], v[214:217], v[178:181], v[42:45]
	v_mfma_f32_16x16x32_bf16 v[38:41], v[206:209], v[186:189], v[38:41]
	v_mfma_f32_16x16x32_bf16 v[34:37], v[214:217], v[186:189], v[34:37]
	v_mfma_f32_16x16x32_bf16 v[62:65], v[210:213], v[166:169], v[62:65]
	v_mfma_f32_16x16x32_bf16 v[58:61], v[218:221], v[166:169], v[58:61]
	v_mfma_f32_16x16x32_bf16 v[54:57], v[210:213], v[174:177], v[54:57]
	v_mfma_f32_16x16x32_bf16 v[46:49], v[218:221], v[174:177], v[46:49]
	v_mfma_f32_16x16x32_bf16 v[50:53], v[210:213], v[182:185], v[50:53]
	v_mfma_f32_16x16x32_bf16 v[42:45], v[218:221], v[182:185], v[42:45]
	s_mov_b32 m0, s42
	v_mfma_f32_16x16x32_bf16 v[38:41], v[210:213], v[190:193], v[38:41]
	v_lshl_add_u64 v[226:227], s[10:11], 0, v[142:143]
	v_mfma_f32_16x16x32_bf16 v[34:37], v[218:221], v[190:193], v[34:37]
	s_barrier
	s_setprio 0
	ds_read_b128 v[158:161], v162 offset:16384
	ds_read_b128 v[166:169], v162 offset:17408
	ds_read_b128 v[170:173], v162 offset:18432
	ds_read_b128 v[174:177], v162 offset:19456
	ds_read_b128 v[178:181], v162 offset:20480
	ds_read_b128 v[182:185], v162 offset:21504
	ds_read_b128 v[186:189], v162 offset:22528
	ds_read_b128 v[190:193], v162 offset:23552
	global_load_lds_dwordx4 v[226:227], off
	v_lshl_add_u64 v[228:229], s[10:11], 0, v[140:141]
	s_mov_b32 m0, s58
	s_nop 0
	global_load_lds_dwordx4 v[228:229], off
	s_setprio 1
	s_barrier
	s_waitcnt lgkmcnt(0)
	v_mfma_f32_16x16x32_bf16 v[94:97], v[130:133], v[158:161], v[94:97]
	v_mfma_f32_16x16x32_bf16 v[90:93], v[150:153], v[158:161], v[90:93]
	v_mfma_f32_16x16x32_bf16 v[86:89], v[130:133], v[170:173], v[86:89]
	v_mfma_f32_16x16x32_bf16 v[82:85], v[150:153], v[170:173], v[82:85]
	v_mfma_f32_16x16x32_bf16 v[78:81], v[130:133], v[178:181], v[78:81]
	v_mfma_f32_16x16x32_bf16 v[74:77], v[150:153], v[178:181], v[74:77]
	v_mfma_f32_16x16x32_bf16 v[70:73], v[130:133], v[186:189], v[70:73]
	v_mfma_f32_16x16x32_bf16 v[66:69], v[150:153], v[186:189], v[66:69]
	v_mfma_f32_16x16x32_bf16 v[94:97], v[134:137], v[166:169], v[94:97]
	v_mfma_f32_16x16x32_bf16 v[90:93], v[154:157], v[166:169], v[90:93]
	v_mfma_f32_16x16x32_bf16 v[86:89], v[134:137], v[174:177], v[86:89]
	v_mfma_f32_16x16x32_bf16 v[82:85], v[154:157], v[174:177], v[82:85]
	v_mfma_f32_16x16x32_bf16 v[78:81], v[134:137], v[182:185], v[78:81]
	v_mfma_f32_16x16x32_bf16 v[74:77], v[154:157], v[182:185], v[74:77]
	v_mfma_f32_16x16x32_bf16 v[70:73], v[134:137], v[190:193], v[70:73]
	v_mfma_f32_16x16x32_bf16 v[66:69], v[154:157], v[190:193], v[66:69]
	s_barrier
	s_setprio 0
	s_add_u32 s86, s54, 0x80000
	s_addc_u32 s87, s55, 0
	s_mov_b32 m0, s59
	global_load_lds_dwordx4 v194, s[86:87]
	s_mov_b32 m0, s60
	s_nop 0
	global_load_lds_dwordx4 v138, s[86:87]
	s_waitcnt vmcnt(6)
	s_setprio 1
	s_barrier
	v_mfma_f32_16x16x32_bf16 v[30:33], v[206:209], v[158:161], v[30:33]
	v_mfma_f32_16x16x32_bf16 v[18:21], v[214:217], v[158:161], v[18:21]
	v_mfma_f32_16x16x32_bf16 v[26:29], v[206:209], v[170:173], v[26:29]
	v_mfma_f32_16x16x32_bf16 v[14:17], v[214:217], v[170:173], v[14:17]
	v_mfma_f32_16x16x32_bf16 v[22:25], v[206:209], v[178:181], v[22:25]
	v_mfma_f32_16x16x32_bf16 v[6:9], v[214:217], v[178:181], v[6:9]
	v_mfma_f32_16x16x32_bf16 v[10:13], v[206:209], v[186:189], v[10:13]
	v_mfma_f32_16x16x32_bf16 v[2:5], v[214:217], v[186:189], v[2:5]
	v_mfma_f32_16x16x32_bf16 v[30:33], v[210:213], v[166:169], v[30:33]
	v_mfma_f32_16x16x32_bf16 v[18:21], v[218:221], v[166:169], v[18:21]
	v_mfma_f32_16x16x32_bf16 v[26:29], v[210:213], v[174:177], v[26:29]
	v_mfma_f32_16x16x32_bf16 v[14:17], v[218:221], v[174:177], v[14:17]
	v_mfma_f32_16x16x32_bf16 v[22:25], v[210:213], v[182:185], v[22:25]
	v_mfma_f32_16x16x32_bf16 v[6:9], v[218:221], v[182:185], v[6:9]
	v_mfma_f32_16x16x32_bf16 v[10:13], v[210:213], v[190:193], v[10:13]
	v_mfma_f32_16x16x32_bf16 v[2:5], v[218:221], v[190:193], v[2:5]
	s_barrier
	s_setprio 0
	ds_read_b128 v[130:133], v253 offset:32768
	ds_read_b128 v[134:137], v253 offset:33792
	ds_read_b128 v[150:153], v253 offset:34816
	ds_read_b128 v[154:157], v253 offset:35840
	s_add_u32 s10, s10, 0x80000
	s_addc_u32 s11, s11, 0
	s_mov_b32 m0, s61
	ds_read_b128 v[158:161], v162 offset:32768
	ds_read_b128 v[166:169], v162 offset:33792
	ds_read_b128 v[170:173], v162 offset:34816
	ds_read_b128 v[174:177], v162 offset:35840
	ds_read_b128 v[178:181], v162 offset:36864
	ds_read_b128 v[182:185], v162 offset:37888
	ds_read_b128 v[186:189], v162 offset:38912
	ds_read_b128 v[190:193], v162 offset:39936
	global_load_lds_dwordx4 v142, s[10:11]
	s_mov_b32 m0, s62
	s_nop 0
	global_load_lds_dwordx4 v140, s[10:11]
	s_waitcnt lgkmcnt(8)
	s_setprio 1
	s_barrier
	s_waitcnt lgkmcnt(0)
	v_mfma_f32_16x16x32_bf16 v[126:129], v[130:133], v[158:161], v[126:129]
	v_mfma_f32_16x16x32_bf16 v[122:125], v[150:153], v[158:161], v[122:125]
	v_mfma_f32_16x16x32_bf16 v[118:121], v[130:133], v[170:173], v[118:121]
	v_mfma_f32_16x16x32_bf16 v[114:117], v[150:153], v[170:173], v[114:117]
	v_mfma_f32_16x16x32_bf16 v[110:113], v[130:133], v[178:181], v[110:113]
	v_mfma_f32_16x16x32_bf16 v[106:109], v[150:153], v[178:181], v[106:109]
	v_mfma_f32_16x16x32_bf16 v[102:105], v[130:133], v[186:189], v[102:105]
	v_mfma_f32_16x16x32_bf16 v[98:101], v[150:153], v[186:189], v[98:101]
	v_mfma_f32_16x16x32_bf16 v[126:129], v[134:137], v[166:169], v[126:129]
	v_mfma_f32_16x16x32_bf16 v[122:125], v[154:157], v[166:169], v[122:125]
	v_mfma_f32_16x16x32_bf16 v[118:121], v[134:137], v[174:177], v[118:121]
	v_mfma_f32_16x16x32_bf16 v[114:117], v[154:157], v[174:177], v[114:117]
	v_mfma_f32_16x16x32_bf16 v[110:113], v[134:137], v[182:185], v[110:113]
	v_mfma_f32_16x16x32_bf16 v[106:109], v[154:157], v[182:185], v[106:109]
	v_mfma_f32_16x16x32_bf16 v[102:105], v[134:137], v[190:193], v[102:105]
	v_mfma_f32_16x16x32_bf16 v[98:101], v[154:157], v[190:193], v[98:101]
	s_barrier
	s_setprio 0
	s_mov_b32 m0, s70
	ds_read_b128 v[206:209], v253 offset:49152
	ds_read_b128 v[210:213], v253 offset:50176
	v_lshl_add_u64 v[222:223], v[222:223], 0, s[76:77]
	ds_read_b128 v[214:217], v253 offset:51200
	ds_read_b128 v[218:221], v253 offset:52224
	global_load_lds_dwordx4 v[222:223], off
	v_lshl_add_u64 v[222:223], v[224:225], 0, s[76:77]
	s_mov_b32 m0, s71
	s_nop 0
	global_load_lds_dwordx4 v[222:223], off
	s_setprio 1
	s_barrier
	s_waitcnt lgkmcnt(0)
	v_mfma_f32_16x16x32_bf16 v[62:65], v[206:209], v[158:161], v[62:65]
	v_mfma_f32_16x16x32_bf16 v[58:61], v[214:217], v[158:161], v[58:61]
	v_mfma_f32_16x16x32_bf16 v[54:57], v[206:209], v[170:173], v[54:57]
	v_mfma_f32_16x16x32_bf16 v[46:49], v[214:217], v[170:173], v[46:49]
	v_mfma_f32_16x16x32_bf16 v[50:53], v[206:209], v[178:181], v[50:53]
	v_mfma_f32_16x16x32_bf16 v[42:45], v[214:217], v[178:181], v[42:45]
	v_mfma_f32_16x16x32_bf16 v[38:41], v[206:209], v[186:189], v[38:41]
	v_mfma_f32_16x16x32_bf16 v[34:37], v[214:217], v[186:189], v[34:37]
	v_mfma_f32_16x16x32_bf16 v[62:65], v[210:213], v[166:169], v[62:65]
	v_mfma_f32_16x16x32_bf16 v[58:61], v[218:221], v[166:169], v[58:61]
	v_mfma_f32_16x16x32_bf16 v[54:57], v[210:213], v[174:177], v[54:57]
	v_mfma_f32_16x16x32_bf16 v[46:49], v[218:221], v[174:177], v[46:49]
	v_mfma_f32_16x16x32_bf16 v[50:53], v[210:213], v[182:185], v[50:53]
	v_mfma_f32_16x16x32_bf16 v[42:45], v[218:221], v[182:185], v[42:45]
	s_mov_b32 m0, s78
	v_mfma_f32_16x16x32_bf16 v[38:41], v[210:213], v[190:193], v[38:41]
	v_lshl_add_u64 v[222:223], v[226:227], 0, s[76:77]
	v_mfma_f32_16x16x32_bf16 v[34:37], v[218:221], v[190:193], v[34:37]
	s_barrier
	s_setprio 0
	ds_read_b128 v[158:161], v162 offset:49152
	ds_read_b128 v[166:169], v162 offset:50176
	ds_read_b128 v[170:173], v162 offset:51200
	ds_read_b128 v[174:177], v162 offset:52224
	ds_read_b128 v[178:181], v162 offset:53248
	ds_read_b128 v[182:185], v162 offset:54272
	ds_read_b128 v[186:189], v162 offset:55296
	ds_read_b128 v[190:193], v162 offset:56320
	global_load_lds_dwordx4 v[222:223], off
	v_lshl_add_u64 v[222:223], v[228:229], 0, s[76:77]
	s_mov_b32 m0, s79
	s_nop 0
	global_load_lds_dwordx4 v[222:223], off
	s_setprio 1
	s_barrier
	s_waitcnt lgkmcnt(0)
	v_mfma_f32_16x16x32_bf16 v[94:97], v[130:133], v[158:161], v[94:97]
	v_mfma_f32_16x16x32_bf16 v[90:93], v[150:153], v[158:161], v[90:93]
	v_mfma_f32_16x16x32_bf16 v[86:89], v[130:133], v[170:173], v[86:89]
	v_mfma_f32_16x16x32_bf16 v[82:85], v[150:153], v[170:173], v[82:85]
	v_mfma_f32_16x16x32_bf16 v[78:81], v[130:133], v[178:181], v[78:81]
	v_mfma_f32_16x16x32_bf16 v[74:77], v[150:153], v[178:181], v[74:77]
	v_mfma_f32_16x16x32_bf16 v[70:73], v[130:133], v[186:189], v[70:73]
	v_mfma_f32_16x16x32_bf16 v[66:69], v[150:153], v[186:189], v[66:69]
	v_mfma_f32_16x16x32_bf16 v[94:97], v[134:137], v[166:169], v[94:97]
	v_mfma_f32_16x16x32_bf16 v[90:93], v[154:157], v[166:169], v[90:93]
	v_mfma_f32_16x16x32_bf16 v[86:89], v[134:137], v[174:177], v[86:89]
	v_mfma_f32_16x16x32_bf16 v[82:85], v[154:157], v[174:177], v[82:85]
	v_mfma_f32_16x16x32_bf16 v[78:81], v[134:137], v[182:185], v[78:81]
	v_mfma_f32_16x16x32_bf16 v[74:77], v[154:157], v[182:185], v[74:77]
	v_mfma_f32_16x16x32_bf16 v[70:73], v[134:137], v[190:193], v[70:73]
	v_mfma_f32_16x16x32_bf16 v[66:69], v[154:157], v[190:193], v[66:69]
	s_barrier
	s_setprio 0
	s_add_u32 s10, s54, 0x80080
	s_addc_u32 s11, s55, 0
	s_mov_b32 m0, s80
	global_load_lds_dwordx4 v194, s[10:11]
	s_mov_b32 m0, s81
	s_nop 0
	global_load_lds_dwordx4 v138, s[10:11]
	s_waitcnt vmcnt(6)
	s_setprio 1
	s_barrier
	v_mfma_f32_16x16x32_bf16 v[30:33], v[206:209], v[158:161], v[30:33]
	v_mfma_f32_16x16x32_bf16 v[18:21], v[214:217], v[158:161], v[18:21]
	v_mfma_f32_16x16x32_bf16 v[26:29], v[206:209], v[170:173], v[26:29]
	v_mfma_f32_16x16x32_bf16 v[14:17], v[214:217], v[170:173], v[14:17]
	v_mfma_f32_16x16x32_bf16 v[22:25], v[206:209], v[178:181], v[22:25]
	v_mfma_f32_16x16x32_bf16 v[6:9], v[214:217], v[178:181], v[6:9]
	v_mfma_f32_16x16x32_bf16 v[10:13], v[206:209], v[186:189], v[10:13]
	v_mfma_f32_16x16x32_bf16 v[2:5], v[214:217], v[186:189], v[2:5]
	v_mfma_f32_16x16x32_bf16 v[30:33], v[210:213], v[166:169], v[30:33]
	v_mfma_f32_16x16x32_bf16 v[18:21], v[218:221], v[166:169], v[18:21]
	v_mfma_f32_16x16x32_bf16 v[26:29], v[210:213], v[174:177], v[26:29]
	v_mfma_f32_16x16x32_bf16 v[14:17], v[218:221], v[174:177], v[14:17]
	v_mfma_f32_16x16x32_bf16 v[22:25], v[210:213], v[182:185], v[22:25]
	v_mfma_f32_16x16x32_bf16 v[6:9], v[218:221], v[182:185], v[6:9]
	v_mfma_f32_16x16x32_bf16 v[10:13], v[210:213], v[190:193], v[10:13]
	v_mfma_f32_16x16x32_bf16 v[2:5], v[218:221], v[190:193], v[2:5]
	s_setprio 0
	s_add_i32 s29, s29, 2
	s_add_u32 s52, s52, 0x100
	s_addc_u32 s53, s53, 0
	s_add_u32 s5, s5, 0x100
	s_addc_u32 s7, s7, 0
	s_cmp_gt_u32 s29, 29
	s_barrier
	s_cbranch_scc0 .LBB0_504
	v_readlane_b32 s10, v250, 21
	s_cmp_gt_i32 s40, 63
	v_readlane_b32 s11, v250, 22
	s_mov_b64 s[20:21], s[48:49]
	s_cselect_b32 s11, s21, s11
	s_cselect_b32 s10, s20, s10
	v_readlane_b32 s20, v252, 0
	v_readlane_b32 s26, v252, 6
	v_readlane_b32 s27, v252, 7
	s_cselect_b32 s53, s3, s27
	s_cselect_b32 s52, s2, s26
	s_sub_i32 s5, s40, 64
	s_cmp_gt_i32 s40, 63
	s_cselect_b32 s54, s5, s40
	s_lshr_b32 s5, s40, 3
	s_cmp_gt_i32 s40, 63
	s_mulk_i32 s5, 0x1800
	v_lshl_or_b32 v130, s28, 8, v164
	s_cselect_b32 s28, 0xc000, s5
	s_ashr_i32 s29, s28, 31
	s_lshl_b64 s[28:29], s[28:29], 2
	s_add_u32 s28, s63, s28
	v_ashrrev_i32_e32 v131, 31, v130
	s_addc_u32 s29, s67, s29
	v_lshlrev_b64 v[130:131], 2, v[130:131]
	v_lshl_add_u64 v[132:133], s[28:29], 0, v[130:131]
	s_mov_b64 s[28:29], 0x6484000
	s_ashr_i32 s55, s54, 31
	v_lshl_add_u64 v[154:155], v[132:133], 0, s[28:29]
	s_lshl_b64 s[28:29], s[54:55], 19
	v_lshl_add_u64 v[134:135], s[28:29], 0, v[144:145]
	v_lshlrev_b64 v[134:135], 2, v[134:135]
	v_lshl_add_u64 v[136:137], s[10:11], 0, v[134:135]
	v_lshl_add_u64 v[134:135], s[52:53], 0, v[134:135]
	s_mov_b32 s5, 0x6484000
	v_lshl_add_u64 v[150:151], v[136:137], 0, v[130:131]
	v_lshl_add_u64 v[152:153], v[134:135], 0, v[130:131]
	v_add_co_u32_e32 v130, vcc, s5, v132
	s_mov_b64 s[10:11], 0x20000
	s_nop 0
	v_addc_co_u32_e32 v131, vcc, 0, v133, vcc
	v_add_co_u32_e32 v156, vcc, s13, v150
	global_load_dwordx4 v[134:137], v[130:131], off
	s_nop 0
	global_load_dwordx4 v[130:133], v[154:155], off offset:16
	global_load_dwordx4 v[166:169], v[150:151], off offset:16
	global_load_dwordx4 v[170:173], v[150:151], off
	v_lshl_add_u64 v[158:159], v[150:151], 0, s[10:11]
	v_addc_co_u32_e32 v157, vcc, 0, v151, vcc
	s_mov_b32 s5, 0x40000
	global_load_dwordx4 v[174:177], v[156:157], off
	global_load_dwordx4 v[178:181], v[158:159], off offset:16
	s_mov_b64 s[10:11], 0x40000
	v_add_co_u32_e32 v158, vcc, s5, v150
	v_lshl_add_u64 v[160:161], v[150:151], 0, s[10:11]
	s_nop 0
	v_addc_co_u32_e32 v159, vcc, 0, v151, vcc
	s_mov_b32 s7, 0x60000
	global_load_dwordx4 v[182:185], v[158:159], off
	global_load_dwordx4 v[186:189], v[160:161], off offset:16
	s_mov_b64 s[10:11], 0x60000
	v_add_co_u32_e32 v160, vcc, s7, v150
	v_lshl_add_u64 v[206:207], v[150:151], 0, s[10:11]
	s_nop 0
	v_addc_co_u32_e32 v161, vcc, 0, v151, vcc
	global_load_dwordx4 v[190:193], v[160:161], off
	s_nop 0
	global_load_dwordx4 v[206:209], v[206:207], off offset:16
	v_readlane_b32 s21, v252, 1
	v_readlane_b32 s22, v252, 2
	v_readlane_b32 s23, v252, 3
	v_readlane_b32 s24, v252, 4
	v_readlane_b32 s25, v252, 5
	s_waitcnt vmcnt(0)
	v_pk_fma_f32 v[124:125], v[124:125], v[132:133], v[168:169]
	v_pk_fma_f32 v[122:123], v[122:123], v[130:131], v[166:167]
	global_store_dwordx4 v[152:153], v[122:125], off offset:16
	v_pk_fma_f32 v[128:129], v[128:129], v[136:137], v[172:173]
	v_pk_fma_f32 v[126:127], v[126:127], v[134:135], v[170:171]
	v_pk_fma_f32 v[122:123], v[120:121], v[136:137], v[176:177]
	v_pk_fma_f32 v[120:121], v[118:119], v[134:135], v[174:175]
	v_add_co_u32_e32 v118, vcc, s13, v152
	v_pk_fma_f32 v[116:117], v[116:117], v[132:133], v[180:181]
	s_nop 0
	v_addc_co_u32_e32 v119, vcc, 0, v153, vcc
	v_pk_fma_f32 v[114:115], v[114:115], v[130:131], v[178:179]
	global_store_dwordx4 v[118:119], v[114:117], off offset:16
	v_pk_fma_f32 v[108:109], v[108:109], v[132:133], v[188:189]
	v_pk_fma_f32 v[106:107], v[106:107], v[130:131], v[186:187]
	v_pk_fma_f32 v[114:115], v[112:113], v[136:137], v[184:185]
	v_pk_fma_f32 v[112:113], v[110:111], v[134:135], v[182:183]
	v_add_co_u32_e32 v110, vcc, s5, v152
	global_store_dwordx4 v[152:153], v[126:129], off
	s_nop 0
	v_addc_co_u32_e32 v111, vcc, 0, v153, vcc
	global_store_dwordx4 v[110:111], v[106:109], off offset:16
	v_pk_fma_f32 v[100:101], v[100:101], v[132:133], v[208:209]
	v_pk_fma_f32 v[98:99], v[98:99], v[130:131], v[206:207]
	v_pk_fma_f32 v[106:107], v[104:105], v[136:137], v[192:193]
	v_pk_fma_f32 v[104:105], v[102:103], v[134:135], v[190:191]
	v_add_co_u32_e32 v102, vcc, s7, v152
	global_store_dwordx4 v[118:119], v[120:123], off
	s_nop 0
	v_addc_co_u32_e32 v103, vcc, 0, v153, vcc
	global_store_dwordx4 v[110:111], v[112:115], off
	global_store_dwordx4 v[102:103], v[104:107], off
	global_store_dwordx4 v[102:103], v[98:101], off offset:16
	s_mov_b32 s5, 0x100000
	s_mov_b64 s[10:11], 0x100000
	v_add_co_u32_e32 v98, vcc, s5, v150
	v_lshl_add_u64 v[100:101], v[150:151], 0, s[10:11]
	s_nop 0
	v_addc_co_u32_e32 v99, vcc, 0, v151, vcc
	global_load_dwordx4 v[112:115], v[98:99], off
	global_load_dwordx4 v[120:123], v[100:101], off offset:16
	s_mov_b64 s[10:11], 0x120000
	v_add_co_u32_e32 v100, vcc, s45, v150
	v_lshl_add_u64 v[104:105], v[150:151], 0, s[10:11]
	s_nop 0
	v_addc_co_u32_e32 v101, vcc, 0, v151, vcc
	s_mov_b64 s[10:11], 0x140000
	s_mov_b32 s7, 0x140000
	global_load_dwordx4 v[124:127], v[100:101], off
	global_load_dwordx4 v[166:169], v[104:105], off offset:16
	v_lshl_add_u64 v[106:107], v[150:151], 0, s[10:11]
	v_add_co_u32_e32 v104, vcc, s7, v150
	s_mov_b64 s[10:11], 0x160000
	s_nop 0
	v_addc_co_u32_e32 v105, vcc, 0, v151, vcc
	v_lshl_add_u64 v[108:109], v[150:151], 0, s[10:11]
	s_mov_b32 s10, 0x160000
	global_load_dwordx4 v[170:173], v[104:105], off
	global_load_dwordx4 v[174:177], v[106:107], off offset:16
	v_add_co_u32_e32 v106, vcc, s10, v150
	s_waitcnt vmcnt(0)
	v_pk_fma_f32 v[112:113], v[94:95], v[134:135], v[112:113]
	v_addc_co_u32_e32 v107, vcc, 0, v151, vcc
	global_load_dwordx4 v[178:181], v[106:107], off
	global_load_dwordx4 v[182:185], v[108:109], off offset:16
	v_add_co_u32_e32 v94, vcc, s5, v152
	v_pk_fma_f32 v[92:93], v[92:93], v[132:133], v[122:123]
	s_nop 0
	v_addc_co_u32_e32 v95, vcc, 0, v153, vcc
	v_pk_fma_f32 v[90:91], v[90:91], v[130:131], v[120:121]
	global_store_dwordx4 v[94:95], v[90:93], off offset:16
	v_pk_fma_f32 v[84:85], v[84:85], v[132:133], v[168:169]
	v_pk_fma_f32 v[82:83], v[82:83], v[130:131], v[166:167]
	v_pk_fma_f32 v[90:91], v[88:89], v[136:137], v[126:127]
	v_pk_fma_f32 v[88:89], v[86:87], v[134:135], v[124:125]
	v_add_co_u32_e32 v86, vcc, s45, v152
	v_pk_fma_f32 v[114:115], v[96:97], v[136:137], v[114:115]
	s_nop 0
	v_addc_co_u32_e32 v87, vcc, 0, v153, vcc
	global_store_dwordx4 v[86:87], v[82:85], off offset:16
	v_pk_fma_f32 v[76:77], v[76:77], v[132:133], v[176:177]
	v_pk_fma_f32 v[74:75], v[74:75], v[130:131], v[174:175]
	v_pk_fma_f32 v[82:83], v[80:81], v[136:137], v[172:173]
	v_pk_fma_f32 v[80:81], v[78:79], v[134:135], v[170:171]
	v_add_co_u32_e32 v78, vcc, s7, v152
	global_store_dwordx4 v[94:95], v[112:115], off
	s_nop 0
	v_addc_co_u32_e32 v79, vcc, 0, v153, vcc
	global_store_dwordx4 v[78:79], v[74:77], off offset:16
	global_store_dwordx4 v[86:87], v[88:91], off
	global_store_dwordx4 v[78:79], v[80:83], off
	v_add_co_u32_e32 v74, vcc, s10, v152
	s_waitcnt vmcnt(0)
	v_pk_fma_f32 v[72:73], v[72:73], v[136:137], v[180:181]
	v_pk_fma_f32 v[70:71], v[70:71], v[134:135], v[178:179]
	v_addc_co_u32_e32 v75, vcc, 0, v153, vcc
	v_pk_fma_f32 v[68:69], v[68:69], v[132:133], v[184:185]
	v_pk_fma_f32 v[66:67], v[66:67], v[130:131], v[182:183]
	global_store_dwordx4 v[74:75], v[70:73], off
	global_store_dwordx4 v[74:75], v[66:69], off offset:16
	s_mov_b64 s[10:11], 0x20200
	v_lshl_add_u64 v[76:77], v[150:151], 0, s[10:11]
	s_mov_b64 s[10:11], 0x40200
	global_load_dwordx4 v[80:83], v[150:151], off offset:512
	global_load_dwordx4 v[70:73], v[154:155], off offset:512
	global_load_dwordx4 v[66:69], v[154:155], off offset:528
	global_load_dwordx4 v[88:91], v[150:151], off offset:528
	global_load_dwordx4 v[112:115], v[156:157], off offset:512
	global_load_dwordx4 v[120:123], v[158:159], off offset:512
	global_load_dwordx4 v[124:127], v[76:77], off offset:16
	v_lshl_add_u64 v[76:77], v[150:151], 0, s[10:11]
	s_mov_b64 s[10:11], 0x60200
	global_load_dwordx4 v[128:131], v[76:77], off offset:16
	global_load_dwordx4 v[132:135], v[160:161], off offset:512
	v_lshl_add_u64 v[76:77], v[150:151], 0, s[10:11]
	global_load_dwordx4 v[154:157], v[76:77], off offset:16
	s_waitcnt vmcnt(0)
	v_pk_fma_f32 v[64:65], v[64:65], v[72:73], v[82:83]
	v_pk_fma_f32 v[62:63], v[62:63], v[70:71], v[80:81]
	v_pk_fma_f32 v[60:61], v[60:61], v[68:69], v[90:91]
	v_pk_fma_f32 v[58:59], v[58:59], v[66:67], v[88:89]
	v_pk_fma_f32 v[52:53], v[52:53], v[72:73], v[122:123]
	v_pk_fma_f32 v[50:51], v[50:51], v[70:71], v[120:121]
	v_pk_fma_f32 v[48:49], v[48:49], v[68:69], v[126:127]
	v_pk_fma_f32 v[46:47], v[46:47], v[66:67], v[124:125]
	v_pk_fma_f32 v[56:57], v[56:57], v[72:73], v[114:115]
	v_pk_fma_f32 v[54:55], v[54:55], v[70:71], v[112:113]
	global_store_dwordx4 v[152:153], v[62:65], off offset:512
	global_store_dwordx4 v[152:153], v[58:61], off offset:528
	global_store_dwordx4 v[118:119], v[54:57], off offset:512
	global_store_dwordx4 v[110:111], v[50:53], off offset:512
	v_pk_fma_f32 v[44:45], v[44:45], v[68:69], v[130:131]
	v_pk_fma_f32 v[42:43], v[42:43], v[66:67], v[128:129]
	v_pk_fma_f32 v[40:41], v[40:41], v[72:73], v[134:135]
	v_pk_fma_f32 v[38:39], v[38:39], v[70:71], v[132:133]
	v_pk_fma_f32 v[36:37], v[36:37], v[68:69], v[156:157]
	v_pk_fma_f32 v[34:35], v[34:35], v[66:67], v[154:155]
	global_store_dwordx4 v[118:119], v[46:49], off offset:528
	global_store_dwordx4 v[110:111], v[42:45], off offset:528
	global_store_dwordx4 v[102:103], v[38:41], off offset:512
	global_store_dwordx4 v[102:103], v[34:37], off offset:528
	s_mov_b64 s[10:11], 0x100200
	v_lshl_add_u64 v[50:51], v[150:151], 0, s[10:11]
	s_mov_b64 s[10:11], 0x120200
	v_lshl_add_u64 v[54:55], v[150:151], 0, s[10:11]
	s_mov_b64 s[10:11], 0x140200
	v_lshl_add_u64 v[58:59], v[150:151], 0, s[10:11]
	s_mov_b64 s[10:11], 0x160200
	global_load_dwordx4 v[34:37], v[98:99], off offset:512
	global_load_dwordx4 v[38:41], v[100:101], off offset:512
	global_load_dwordx4 v[42:45], v[104:105], off offset:512
	global_load_dwordx4 v[46:49], v[106:107], off offset:512
	v_lshl_add_u64 v[62:63], v[150:151], 0, s[10:11]
	global_load_dwordx4 v[50:53], v[50:51], off offset:16
	s_waitcnt vmcnt(0)
	v_pk_fma_f32 v[32:33], v[32:33], v[72:73], v[36:37]
	global_load_dwordx4 v[54:57], v[54:55], off offset:16
	v_pk_fma_f32 v[30:31], v[30:31], v[70:71], v[34:35]
	global_load_dwordx4 v[58:61], v[58:59], off offset:16
	v_pk_fma_f32 v[28:29], v[28:29], v[72:73], v[40:41]
	global_load_dwordx4 v[62:65], v[62:63], off offset:16
	v_pk_fma_f32 v[26:27], v[26:27], v[70:71], v[38:39]
	v_pk_fma_f32 v[24:25], v[24:25], v[72:73], v[44:45]
	v_pk_fma_f32 v[22:23], v[22:23], v[70:71], v[42:43]
	v_pk_fma_f32 v[12:13], v[12:13], v[72:73], v[48:49]
	v_pk_fma_f32 v[10:11], v[10:11], v[70:71], v[46:47]
	v_pk_fma_f32 v[20:21], v[20:21], v[68:69], v[52:53]
	v_pk_fma_f32 v[18:19], v[18:19], v[66:67], v[50:51]
	global_store_dwordx4 v[94:95], v[30:33], off offset:512
	global_store_dwordx4 v[86:87], v[26:29], off offset:512
	global_store_dwordx4 v[78:79], v[22:25], off offset:512
	global_store_dwordx4 v[74:75], v[10:13], off offset:512
	s_waitcnt vmcnt(0)
	v_pk_fma_f32 v[16:17], v[16:17], v[68:69], v[56:57]
	v_pk_fma_f32 v[14:15], v[14:15], v[66:67], v[54:55]
	v_pk_fma_f32 v[8:9], v[8:9], v[68:69], v[60:61]
	v_pk_fma_f32 v[6:7], v[6:7], v[66:67], v[58:59]
	v_pk_fma_f32 v[4:5], v[4:5], v[68:69], v[64:65]
	v_pk_fma_f32 v[2:3], v[2:3], v[66:67], v[62:63]
	global_store_dwordx4 v[94:95], v[18:21], off offset:528
	global_store_dwordx4 v[86:87], v[14:17], off offset:528
	global_store_dwordx4 v[78:79], v[6:9], off offset:528
	global_store_dwordx4 v[74:75], v[2:5], off offset:528
	s_and_b64 vcc, exec, s[0:1]
	s_mov_b32 s40, s6
	s_mov_b32 s28, s4
	s_mov_b64 s[54:55], s[34:35]
	s_mov_b64 s[52:53], s[8:9]
	s_cbranch_vccz .LBB0_501
	s_waitcnt vmcnt(0)
	v_readlane_b32 s28, v250, 12
	v_readlane_b32 s26, v250, 15
	s_cmpk_gt_u32 s12, 0xff
	v_readlane_b32 s29, v250, 13
	v_readlane_b32 s27, v250, 16
	s_mov_b32 s70, 0x800000
	v_readlane_b32 s79, v250, 18
	s_cbranch_scc1 .LBB0_508
	s_barrier
